# hand-scheduled rope epilogues for RET q/k tiles and RETT K^T tiles (packed f32 rotation, v_sin/v_cos, 16-byte stores)
# speedup vs baseline: 1.0109x; 1.0062x over previous
.LBB0_825:
	s_and_b64 vcc, exec, s[2:3]
	s_cbranch_vccz .LBB0_830
	s_cmp_gt_i32 s66, 3
	s_mov_b64 s[2:3], -1
	s_cbranch_scc1 .LBB0_828
	s_branch .Lrettk_fast
	v_readlane_b32 s2, v253, 35
	s_cmp_eq_u32 s68, 0
	v_and_b32_e32 v217, 60, v146
	v_mov_b32_e32 v0, s2
	ds_read_b64 v[130:131], v0
	v_cvt_f32_i32_e32 v0, v163
	s_mov_b32 s2, 0xc2fc0000
	v_cmp_gt_i32_e64 s[4:5], s86, v162
	v_or_b32_e32 v218, 1, v217
	v_mul_f32_e32 v132, 0xbe549a78, v0
	v_cmp_gt_f32_e32 vcc, s2, v132
	v_or_b32_e32 v219, 2, v217
	v_or_b32_e32 v220, 3, v217
	v_cndmask_b32_e32 v133, 0, v201, vcc
	v_fmac_f32_e32 v133, 0xbe549a78, v0
	v_exp_f32_e32 v0, v133
	v_cndmask_b32_e32 v132, 0, v200, vcc
	v_bfe_u32 v209, v206, 5, 3
	v_lshlrev_b32_e32 v136, 6, v146
	v_ldexp_f32 v208, v0, v132
	v_add_u32_e32 v0, 16, v163
	v_cvt_f32_i32_e32 v0, v0
	v_and_b32_e32 v138, 4, v148
	v_and_b32_e32 v172, 0x1c00, v136
	v_mov_b32_e32 v173, v1
	v_mul_f32_e32 v132, 0xbe549a78, v0
	v_cmp_gt_f32_e32 vcc, s2, v132
	v_add_u32_e32 v185, 32, v206
	v_add_u32_e32 v214, s67, v185
	v_cndmask_b32_e32 v132, 0, v201, vcc
	v_fmac_f32_e32 v132, 0xbe549a78, v0
	v_exp_f32_e32 v0, v132
	v_cndmask_b32_e32 v132, 0, v200, vcc
	v_bfe_u32 v213, v185, 5, 3
	v_ldexp_f32 v207, v0, v132
	v_add_u32_e32 v0, 32, v163
	v_cvt_f32_i32_e32 v0, v0
	v_mul_f32_e32 v132, 0xbe549a78, v0
	v_cmp_gt_f32_e32 vcc, s2, v132
	s_nop 1
	v_cndmask_b32_e32 v132, 0, v201, vcc
	v_fmac_f32_e32 v132, 0xbe549a78, v0
	v_exp_f32_e32 v0, v132
	v_cndmask_b32_e32 v132, 0, v200, vcc
	v_ldexp_f32 v161, v0, v132
	v_add_u32_e32 v0, 48, v163
	v_cvt_f32_i32_e32 v0, v0
	v_mul_f32_e32 v132, 0xbe549a78, v0
	v_cmp_gt_f32_e32 vcc, s2, v132
	s_movk_i32 s2, 0x3ff0
	s_nop 0
	v_cndmask_b32_e32 v132, 0, v201, vcc
	v_fmac_f32_e32 v132, 0xbe549a78, v0
	v_exp_f32_e32 v0, v132
	v_cndmask_b32_e32 v132, 0, v200, vcc
	s_cselect_b64 vcc, -1, 0
	v_ldexp_f32 v149, v0, v132
	v_lshlrev_b32_e32 v0, 4, v147
	v_ashrrev_i32_e32 v132, 7, v162
	v_and_b32_e32 v164, 32, v0
	v_ashrrev_i32_e32 v0, 6, v162
	v_ashrrev_i32_e32 v133, 31, v132
	v_lshlrev_b64 v[174:175], 5, v[132:133]
	v_cndmask_b32_e32 v132, v217, v0, vcc
	v_cvt_f32_i32_e32 v165, v132
	v_mul_f32_e32 v132, v208, v165
	v_mul_f32_e32 v132, 0.15915494, v132
	v_cos_f32_e32 v133, v132
	v_sin_f32_e32 v132, v132
	v_cndmask_b32_e64 v133, 1.0, v133, s[4:5]
	v_cndmask_b32_e64 v132, 0, v132, s[4:5]
	v_mul_f32_e32 v134, v62, v132
	v_fma_f32 v134, v126, v133, -v134
	v_mul_f32_e32 v133, v62, v133
	v_fmac_f32_e32 v133, v126, v132
	v_cndmask_b32_e32 v132, v218, v0, vcc
	v_cvt_f32_i32_e32 v168, v132
	v_mul_f32_e32 v140, 0x3d800000, v133
	v_mul_f32_e32 v139, 0x3d800000, v134
	v_mul_f32_e32 v132, v208, v168
	v_mul_f32_e32 v132, 0.15915494, v132
	v_cos_f32_e32 v133, v132
	v_sin_f32_e32 v132, v132
	v_cndmask_b32_e64 v133, 1.0, v133, s[4:5]
	v_cndmask_b32_e64 v132, 0, v132, s[4:5]
	v_mul_f32_e32 v134, v63, v132
	v_fma_f32 v134, v127, v133, -v134
	v_mul_f32_e32 v133, v63, v133
	v_fmac_f32_e32 v133, v127, v132
	v_cndmask_b32_e32 v132, v219, v0, vcc
	v_cvt_f32_i32_e32 v169, v132
	v_mul_f32_e32 v142, 0x3d800000, v133
	v_cndmask_b32_e32 v0, v220, v0, vcc
	v_cvt_f32_i32_e32 v180, v0
	v_mul_f32_e32 v132, v208, v169
	v_mul_f32_e32 v132, 0.15915494, v132
	v_cos_f32_e32 v133, v132
	v_sin_f32_e32 v132, v132
	v_mul_f32_e32 v141, 0x3d800000, v134
	v_mul_f32_e32 v0, v208, v180
	v_cndmask_b32_e64 v133, 1.0, v133, s[4:5]
	v_cndmask_b32_e64 v132, 0, v132, s[4:5]
	v_mul_f32_e32 v134, v64, v132
	v_fma_f32 v134, v128, v133, -v134
	v_mul_f32_e32 v133, v64, v133
	v_mul_f32_e32 v0, 0.15915494, v0
	v_fmac_f32_e32 v133, v128, v132
	v_cos_f32_e32 v132, v0
	v_sin_f32_e32 v0, v0
	v_mul_f32_e32 v144, 0x3d800000, v133
	v_mul_f32_e32 v143, 0x3d800000, v134
	v_cndmask_b32_e64 v132, 1.0, v132, s[4:5]
	v_cndmask_b32_e64 v0, 0, v0, s[4:5]
	v_mul_f32_e32 v133, v65, v0
	v_fma_f32 v133, v129, v132, -v133
	v_mul_f32_e32 v132, v65, v132
	v_fmac_f32_e32 v132, v129, v0
	v_mul_f32_e32 v166, 0x3d800000, v132
	v_ashrrev_i32_e32 v132, 8, v160
	v_mul_f32_e32 v145, 0x3d800000, v133
	v_ashrrev_i32_e32 v133, 31, v132
	v_lshlrev_b64 v[134:135], 3, v[132:133]
	v_lshl_add_u64 v[132:133], v[134:135], 0, v[174:175]
	v_or_b32_e32 v132, v132, v209
	v_and_or_b32 v0, v163, 31, v164
	v_lshlrev_b64 v[132:133], 13, v[132:133]
	s_waitcnt lgkmcnt(0)
	v_lshl_add_u64 v[132:133], v[130:131], 0, v[132:133]
	v_lshlrev_b32_e32 v0, 4, v0
	v_lshl_add_u64 v[132:133], v[132:133], 0, v[0:1]
	v_lshl_add_u64 v[136:137], v[132:133], 0, v[172:173]
	v_lshlrev_b32_e32 v132, 1, v138
	v_mov_b32_e32 v133, v1
	v_lshl_add_u64 v[136:137], v[136:137], 0, v[132:133]
	v_cvt_pk_bf16_f32 v138, v139, v141
	v_cvt_pk_bf16_f32 v139, v143, v145
	v_add_u32_e32 v141, 0x80, v160
	global_store_dwordx2 v[136:137], v[138:139], off
	v_ashrrev_i32_e32 v136, 8, v141
	v_ashrrev_i32_e32 v137, 31, v136
	v_lshlrev_b64 v[138:139], 3, v[136:137]
	v_lshl_add_u64 v[136:137], v[138:139], 0, v[174:175]
	v_bfe_u32 v210, v141, 5, 3
	v_or_b32_e32 v136, v136, v210
	v_lshlrev_b64 v[136:137], 13, v[136:137]
	v_lshl_add_u64 v[136:137], v[130:131], 0, v[136:137]
	v_lshl_add_u64 v[136:137], v[136:137], 0, v[0:1]
	v_lshl_add_u64 v[136:137], v[136:137], 0, v[172:173]
	v_lshl_add_u64 v[136:137], v[136:137], 0, v[132:133]
	v_cvt_pk_bf16_f32 v140, v140, v142
	v_cvt_pk_bf16_f32 v141, v144, v166
	global_store_dwordx2 v[136:137], v[140:141], off
	v_mul_f32_e32 v136, v207, v165
	v_mul_f32_e32 v136, 0.15915494, v136
	v_cos_f32_e32 v137, v136
	v_sin_f32_e32 v136, v136
	v_add_u32_e32 v142, 16, v206
	v_add_u32_e32 v181, s67, v142
	v_cndmask_b32_e64 v137, 1.0, v137, s[4:5]
	v_cndmask_b32_e64 v136, 0, v136, s[4:5]
	v_mul_f32_e32 v140, v46, v136
	v_fma_f32 v140, v110, v137, -v140
	v_mul_f32_e32 v137, v46, v137
	v_fmac_f32_e32 v137, v110, v136
	v_mul_f32_e32 v136, v207, v168
	v_mul_f32_e32 v136, 0.15915494, v136
	v_mul_f32_e32 v166, 0x3d800000, v137
	v_cos_f32_e32 v137, v136
	v_sin_f32_e32 v136, v136
	v_mul_f32_e32 v144, 0x3d800000, v140
	v_bfe_u32 v211, v142, 5, 3
	v_cndmask_b32_e64 v137, 1.0, v137, s[4:5]
	v_cndmask_b32_e64 v136, 0, v136, s[4:5]
	v_mul_f32_e32 v140, v47, v136
	v_fma_f32 v140, v111, v137, -v140
	v_mul_f32_e32 v137, v47, v137
	v_fmac_f32_e32 v137, v111, v136
	v_mul_f32_e32 v136, v207, v169
	v_mul_f32_e32 v136, 0.15915494, v136
	v_mul_f32_e32 v167, 0x3d800000, v137
	v_cos_f32_e32 v137, v136
	v_sin_f32_e32 v136, v136
	v_mul_f32_e32 v145, 0x3d800000, v140
	v_and_or_b32 v182, v142, 31, v164
	v_cndmask_b32_e64 v137, 1.0, v137, s[4:5]
	v_cndmask_b32_e64 v136, 0, v136, s[4:5]
	v_mul_f32_e32 v140, v48, v136
	v_fma_f32 v140, v112, v137, -v140
	v_mul_f32_e32 v137, v48, v137
	v_fmac_f32_e32 v137, v112, v136
	v_mul_f32_e32 v136, v207, v180
	v_mul_f32_e32 v136, 0.15915494, v136
	v_mul_f32_e32 v171, 0x3d800000, v137
	v_cos_f32_e32 v137, v136
	v_sin_f32_e32 v136, v136
	v_mul_f32_e32 v170, 0x3d800000, v140
	v_cvt_pk_bf16_f32 v144, v144, v145
	v_cndmask_b32_e64 v137, 1.0, v137, s[4:5]
	v_cndmask_b32_e64 v136, 0, v136, s[4:5]
	v_mul_f32_e32 v140, v49, v136
	v_fma_f32 v140, v113, v137, -v140
	v_mul_f32_e32 v137, v49, v137
	v_fmac_f32_e32 v137, v113, v136
	v_ashrrev_i32_e32 v136, 8, v181
	v_mul_f32_e32 v177, 0x3d800000, v137
	v_ashrrev_i32_e32 v137, 31, v136
	v_mul_f32_e32 v176, 0x3d800000, v140
	v_lshlrev_b64 v[140:141], 3, v[136:137]
	v_lshl_add_u64 v[136:137], v[140:141], 0, v[174:175]
	v_or_b32_e32 v136, v136, v211
	v_lshlrev_b64 v[136:137], 13, v[136:137]
	v_lshl_add_u64 v[142:143], v[130:131], 0, v[136:137]
	v_lshlrev_b32_e32 v136, 4, v182
	v_mov_b32_e32 v137, v1
	v_lshl_add_u64 v[142:143], v[142:143], 0, v[136:137]
	v_lshl_add_u64 v[142:143], v[142:143], 0, v[172:173]
	v_lshl_add_u64 v[142:143], v[142:143], 0, v[132:133]
	v_cvt_pk_bf16_f32 v145, v170, v176
	v_add_u32_e32 v170, 0x80, v181
	global_store_dwordx2 v[142:143], v[144:145], off
	v_ashrrev_i32_e32 v142, 8, v170
	v_ashrrev_i32_e32 v143, 31, v142
	v_lshlrev_b64 v[142:143], 3, v[142:143]
	v_lshl_add_u64 v[144:145], v[142:143], 0, v[174:175]
	v_bfe_u32 v212, v170, 5, 3
	v_or_b32_e32 v144, v144, v212
	v_lshlrev_b64 v[144:145], 13, v[144:145]
	v_lshl_add_u64 v[144:145], v[130:131], 0, v[144:145]
	v_lshl_add_u64 v[144:145], v[144:145], 0, v[136:137]
	v_lshl_add_u64 v[144:145], v[144:145], 0, v[172:173]
	v_lshl_add_u64 v[144:145], v[144:145], 0, v[132:133]
	v_cvt_pk_bf16_f32 v166, v166, v167
	v_cvt_pk_bf16_f32 v167, v171, v177
	global_store_dwordx2 v[144:145], v[166:167], off
	v_mul_f32_e32 v144, v161, v165
	v_mul_f32_e32 v144, 0.15915494, v144
	v_cos_f32_e32 v145, v144
	v_sin_f32_e32 v144, v144
	v_mul_f32_e32 v165, v149, v165
	v_mul_f32_e32 v165, 0.15915494, v165
	v_cndmask_b32_e64 v145, 1.0, v145, s[4:5]
	v_cndmask_b32_e64 v144, 0, v144, s[4:5]
	v_mul_f32_e32 v166, v30, v144
	v_fma_f32 v166, v94, v145, -v166
	v_mul_f32_e32 v145, v30, v145
	v_fmac_f32_e32 v145, v94, v144
	v_mul_f32_e32 v144, v161, v168
	v_mul_f32_e32 v144, 0.15915494, v144
	v_mul_f32_e32 v176, 0x3d800000, v145
	v_cos_f32_e32 v145, v144
	v_sin_f32_e32 v144, v144
	v_mul_f32_e32 v170, 0x3d800000, v166
	v_cndmask_b32_e64 v145, 1.0, v145, s[4:5]
	v_cndmask_b32_e64 v144, 0, v144, s[4:5]
	v_mul_f32_e32 v166, v31, v144
	v_fma_f32 v166, v95, v145, -v166
	v_mul_f32_e32 v145, v31, v145
	v_fmac_f32_e32 v145, v95, v144
	v_mul_f32_e32 v144, v161, v169
	v_mul_f32_e32 v144, 0.15915494, v144
	v_mul_f32_e32 v177, 0x3d800000, v145
	v_cos_f32_e32 v145, v144
	v_sin_f32_e32 v144, v144
	v_mul_f32_e32 v171, 0x3d800000, v166
	v_cvt_pk_bf16_f32 v170, v170, v171
	v_cndmask_b32_e64 v145, 1.0, v145, s[4:5]
	v_cndmask_b32_e64 v144, 0, v144, s[4:5]
	v_mul_f32_e32 v166, v32, v144
	v_fma_f32 v166, v96, v145, -v166
	v_mul_f32_e32 v145, v32, v145
	v_fmac_f32_e32 v145, v96, v144
	v_mul_f32_e32 v144, v161, v180
	v_mul_f32_e32 v144, 0.15915494, v144
	v_mul_f32_e32 v182, 0x3d800000, v145
	v_cos_f32_e32 v145, v144
	v_sin_f32_e32 v144, v144
	v_mul_f32_e32 v181, 0x3d800000, v166
	v_cvt_pk_bf16_f32 v176, v176, v177
	v_cndmask_b32_e64 v145, 1.0, v145, s[4:5]
	v_cndmask_b32_e64 v144, 0, v144, s[4:5]
	v_mul_f32_e32 v166, v33, v144
	v_fma_f32 v166, v97, v145, -v166
	v_mul_f32_e32 v145, v33, v145
	v_fmac_f32_e32 v145, v97, v144
	v_ashrrev_i32_e32 v144, 8, v214
	v_mul_f32_e32 v184, 0x3d800000, v145
	v_ashrrev_i32_e32 v145, 31, v144
	v_lshlrev_b64 v[144:145], 3, v[144:145]
	v_mul_f32_e32 v183, 0x3d800000, v166
	v_lshl_add_u64 v[166:167], v[144:145], 0, v[174:175]
	v_or_b32_e32 v166, v166, v213
	v_lshlrev_b64 v[166:167], 13, v[166:167]
	v_lshl_add_u64 v[166:167], v[130:131], 0, v[166:167]
	v_lshl_add_u64 v[166:167], v[166:167], 0, v[0:1]
	v_lshl_add_u64 v[166:167], v[166:167], 0, v[172:173]
	v_lshl_add_u64 v[166:167], v[166:167], 0, v[132:133]
	v_cvt_pk_bf16_f32 v171, v181, v183
	v_add_u32_e32 v181, 0x80, v214
	global_store_dwordx2 v[166:167], v[170:171], off
	v_ashrrev_i32_e32 v166, 8, v181
	v_ashrrev_i32_e32 v167, 31, v166
	v_lshlrev_b64 v[166:167], 3, v[166:167]
	v_lshl_add_u64 v[170:171], v[166:167], 0, v[174:175]
	v_bfe_u32 v214, v181, 5, 3
	v_or_b32_e32 v170, v170, v214
	v_lshlrev_b64 v[170:171], 13, v[170:171]
	v_lshl_add_u64 v[170:171], v[130:131], 0, v[170:171]
	v_lshl_add_u64 v[170:171], v[170:171], 0, v[0:1]
	v_lshl_add_u64 v[170:171], v[170:171], 0, v[172:173]
	v_lshl_add_u64 v[170:171], v[170:171], 0, v[132:133]
	v_cvt_pk_bf16_f32 v177, v182, v184
	global_store_dwordx2 v[170:171], v[176:177], off
	v_cos_f32_e32 v170, v165
	v_sin_f32_e32 v165, v165
	v_cndmask_b32_e64 v170, 1.0, v170, s[4:5]
	v_cndmask_b32_e64 v165, 0, v165, s[4:5]
	v_mul_f32_e32 v171, v14, v165
	v_fma_f32 v171, v78, v170, -v171
	v_mul_f32_e32 v170, v14, v170
	v_fmac_f32_e32 v170, v78, v165
	v_mul_f32_e32 v165, v149, v168
	v_mul_f32_e32 v165, 0.15915494, v165
	v_cos_f32_e32 v168, v165
	v_sin_f32_e32 v165, v165
	v_mul_f32_e32 v181, 0x3d800000, v170
	v_mul_f32_e32 v176, 0x3d800000, v171
	v_cndmask_b32_e64 v168, 1.0, v168, s[4:5]
	v_cndmask_b32_e64 v165, 0, v165, s[4:5]
	v_mul_f32_e32 v170, v15, v165
	v_fma_f32 v170, v79, v168, -v170
	v_mul_f32_e32 v168, v15, v168
	v_fmac_f32_e32 v168, v79, v165
	v_mul_f32_e32 v165, v149, v169
	v_mul_f32_e32 v165, 0.15915494, v165
	v_mul_f32_e32 v182, 0x3d800000, v168
	v_cos_f32_e32 v168, v165
	v_sin_f32_e32 v165, v165
	v_mul_f32_e32 v177, 0x3d800000, v170
	v_cvt_pk_bf16_f32 v176, v176, v177
	v_cndmask_b32_e64 v168, 1.0, v168, s[4:5]
	v_cndmask_b32_e64 v165, 0, v165, s[4:5]
	v_mul_f32_e32 v169, v16, v165
	v_fma_f32 v169, v80, v168, -v169
	v_mul_f32_e32 v168, v16, v168
	v_fmac_f32_e32 v168, v80, v165
	v_mul_f32_e32 v165, v149, v180
	v_mul_f32_e32 v165, 0.15915494, v165
	v_mul_f32_e32 v184, 0x3d800000, v168
	v_cos_f32_e32 v168, v165
	v_sin_f32_e32 v165, v165
	v_mul_f32_e32 v183, 0x3d800000, v169
	v_cndmask_b32_e64 v168, 1.0, v168, s[4:5]
	v_cndmask_b32_e64 v165, 0, v165, s[4:5]
	v_mul_f32_e32 v169, v17, v165
	v_fma_f32 v169, v81, v168, -v169
	v_mul_f32_e32 v168, v17, v168
	v_fmac_f32_e32 v168, v81, v165
	v_add_u32_e32 v165, 48, v206
	v_add_u32_e32 v216, s67, v165
	v_mul_f32_e32 v185, 0x3d800000, v168
	v_ashrrev_i32_e32 v168, 8, v216
	v_mul_f32_e32 v180, 0x3d800000, v169
	v_ashrrev_i32_e32 v169, 31, v168
	v_lshlrev_b64 v[168:169], 3, v[168:169]
	v_lshl_add_u64 v[170:171], v[168:169], 0, v[174:175]
	v_bfe_u32 v215, v165, 5, 3
	v_or_b32_e32 v170, v170, v215
	v_and_or_b32 v221, v165, 31, v164
	v_lshlrev_b64 v[164:165], 13, v[170:171]
	v_lshl_add_u64 v[170:171], v[130:131], 0, v[164:165]
	v_lshlrev_b32_e32 v164, 4, v221
	v_mov_b32_e32 v165, v1
	v_lshl_add_u64 v[170:171], v[170:171], 0, v[164:165]
	v_lshl_add_u64 v[170:171], v[170:171], 0, v[172:173]
	v_lshl_add_u64 v[170:171], v[170:171], 0, v[132:133]
	v_cvt_pk_bf16_f32 v177, v183, v180
	global_store_dwordx2 v[170:171], v[176:177], off
	v_add_u32_e32 v176, 0x80, v216
	v_ashrrev_i32_e32 v170, 8, v176
	v_ashrrev_i32_e32 v171, 31, v170
	v_lshlrev_b64 v[170:171], 3, v[170:171]
	v_lshl_add_u64 v[174:175], v[170:171], 0, v[174:175]
	v_bfe_u32 v216, v176, 5, 3
	v_or_b32_e32 v174, v174, v216
	v_lshlrev_b64 v[174:175], 13, v[174:175]
	v_lshl_add_u64 v[174:175], v[130:131], 0, v[174:175]
	v_lshl_add_u64 v[174:175], v[174:175], 0, v[164:165]
	v_lshl_add_u64 v[174:175], v[174:175], 0, v[172:173]
	v_lshl_add_u64 v[174:175], v[174:175], 0, v[132:133]
	v_cvt_pk_bf16_f32 v176, v181, v182
	v_cvt_pk_bf16_f32 v177, v184, v185
	v_add_u32_e32 v180, 16, v162
	global_store_dwordx2 v[174:175], v[176:177], off
	v_ashrrev_i32_e32 v176, 6, v180
	v_and_b32_e32 v177, 60, v180
	v_cndmask_b32_e32 v181, v177, v176, vcc
	v_cvt_f32_i32_e32 v221, v181
	v_cmp_gt_i32_e64 s[4:5], s2, v162
	v_ashrrev_i32_e32 v174, 7, v180
	v_ashrrev_i32_e32 v175, 31, v174
	v_mul_f32_e32 v181, v208, v221
	v_mul_f32_e32 v181, 0.15915494, v181
	v_cos_f32_e32 v182, v181
	v_sin_f32_e32 v181, v181
	v_lshlrev_b64 v[174:175], 5, v[174:175]
	s_movk_i32 s2, 0x3f80
	v_cndmask_b32_e64 v182, 1.0, v182, s[4:5]
	v_cndmask_b32_e64 v181, 0, v181, s[4:5]
	v_mul_f32_e32 v183, v54, v181
	v_fma_f32 v183, v118, v182, -v183
	v_mul_f32_e32 v182, v54, v182
	v_fmac_f32_e32 v182, v118, v181
	v_mul_f32_e32 v181, 0x3d800000, v182
	v_or_b32_e32 v182, 1, v177
	v_cndmask_b32_e32 v182, v182, v176, vcc
	v_cvt_f32_i32_e32 v182, v182
	v_mul_f32_e32 v183, 0x3d800000, v183
	v_mul_f32_e32 v184, v208, v182
	v_mul_f32_e32 v184, 0.15915494, v184
	v_cos_f32_e32 v185, v184
	v_sin_f32_e32 v184, v184
	v_cndmask_b32_e64 v185, 1.0, v185, s[4:5]
	v_cndmask_b32_e64 v184, 0, v184, s[4:5]
	v_mul_f32_e32 v222, v55, v184
	v_fma_f32 v222, v119, v185, -v222
	v_mul_f32_e32 v185, v55, v185
	v_fmac_f32_e32 v185, v119, v184
	v_mul_f32_e32 v184, 0x3d800000, v185
	v_or_b32_e32 v185, 2, v177
	v_cndmask_b32_e32 v185, v185, v176, vcc
	v_cvt_f32_i32_e32 v185, v185
	v_or_b32_e32 v177, 3, v177
	v_cndmask_b32_e32 v176, v177, v176, vcc
	v_cvt_f32_i32_e32 v227, v176
	v_mul_f32_e32 v224, 0x3d800000, v222
	v_mul_f32_e32 v222, v208, v185
	v_mul_f32_e32 v222, 0.15915494, v222
	v_cos_f32_e32 v223, v222
	v_sin_f32_e32 v222, v222
	v_mul_f32_e32 v176, v208, v227
	v_mul_f32_e32 v176, 0.15915494, v176
	v_cos_f32_e32 v177, v176
	v_sin_f32_e32 v176, v176
	v_cndmask_b32_e64 v222, 0, v222, s[4:5]
	v_cndmask_b32_e64 v223, 1.0, v223, s[4:5]
	v_mul_f32_e32 v225, v56, v222
	v_fma_f32 v225, v120, v223, -v225
	v_mul_f32_e32 v223, v56, v223
	v_cndmask_b32_e64 v176, 0, v176, s[4:5]
	v_fmac_f32_e32 v223, v120, v222
	v_cndmask_b32_e64 v177, 1.0, v177, s[4:5]
	v_mul_f32_e32 v222, v57, v176
	v_fma_f32 v222, v121, v177, -v222
	v_mul_f32_e32 v177, v57, v177
	v_fmac_f32_e32 v177, v121, v176
	v_mul_f32_e32 v229, 0x3d800000, v177
	v_lshl_add_u64 v[176:177], v[174:175], 0, v[134:135]
	v_or_b32_e32 v176, v176, v209
	v_lshlrev_b64 v[176:177], 13, v[176:177]
	v_lshl_add_u64 v[176:177], v[130:131], 0, v[176:177]
	v_mul_f32_e32 v226, 0x3d800000, v223
	v_mul_f32_e32 v228, 0x3d800000, v222
	v_lshl_add_u64 v[222:223], v[176:177], 0, v[0:1]
	v_lshlrev_b32_e32 v176, 6, v180
	v_and_b32_e32 v176, 0x1c00, v176
	v_mov_b32_e32 v177, v1
	v_mul_f32_e32 v225, 0x3d800000, v225
	v_lshl_add_u64 v[222:223], v[222:223], 0, v[176:177]
	v_mul_f32_e32 v180, v207, v221
	v_lshl_add_u64 v[222:223], v[222:223], 0, v[132:133]
	v_cvt_pk_bf16_f32 v224, v183, v224
	v_cvt_pk_bf16_f32 v225, v225, v228
	v_mul_f32_e32 v180, 0.15915494, v180
	global_store_dwordx2 v[222:223], v[224:225], off
	v_cvt_pk_bf16_f32 v224, v181, v184
	v_cos_f32_e32 v181, v180
	v_sin_f32_e32 v180, v180
	v_lshl_add_u64 v[222:223], v[138:139], 0, v[174:175]
	v_or_b32_e32 v222, v222, v210
	v_cndmask_b32_e64 v181, 1.0, v181, s[4:5]
	v_cndmask_b32_e64 v180, 0, v180, s[4:5]
	v_mul_f32_e32 v183, v38, v180
	v_fma_f32 v183, v102, v181, -v183
	v_mul_f32_e32 v181, v38, v181
	v_fmac_f32_e32 v181, v102, v180
	v_mul_f32_e32 v180, 0x3d800000, v181
	v_mul_f32_e32 v181, v207, v182
	v_mul_f32_e32 v181, 0.15915494, v181
	v_lshlrev_b64 v[222:223], 13, v[222:223]
	v_cos_f32_e32 v184, v181
	v_sin_f32_e32 v181, v181
	v_lshl_add_u64 v[222:223], v[130:131], 0, v[222:223]
	v_lshl_add_u64 v[222:223], v[222:223], 0, v[0:1]
	v_lshl_add_u64 v[222:223], v[222:223], 0, v[176:177]
	v_lshl_add_u64 v[222:223], v[222:223], 0, v[132:133]
	v_cvt_pk_bf16_f32 v225, v226, v229
	v_cndmask_b32_e64 v181, 0, v181, s[4:5]
	global_store_dwordx2 v[222:223], v[224:225], off
	v_cndmask_b32_e64 v184, 1.0, v184, s[4:5]
	v_mul_f32_e32 v222, v39, v181
	v_fma_f32 v222, v103, v184, -v222
	v_mul_f32_e32 v184, v39, v184
	v_fmac_f32_e32 v184, v103, v181
	v_mul_f32_e32 v181, 0x3d800000, v184
	v_mul_f32_e32 v184, v207, v185
	v_mul_f32_e32 v184, 0.15915494, v184
	v_mul_f32_e32 v224, 0x3d800000, v222
	v_cos_f32_e32 v222, v184
	v_sin_f32_e32 v184, v184
	v_mul_f32_e32 v183, 0x3d800000, v183
	v_cvt_pk_bf16_f32 v224, v183, v224
	v_cndmask_b32_e64 v222, 1.0, v222, s[4:5]
	v_cndmask_b32_e64 v184, 0, v184, s[4:5]
	v_mul_f32_e32 v223, v40, v184
	v_fma_f32 v223, v104, v222, -v223
	v_mul_f32_e32 v222, v40, v222
	v_fmac_f32_e32 v222, v104, v184
	v_mul_f32_e32 v184, 0x3d800000, v222
	v_mul_f32_e32 v222, v207, v227
	v_mul_f32_e32 v222, 0.15915494, v222
	v_mul_f32_e32 v225, 0x3d800000, v223
	v_cos_f32_e32 v223, v222
	v_sin_f32_e32 v222, v222
	v_cndmask_b32_e64 v223, 1.0, v223, s[4:5]
	v_cndmask_b32_e64 v222, 0, v222, s[4:5]
	v_mul_f32_e32 v226, v41, v222
	v_fma_f32 v226, v105, v223, -v226
	v_mul_f32_e32 v223, v41, v223
	v_fmac_f32_e32 v223, v105, v222
	v_mul_f32_e32 v228, 0x3d800000, v223
	v_lshl_add_u64 v[222:223], v[140:141], 0, v[174:175]
	v_or_b32_e32 v222, v222, v211
	v_lshlrev_b64 v[222:223], 13, v[222:223]
	v_lshl_add_u64 v[222:223], v[130:131], 0, v[222:223]
	v_lshl_add_u64 v[222:223], v[222:223], 0, v[136:137]
	v_mul_f32_e32 v226, 0x3d800000, v226
	v_lshl_add_u64 v[222:223], v[222:223], 0, v[176:177]
	v_lshl_add_u64 v[222:223], v[222:223], 0, v[132:133]
	v_cvt_pk_bf16_f32 v225, v225, v226
	global_store_dwordx2 v[222:223], v[224:225], off
	v_cvt_pk_bf16_f32 v224, v180, v181
	v_mul_f32_e32 v180, v161, v221
	v_mul_f32_e32 v180, 0.15915494, v180
	v_cos_f32_e32 v181, v180
	v_sin_f32_e32 v180, v180
	v_lshl_add_u64 v[222:223], v[142:143], 0, v[174:175]
	v_or_b32_e32 v222, v222, v212
	v_cndmask_b32_e64 v181, 1.0, v181, s[4:5]
	v_cndmask_b32_e64 v180, 0, v180, s[4:5]
	v_mul_f32_e32 v183, v22, v180
	v_fma_f32 v183, v86, v181, -v183
	v_mul_f32_e32 v181, v22, v181
	v_fmac_f32_e32 v181, v86, v180
	v_mul_f32_e32 v180, 0x3d800000, v181
	v_mul_f32_e32 v181, v161, v182
	v_mul_f32_e32 v181, 0.15915494, v181
	v_lshlrev_b64 v[222:223], 13, v[222:223]
	v_cvt_pk_bf16_f32 v225, v184, v228
	v_cos_f32_e32 v184, v181
	v_sin_f32_e32 v181, v181
	v_lshl_add_u64 v[222:223], v[130:131], 0, v[222:223]
	v_lshl_add_u64 v[222:223], v[222:223], 0, v[136:137]
	v_lshl_add_u64 v[222:223], v[222:223], 0, v[176:177]
	v_lshl_add_u64 v[222:223], v[222:223], 0, v[132:133]
	v_cndmask_b32_e64 v181, 0, v181, s[4:5]
	global_store_dwordx2 v[222:223], v[224:225], off
	v_cndmask_b32_e64 v184, 1.0, v184, s[4:5]
	v_mul_f32_e32 v222, v23, v181
	v_fma_f32 v222, v87, v184, -v222
	v_mul_f32_e32 v184, v23, v184
	v_fmac_f32_e32 v184, v87, v181
	v_mul_f32_e32 v181, 0x3d800000, v184
	v_mul_f32_e32 v184, v161, v185
	v_mul_f32_e32 v184, 0.15915494, v184
	v_mul_f32_e32 v224, 0x3d800000, v222
	v_cos_f32_e32 v222, v184
	v_sin_f32_e32 v184, v184
	v_mul_f32_e32 v183, 0x3d800000, v183
	v_cvt_pk_bf16_f32 v224, v183, v224
	v_cndmask_b32_e64 v222, 1.0, v222, s[4:5]
	v_cndmask_b32_e64 v184, 0, v184, s[4:5]
	v_mul_f32_e32 v223, v24, v184
	v_fma_f32 v223, v88, v222, -v223
	v_mul_f32_e32 v222, v24, v222
	v_fmac_f32_e32 v222, v88, v184
	v_mul_f32_e32 v184, 0x3d800000, v222
	v_mul_f32_e32 v222, v161, v227
	v_mul_f32_e32 v222, 0.15915494, v222
	v_mul_f32_e32 v225, 0x3d800000, v223
	v_cos_f32_e32 v223, v222
	v_sin_f32_e32 v222, v222
	v_cndmask_b32_e64 v223, 1.0, v223, s[4:5]
	v_cndmask_b32_e64 v222, 0, v222, s[4:5]
	v_mul_f32_e32 v226, v25, v222
	v_fma_f32 v226, v89, v223, -v226
	v_mul_f32_e32 v223, v25, v223
	v_fmac_f32_e32 v223, v89, v222
	v_mul_f32_e32 v228, 0x3d800000, v223
	v_lshl_add_u64 v[222:223], v[144:145], 0, v[174:175]
	v_or_b32_e32 v222, v222, v213
	v_lshlrev_b64 v[222:223], 13, v[222:223]
	v_lshl_add_u64 v[222:223], v[130:131], 0, v[222:223]
	v_lshl_add_u64 v[222:223], v[222:223], 0, v[0:1]
	v_mul_f32_e32 v226, 0x3d800000, v226
	v_lshl_add_u64 v[222:223], v[222:223], 0, v[176:177]
	v_lshl_add_u64 v[222:223], v[222:223], 0, v[132:133]
	v_cvt_pk_bf16_f32 v225, v225, v226
	global_store_dwordx2 v[222:223], v[224:225], off
	v_cvt_pk_bf16_f32 v224, v180, v181
	v_mul_f32_e32 v180, v149, v221
	v_mul_f32_e32 v180, 0.15915494, v180
	v_cos_f32_e32 v181, v180
	v_sin_f32_e32 v180, v180
	v_cvt_pk_bf16_f32 v225, v184, v228
	v_lshl_add_u64 v[222:223], v[166:167], 0, v[174:175]
	v_cndmask_b32_e64 v181, 1.0, v181, s[4:5]
	v_cndmask_b32_e64 v180, 0, v180, s[4:5]
	v_mul_f32_e32 v183, v6, v180
	v_fma_f32 v183, v70, v181, -v183
	v_mul_f32_e32 v181, v6, v181
	v_fmac_f32_e32 v181, v70, v180
	v_mul_f32_e32 v180, 0x3d800000, v181
	v_mul_f32_e32 v181, v149, v182
	v_mul_f32_e32 v181, 0.15915494, v181
	v_cos_f32_e32 v182, v181
	v_sin_f32_e32 v181, v181
	v_or_b32_e32 v222, v222, v214
	v_lshlrev_b64 v[222:223], 13, v[222:223]
	v_cndmask_b32_e64 v182, 1.0, v182, s[4:5]
	v_cndmask_b32_e64 v181, 0, v181, s[4:5]
	v_mul_f32_e32 v184, v7, v181
	v_fma_f32 v184, v71, v182, -v184
	v_mul_f32_e32 v182, v7, v182
	v_fmac_f32_e32 v182, v71, v181
	v_mul_f32_e32 v181, 0x3d800000, v182
	v_mul_f32_e32 v182, v149, v185
	v_mul_f32_e32 v182, 0.15915494, v182
	v_cos_f32_e32 v185, v182
	v_sin_f32_e32 v182, v182
	v_lshl_add_u64 v[222:223], v[130:131], 0, v[222:223]
	v_lshl_add_u64 v[222:223], v[222:223], 0, v[0:1]
	v_cndmask_b32_e64 v185, 1.0, v185, s[4:5]
	v_cndmask_b32_e64 v182, 0, v182, s[4:5]
	v_mul_f32_e32 v221, v8, v182
	v_fma_f32 v221, v72, v185, -v221
	v_mul_f32_e32 v185, v8, v185
	v_fmac_f32_e32 v185, v72, v182
	v_lshl_add_u64 v[222:223], v[222:223], 0, v[176:177]
	v_mul_f32_e32 v182, 0x3d800000, v185
	v_mul_f32_e32 v185, v149, v227
	v_lshl_add_u64 v[222:223], v[222:223], 0, v[132:133]
	v_mul_f32_e32 v185, 0.15915494, v185
	global_store_dwordx2 v[222:223], v[224:225], off
	v_cos_f32_e32 v222, v185
	v_sin_f32_e32 v185, v185
	v_mul_f32_e32 v183, 0x3d800000, v183
	v_mul_f32_e32 v184, 0x3d800000, v184
	v_cndmask_b32_e64 v222, 1.0, v222, s[4:5]
	v_cndmask_b32_e64 v185, 0, v185, s[4:5]
	v_mul_f32_e32 v223, v9, v185
	v_fma_f32 v223, v73, v222, -v223
	v_mul_f32_e32 v222, v9, v222
	v_fmac_f32_e32 v222, v73, v185
	v_mul_f32_e32 v225, 0x3d800000, v223
	v_mul_f32_e32 v185, 0x3d800000, v222
	v_lshl_add_u64 v[222:223], v[168:169], 0, v[174:175]
	v_lshl_add_u64 v[174:175], v[170:171], 0, v[174:175]
	v_or_b32_e32 v222, v222, v215
	v_or_b32_e32 v174, v174, v216
	v_lshlrev_b64 v[222:223], 13, v[222:223]
	v_lshlrev_b64 v[174:175], 13, v[174:175]
	v_lshl_add_u64 v[222:223], v[130:131], 0, v[222:223]
	v_lshl_add_u64 v[174:175], v[130:131], 0, v[174:175]
	v_lshl_add_u64 v[222:223], v[222:223], 0, v[164:165]
	v_lshl_add_u64 v[174:175], v[174:175], 0, v[164:165]
	v_mul_f32_e32 v221, 0x3d800000, v221
	v_lshl_add_u64 v[222:223], v[222:223], 0, v[176:177]
	v_lshl_add_u64 v[174:175], v[174:175], 0, v[176:177]
	v_lshl_add_u64 v[222:223], v[222:223], 0, v[132:133]
	v_cvt_pk_bf16_f32 v224, v183, v184
	v_cvt_pk_bf16_f32 v225, v221, v225
	v_lshl_add_u64 v[174:175], v[174:175], 0, v[132:133]
	v_cvt_pk_bf16_f32 v176, v180, v181
	v_cvt_pk_bf16_f32 v177, v182, v185
	global_store_dwordx2 v[222:223], v[224:225], off
	global_store_dwordx2 v[174:175], v[176:177], off
	v_add_u32_e32 v174, 0x80, v162
	v_ashrrev_i32_e32 v177, 6, v174
	v_cndmask_b32_e32 v176, v217, v177, vcc
	v_cvt_f32_i32_e32 v176, v176
	v_cmp_gt_i32_e64 s[4:5], s2, v162
	v_ashrrev_i32_e32 v174, 7, v174
	v_ashrrev_i32_e32 v175, 31, v174
	v_mul_f32_e32 v180, v208, v176
	v_mul_f32_e32 v180, 0.15915494, v180
	v_cos_f32_e32 v181, v180
	v_sin_f32_e32 v180, v180
	v_lshlrev_b64 v[174:175], 5, v[174:175]
	s_movk_i32 s2, 0x3f70
	v_cndmask_b32_e64 v181, 1.0, v181, s[4:5]
	v_cndmask_b32_e64 v180, 0, v180, s[4:5]
	v_mul_f32_e32 v182, v58, v180
	v_fma_f32 v182, v122, v181, -v182
	v_mul_f32_e32 v181, v58, v181
	v_fmac_f32_e32 v181, v122, v180
	v_mul_f32_e32 v180, 0x3d800000, v181
	v_cndmask_b32_e32 v181, v218, v177, vcc
	v_cvt_f32_i32_e32 v181, v181
	v_mul_f32_e32 v182, 0x3d800000, v182
	v_mul_f32_e32 v183, v208, v181
	v_mul_f32_e32 v183, 0.15915494, v183
	v_cos_f32_e32 v184, v183
	v_sin_f32_e32 v183, v183
	v_cndmask_b32_e64 v184, 1.0, v184, s[4:5]
	v_cndmask_b32_e64 v183, 0, v183, s[4:5]
	v_mul_f32_e32 v185, v59, v183
	v_fma_f32 v185, v123, v184, -v185
	v_mul_f32_e32 v184, v59, v184
	v_fmac_f32_e32 v184, v123, v183
	v_mul_f32_e32 v183, 0x3d800000, v184
	v_cndmask_b32_e32 v184, v219, v177, vcc
	v_cvt_f32_i32_e32 v184, v184
	v_cndmask_b32_e32 v177, v220, v177, vcc
	v_cvt_f32_i32_e32 v177, v177
	v_mul_f32_e32 v185, 0x3d800000, v185
	v_mul_f32_e32 v217, v208, v184
	v_mul_f32_e32 v217, 0.15915494, v217
	v_cos_f32_e32 v218, v217
	v_sin_f32_e32 v217, v217
	v_cndmask_b32_e64 v218, 1.0, v218, s[4:5]
	v_cndmask_b32_e64 v217, 0, v217, s[4:5]
	v_mul_f32_e32 v219, v60, v217
	v_fma_f32 v219, v124, v218, -v219
	v_mul_f32_e32 v218, v60, v218
	v_fmac_f32_e32 v218, v124, v217
	v_mul_f32_e32 v217, 0x3d800000, v218
	v_mul_f32_e32 v218, v208, v177
	v_mul_f32_e32 v218, 0.15915494, v218
	v_mul_f32_e32 v221, 0x3d800000, v219
	v_cos_f32_e32 v219, v218
	v_sin_f32_e32 v218, v218
	v_cndmask_b32_e64 v219, 1.0, v219, s[4:5]
	v_cndmask_b32_e64 v218, 0, v218, s[4:5]
	v_mul_f32_e32 v220, v61, v218
	v_fma_f32 v220, v125, v219, -v220
	v_mul_f32_e32 v219, v61, v219
	v_fmac_f32_e32 v219, v125, v218
	v_mul_f32_e32 v223, 0x3d800000, v219
	v_lshl_add_u64 v[218:219], v[174:175], 0, v[134:135]
	v_or_b32_e32 v218, v218, v209
	v_lshlrev_b64 v[218:219], 13, v[218:219]
	v_lshl_add_u64 v[218:219], v[130:131], 0, v[218:219]
	v_lshl_add_u64 v[218:219], v[218:219], 0, v[0:1]
	v_mul_f32_e32 v222, 0x3d800000, v220
	v_lshl_add_u64 v[218:219], v[218:219], 0, v[172:173]
	v_lshl_add_u64 v[218:219], v[218:219], 0, v[132:133]
	v_cvt_pk_bf16_f32 v220, v182, v185
	v_cvt_pk_bf16_f32 v221, v221, v222
	global_store_dwordx2 v[218:219], v[220:221], off
	v_cvt_pk_bf16_f32 v220, v180, v183
	v_mul_f32_e32 v180, v207, v176
	v_mul_f32_e32 v180, 0.15915494, v180
	v_cos_f32_e32 v182, v180
	v_sin_f32_e32 v180, v180
	v_lshl_add_u64 v[218:219], v[138:139], 0, v[174:175]
	v_or_b32_e32 v218, v218, v210
	v_cndmask_b32_e64 v182, 1.0, v182, s[4:5]
	v_cndmask_b32_e64 v180, 0, v180, s[4:5]
	v_mul_f32_e32 v183, v42, v180
	v_fma_f32 v183, v106, v182, -v183
	v_mul_f32_e32 v182, v42, v182
	v_fmac_f32_e32 v182, v106, v180
	v_mul_f32_e32 v180, 0x3d800000, v182
	v_mul_f32_e32 v182, v207, v181
	v_mul_f32_e32 v182, 0.15915494, v182
	v_cos_f32_e32 v185, v182
	v_sin_f32_e32 v182, v182
	v_lshlrev_b64 v[218:219], 13, v[218:219]
	v_cvt_pk_bf16_f32 v221, v217, v223
	v_cndmask_b32_e64 v185, 1.0, v185, s[4:5]
	v_cndmask_b32_e64 v182, 0, v182, s[4:5]
	v_mul_f32_e32 v217, v43, v182
	v_lshl_add_u64 v[218:219], v[130:131], 0, v[218:219]
	v_fma_f32 v217, v107, v185, -v217
	v_mul_f32_e32 v185, v43, v185
	v_lshl_add_u64 v[218:219], v[218:219], 0, v[0:1]
	v_fmac_f32_e32 v185, v107, v182
	v_lshl_add_u64 v[218:219], v[218:219], 0, v[172:173]
	v_mul_f32_e32 v182, 0x3d800000, v185
	v_mul_f32_e32 v185, v207, v184
	v_lshl_add_u64 v[218:219], v[218:219], 0, v[132:133]
	v_mul_f32_e32 v185, 0.15915494, v185
	global_store_dwordx2 v[218:219], v[220:221], off
	v_cos_f32_e32 v218, v185
	v_sin_f32_e32 v185, v185
	v_mul_f32_e32 v183, 0x3d800000, v183
	v_mul_f32_e32 v217, 0x3d800000, v217
	v_cndmask_b32_e64 v218, 1.0, v218, s[4:5]
	v_cndmask_b32_e64 v185, 0, v185, s[4:5]
	v_mul_f32_e32 v219, v44, v185
	v_fma_f32 v219, v108, v218, -v219
	v_mul_f32_e32 v218, v44, v218
	v_fmac_f32_e32 v218, v108, v185
	v_mul_f32_e32 v185, 0x3d800000, v218
	v_mul_f32_e32 v218, v207, v177
	v_mul_f32_e32 v218, 0.15915494, v218
	v_mul_f32_e32 v221, 0x3d800000, v219
	v_cos_f32_e32 v219, v218
	v_sin_f32_e32 v218, v218
	v_cndmask_b32_e64 v219, 1.0, v219, s[4:5]
	v_cndmask_b32_e64 v218, 0, v218, s[4:5]
	v_mul_f32_e32 v220, v45, v218
	v_fma_f32 v220, v109, v219, -v220
	v_mul_f32_e32 v219, v45, v219
	v_fmac_f32_e32 v219, v109, v218
	v_mul_f32_e32 v223, 0x3d800000, v219
	v_lshl_add_u64 v[218:219], v[140:141], 0, v[174:175]
	v_or_b32_e32 v218, v218, v211
	v_lshlrev_b64 v[218:219], 13, v[218:219]
	v_lshl_add_u64 v[218:219], v[130:131], 0, v[218:219]
	v_lshl_add_u64 v[218:219], v[218:219], 0, v[136:137]
	v_mul_f32_e32 v222, 0x3d800000, v220
	v_lshl_add_u64 v[218:219], v[218:219], 0, v[172:173]
	v_lshl_add_u64 v[218:219], v[218:219], 0, v[132:133]
	v_cvt_pk_bf16_f32 v220, v183, v217
	v_cvt_pk_bf16_f32 v221, v221, v222
	global_store_dwordx2 v[218:219], v[220:221], off
	v_cvt_pk_bf16_f32 v220, v180, v182
	v_mul_f32_e32 v180, v161, v176
	v_mul_f32_e32 v180, 0.15915494, v180
	v_cos_f32_e32 v182, v180
	v_sin_f32_e32 v180, v180
	v_cvt_pk_bf16_f32 v221, v185, v223
	v_lshl_add_u64 v[218:219], v[142:143], 0, v[174:175]
	v_cndmask_b32_e64 v182, 1.0, v182, s[4:5]
	v_cndmask_b32_e64 v180, 0, v180, s[4:5]
	v_mul_f32_e32 v183, v26, v180
	v_fma_f32 v183, v90, v182, -v183
	v_mul_f32_e32 v182, v26, v182
	v_fmac_f32_e32 v182, v90, v180
	v_mul_f32_e32 v180, 0x3d800000, v182
	v_mul_f32_e32 v182, v161, v181
	v_mul_f32_e32 v182, 0.15915494, v182
	v_cos_f32_e32 v185, v182
	v_sin_f32_e32 v182, v182
	v_or_b32_e32 v218, v218, v212
	v_lshlrev_b64 v[218:219], 13, v[218:219]
	v_cndmask_b32_e64 v185, 1.0, v185, s[4:5]
	v_cndmask_b32_e64 v182, 0, v182, s[4:5]
	v_mul_f32_e32 v217, v27, v182
	v_lshl_add_u64 v[218:219], v[130:131], 0, v[218:219]
	v_fma_f32 v217, v91, v185, -v217
	v_mul_f32_e32 v185, v27, v185
	v_lshl_add_u64 v[218:219], v[218:219], 0, v[136:137]
	v_fmac_f32_e32 v185, v91, v182
	v_lshl_add_u64 v[218:219], v[218:219], 0, v[172:173]
	v_mul_f32_e32 v182, 0x3d800000, v185
	v_mul_f32_e32 v185, v161, v184
	v_lshl_add_u64 v[218:219], v[218:219], 0, v[132:133]
	v_mul_f32_e32 v185, 0.15915494, v185
	global_store_dwordx2 v[218:219], v[220:221], off
	v_cos_f32_e32 v218, v185
	v_sin_f32_e32 v185, v185
	v_mul_f32_e32 v183, 0x3d800000, v183
	v_mul_f32_e32 v217, 0x3d800000, v217
	v_cndmask_b32_e64 v218, 1.0, v218, s[4:5]
	v_cndmask_b32_e64 v185, 0, v185, s[4:5]
	v_mul_f32_e32 v219, v28, v185
	v_fma_f32 v219, v92, v218, -v219
	v_mul_f32_e32 v218, v28, v218
	v_fmac_f32_e32 v218, v92, v185
	v_mul_f32_e32 v185, 0x3d800000, v218
	v_mul_f32_e32 v218, v161, v177
	v_mul_f32_e32 v218, 0.15915494, v218
	v_mul_f32_e32 v221, 0x3d800000, v219
	v_cos_f32_e32 v219, v218
	v_sin_f32_e32 v218, v218
	v_mul_f32_e32 v176, v149, v176
	v_mul_f32_e32 v176, 0.15915494, v176
	v_cndmask_b32_e64 v219, 1.0, v219, s[4:5]
	v_cndmask_b32_e64 v218, 0, v218, s[4:5]
	v_mul_f32_e32 v220, v29, v218
	v_fma_f32 v220, v93, v219, -v220
	v_mul_f32_e32 v219, v29, v219
	v_fmac_f32_e32 v219, v93, v218
	v_mul_f32_e32 v223, 0x3d800000, v219
	v_lshl_add_u64 v[218:219], v[144:145], 0, v[174:175]
	v_or_b32_e32 v218, v218, v213
	v_lshlrev_b64 v[218:219], 13, v[218:219]
	v_lshl_add_u64 v[218:219], v[130:131], 0, v[218:219]
	v_lshl_add_u64 v[218:219], v[218:219], 0, v[0:1]
	v_mul_f32_e32 v222, 0x3d800000, v220
	v_lshl_add_u64 v[218:219], v[218:219], 0, v[172:173]
	v_lshl_add_u64 v[218:219], v[218:219], 0, v[132:133]
	v_cvt_pk_bf16_f32 v220, v183, v217
	v_cvt_pk_bf16_f32 v221, v221, v222
	global_store_dwordx2 v[218:219], v[220:221], off
	v_cvt_pk_bf16_f32 v220, v180, v182
	v_cos_f32_e32 v180, v176
	v_sin_f32_e32 v176, v176
	v_cvt_pk_bf16_f32 v221, v185, v223
	v_lshl_add_u64 v[218:219], v[166:167], 0, v[174:175]
	v_cndmask_b32_e64 v180, 1.0, v180, s[4:5]
	v_cndmask_b32_e64 v176, 0, v176, s[4:5]
	v_mul_f32_e32 v182, v10, v176
	v_fma_f32 v182, v74, v180, -v182
	v_mul_f32_e32 v180, v10, v180
	v_fmac_f32_e32 v180, v74, v176
	v_mul_f32_e32 v176, v149, v181
	v_mul_f32_e32 v176, 0.15915494, v176
	v_cos_f32_e32 v181, v176
	v_sin_f32_e32 v176, v176
	v_or_b32_e32 v218, v218, v214
	v_lshlrev_b64 v[218:219], 13, v[218:219]
	v_cndmask_b32_e64 v181, 1.0, v181, s[4:5]
	v_cndmask_b32_e64 v176, 0, v176, s[4:5]
	v_mul_f32_e32 v183, v11, v176
	v_fma_f32 v183, v75, v181, -v183
	v_mul_f32_e32 v181, v11, v181
	v_fmac_f32_e32 v181, v75, v176
	v_mul_f32_e32 v176, v149, v184
	v_mul_f32_e32 v176, 0.15915494, v176
	v_cos_f32_e32 v184, v176
	v_sin_f32_e32 v176, v176
	v_lshl_add_u64 v[218:219], v[130:131], 0, v[218:219]
	v_lshl_add_u64 v[218:219], v[218:219], 0, v[0:1]
	v_cndmask_b32_e64 v184, 1.0, v184, s[4:5]
	v_cndmask_b32_e64 v176, 0, v176, s[4:5]
	v_mul_f32_e32 v185, v12, v176
	v_fma_f32 v185, v76, v184, -v185
	v_mul_f32_e32 v184, v12, v184
	v_fmac_f32_e32 v184, v76, v176
	v_mul_f32_e32 v176, v149, v177
	v_mul_f32_e32 v176, 0.15915494, v176
	v_cos_f32_e32 v177, v176
	v_sin_f32_e32 v176, v176
	v_lshl_add_u64 v[218:219], v[218:219], 0, v[172:173]
	v_lshl_add_u64 v[218:219], v[218:219], 0, v[132:133]
	v_cndmask_b32_e64 v177, 1.0, v177, s[4:5]
	v_cndmask_b32_e64 v176, 0, v176, s[4:5]
	v_mul_f32_e32 v217, v13, v176
	v_fma_f32 v217, v77, v177, -v217
	v_mul_f32_e32 v177, v13, v177
	v_fmac_f32_e32 v177, v77, v176
	global_store_dwordx2 v[218:219], v[220:221], off
	v_mul_f32_e32 v220, 0x3d800000, v177
	v_lshl_add_u64 v[176:177], v[168:169], 0, v[174:175]
	v_lshl_add_u64 v[174:175], v[170:171], 0, v[174:175]
	v_or_b32_e32 v176, v176, v215
	v_or_b32_e32 v174, v174, v216
	v_lshlrev_b64 v[176:177], 13, v[176:177]
	v_lshlrev_b64 v[174:175], 13, v[174:175]
	v_lshl_add_u64 v[176:177], v[130:131], 0, v[176:177]
	v_lshl_add_u64 v[174:175], v[130:131], 0, v[174:175]
	v_lshl_add_u64 v[176:177], v[176:177], 0, v[164:165]
	v_lshl_add_u64 v[174:175], v[174:175], 0, v[164:165]
	v_mul_f32_e32 v182, 0x3d800000, v182
	v_mul_f32_e32 v180, 0x3d800000, v180
	v_mul_f32_e32 v183, 0x3d800000, v183
	v_mul_f32_e32 v181, 0x3d800000, v181
	v_mul_f32_e32 v185, 0x3d800000, v185
	v_mul_f32_e32 v184, 0x3d800000, v184
	v_mul_f32_e32 v217, 0x3d800000, v217
	v_lshl_add_u64 v[176:177], v[176:177], 0, v[172:173]
	v_lshl_add_u64 v[172:173], v[174:175], 0, v[172:173]
	v_lshl_add_u64 v[176:177], v[176:177], 0, v[132:133]
	v_cvt_pk_bf16_f32 v218, v182, v183
	v_cvt_pk_bf16_f32 v219, v185, v217
	v_lshl_add_u64 v[172:173], v[172:173], 0, v[132:133]
	v_cvt_pk_bf16_f32 v174, v180, v181
	v_cvt_pk_bf16_f32 v175, v184, v220
	global_store_dwordx2 v[176:177], v[218:219], off
	global_store_dwordx2 v[172:173], v[174:175], off
	v_add_u32_e32 v175, 0x90, v162
	v_ashrrev_i32_e32 v176, 6, v175
	v_and_b32_e32 v177, 60, v175
	v_cndmask_b32_e32 v174, v177, v176, vcc
	v_cvt_f32_i32_e32 v174, v174
	v_cmp_gt_i32_e64 s[4:5], s2, v162
	v_ashrrev_i32_e32 v172, 7, v175
	v_ashrrev_i32_e32 v173, 31, v172
	v_mul_f32_e32 v180, v208, v174
	v_mul_f32_e32 v180, 0.15915494, v180
	v_cos_f32_e32 v181, v180
	v_sin_f32_e32 v180, v180
	v_lshlrev_b64 v[172:173], 5, v[172:173]
	v_lshl_add_u64 v[134:135], v[172:173], 0, v[134:135]
	v_cndmask_b32_e64 v181, 1.0, v181, s[4:5]
	v_cndmask_b32_e64 v180, 0, v180, s[4:5]
	v_mul_f32_e32 v182, v50, v180
	v_fma_f32 v182, v114, v181, -v182
	v_mul_f32_e32 v181, v50, v181
	v_fmac_f32_e32 v181, v114, v180
	v_mul_f32_e32 v180, 0x3d800000, v181
	v_or_b32_e32 v181, 1, v177
	v_cndmask_b32_e32 v181, v181, v176, vcc
	v_cvt_f32_i32_e32 v181, v181
	v_or_b32_e32 v134, v134, v209
	v_lshlrev_b64 v[134:135], 13, v[134:135]
	v_lshl_add_u64 v[138:139], v[138:139], 0, v[172:173]
	v_mul_f32_e32 v183, v208, v181
	v_mul_f32_e32 v183, 0.15915494, v183
	v_cos_f32_e32 v184, v183
	v_sin_f32_e32 v183, v183
	v_lshl_add_u64 v[134:135], v[130:131], 0, v[134:135]
	v_or_b32_e32 v138, v138, v210
	v_cndmask_b32_e64 v184, 1.0, v184, s[4:5]
	v_cndmask_b32_e64 v183, 0, v183, s[4:5]
	v_mul_f32_e32 v185, v51, v183
	v_fma_f32 v185, v115, v184, -v185
	v_mul_f32_e32 v184, v51, v184
	v_fmac_f32_e32 v184, v115, v183
	v_mul_f32_e32 v183, 0x3d800000, v184
	v_or_b32_e32 v184, 2, v177
	v_cndmask_b32_e32 v184, v184, v176, vcc
	v_cvt_f32_i32_e32 v184, v184
	v_or_b32_e32 v177, 3, v177
	v_cndmask_b32_e32 v176, v177, v176, vcc
	v_lshlrev_b64 v[138:139], 13, v[138:139]
	v_mul_f32_e32 v217, v208, v184
	v_mul_f32_e32 v217, 0.15915494, v217
	v_cos_f32_e32 v218, v217
	v_sin_f32_e32 v217, v217
	v_lshl_add_u64 v[138:139], v[130:131], 0, v[138:139]
	v_mul_f32_e32 v182, 0x3d800000, v182
	v_cndmask_b32_e64 v218, 1.0, v218, s[4:5]
	v_cndmask_b32_e64 v217, 0, v217, s[4:5]
	v_mul_f32_e32 v219, v52, v217
	v_fma_f32 v219, v116, v218, -v219
	v_mul_f32_e32 v218, v52, v218
	v_fmac_f32_e32 v218, v116, v217
	v_mul_f32_e32 v217, 0x3d800000, v218
	v_cvt_f32_i32_e32 v218, v176
	v_mul_f32_e32 v185, 0x3d800000, v185
	v_mul_f32_e32 v219, 0x3d800000, v219
	v_lshl_add_u64 v[138:139], v[138:139], 0, v[0:1]
	v_mul_f32_e32 v176, v208, v218
	v_mul_f32_e32 v176, 0.15915494, v176
	v_cos_f32_e32 v177, v176
	v_sin_f32_e32 v176, v176
	s_mov_b64 s[2:3], 0
	v_cndmask_b32_e64 v177, 1.0, v177, s[4:5]
	v_cndmask_b32_e64 v176, 0, v176, s[4:5]
	v_mul_f32_e32 v208, v53, v176
	v_fma_f32 v208, v117, v177, -v208
	v_mul_f32_e32 v177, v53, v177
	v_fmac_f32_e32 v177, v117, v176
	v_mul_f32_e32 v221, 0x3d800000, v177
	v_lshl_add_u64 v[176:177], v[134:135], 0, v[0:1]
	v_lshlrev_b32_e32 v134, 6, v175
	v_and_b32_e32 v134, 0x1c00, v134
	v_mov_b32_e32 v135, v1
	v_mul_f32_e32 v220, 0x3d800000, v208
	v_lshl_add_u64 v[176:177], v[176:177], 0, v[134:135]
	v_lshl_add_u64 v[176:177], v[176:177], 0, v[132:133]
	v_cvt_pk_bf16_f32 v208, v182, v185
	v_cvt_pk_bf16_f32 v209, v219, v220
	v_lshl_add_u64 v[138:139], v[138:139], 0, v[134:135]
	global_store_dwordx2 v[176:177], v[208:209], off
	v_lshl_add_u64 v[138:139], v[138:139], 0, v[132:133]
	v_cvt_pk_bf16_f32 v176, v180, v183
	v_cvt_pk_bf16_f32 v177, v217, v221
	global_store_dwordx2 v[138:139], v[176:177], off
	v_mul_f32_e32 v138, v207, v174
	v_mul_f32_e32 v138, 0.15915494, v138
	v_cos_f32_e32 v139, v138
	v_sin_f32_e32 v138, v138
	v_cndmask_b32_e64 v139, 1.0, v139, s[4:5]
	v_cndmask_b32_e64 v138, 0, v138, s[4:5]
	v_mul_f32_e32 v175, v34, v138
	v_fma_f32 v175, v98, v139, -v175
	v_mul_f32_e32 v139, v34, v139
	v_fmac_f32_e32 v139, v98, v138
	v_mul_f32_e32 v138, v207, v181
	v_mul_f32_e32 v138, 0.15915494, v138
	v_mul_f32_e32 v176, 0x3d800000, v139
	v_cos_f32_e32 v139, v138
	v_sin_f32_e32 v138, v138
	v_mul_f32_e32 v175, 0x3d800000, v175
	v_cndmask_b32_e64 v139, 1.0, v139, s[4:5]
	v_cndmask_b32_e64 v138, 0, v138, s[4:5]
	v_mul_f32_e32 v177, v35, v138
	v_fma_f32 v177, v99, v139, -v177
	v_mul_f32_e32 v139, v35, v139
	v_fmac_f32_e32 v139, v99, v138
	v_mul_f32_e32 v138, v207, v184
	v_mul_f32_e32 v138, 0.15915494, v138
	v_mul_f32_e32 v180, 0x3d800000, v139
	v_cos_f32_e32 v139, v138
	v_sin_f32_e32 v138, v138
	v_mul_f32_e32 v177, 0x3d800000, v177
	v_cndmask_b32_e64 v139, 1.0, v139, s[4:5]
	v_cndmask_b32_e64 v138, 0, v138, s[4:5]
	v_mul_f32_e32 v182, v36, v138
	v_fma_f32 v182, v100, v139, -v182
	v_mul_f32_e32 v139, v36, v139
	v_fmac_f32_e32 v139, v100, v138
	v_mul_f32_e32 v138, v207, v218
	v_mul_f32_e32 v138, 0.15915494, v138
	v_mul_f32_e32 v183, 0x3d800000, v139
	v_cos_f32_e32 v139, v138
	v_sin_f32_e32 v138, v138
	v_mul_f32_e32 v182, 0x3d800000, v182
	v_cndmask_b32_e64 v139, 1.0, v139, s[4:5]
	v_cndmask_b32_e64 v138, 0, v138, s[4:5]
	v_mul_f32_e32 v185, v37, v138
	v_fma_f32 v185, v101, v139, -v185
	v_mul_f32_e32 v139, v37, v139
	v_fmac_f32_e32 v139, v101, v138
	v_mul_f32_e32 v207, 0x3d800000, v139
	v_lshl_add_u64 v[138:139], v[140:141], 0, v[172:173]
	v_or_b32_e32 v138, v138, v211
	v_lshlrev_b64 v[138:139], 13, v[138:139]
	v_lshl_add_u64 v[138:139], v[130:131], 0, v[138:139]
	v_lshl_add_u64 v[138:139], v[138:139], 0, v[136:137]
	v_mul_f32_e32 v185, 0x3d800000, v185
	v_lshl_add_u64 v[138:139], v[138:139], 0, v[134:135]
	v_lshl_add_u64 v[138:139], v[138:139], 0, v[132:133]
	v_cvt_pk_bf16_f32 v140, v175, v177
	v_cvt_pk_bf16_f32 v141, v182, v185
	global_store_dwordx2 v[138:139], v[140:141], off
	v_lshl_add_u64 v[138:139], v[142:143], 0, v[172:173]
	v_or_b32_e32 v138, v138, v212
	v_lshlrev_b64 v[138:139], 13, v[138:139]
	v_lshl_add_u64 v[138:139], v[130:131], 0, v[138:139]
	v_lshl_add_u64 v[136:137], v[138:139], 0, v[136:137]
	v_lshl_add_u64 v[136:137], v[136:137], 0, v[134:135]
	v_lshl_add_u64 v[136:137], v[136:137], 0, v[132:133]
	v_cvt_pk_bf16_f32 v138, v176, v180
	v_cvt_pk_bf16_f32 v139, v183, v207
	global_store_dwordx2 v[136:137], v[138:139], off
	v_mul_f32_e32 v136, v161, v174
	v_mul_f32_e32 v136, 0.15915494, v136
	v_cos_f32_e32 v137, v136
	v_sin_f32_e32 v136, v136
	v_cndmask_b32_e64 v137, 1.0, v137, s[4:5]
	v_cndmask_b32_e64 v136, 0, v136, s[4:5]
	v_mul_f32_e32 v138, v18, v136
	v_fma_f32 v138, v82, v137, -v138
	v_mul_f32_e32 v137, v18, v137
	v_fmac_f32_e32 v137, v82, v136
	v_mul_f32_e32 v136, v161, v181
	v_mul_f32_e32 v136, 0.15915494, v136
	v_mul_f32_e32 v140, 0x3d800000, v137
	v_cos_f32_e32 v137, v136
	v_sin_f32_e32 v136, v136
	v_mul_f32_e32 v138, 0x3d800000, v138
	v_cndmask_b32_e64 v137, 1.0, v137, s[4:5]
	v_cndmask_b32_e64 v136, 0, v136, s[4:5]
	v_mul_f32_e32 v139, v19, v136
	v_fma_f32 v139, v83, v137, -v139
	v_mul_f32_e32 v137, v19, v137
	v_fmac_f32_e32 v137, v83, v136
	v_mul_f32_e32 v136, v161, v184
	v_mul_f32_e32 v136, 0.15915494, v136
	v_mul_f32_e32 v141, 0x3d800000, v137
	v_cos_f32_e32 v137, v136
	v_sin_f32_e32 v136, v136
	v_mul_f32_e32 v139, 0x3d800000, v139
	v_cvt_pk_bf16_f32 v138, v138, v139
	v_cndmask_b32_e64 v137, 1.0, v137, s[4:5]
	v_cndmask_b32_e64 v136, 0, v136, s[4:5]
	v_mul_f32_e32 v142, v20, v136
	v_fma_f32 v142, v84, v137, -v142
	v_mul_f32_e32 v137, v20, v137
	v_fmac_f32_e32 v137, v84, v136
	v_mul_f32_e32 v136, v161, v218
	v_mul_f32_e32 v136, 0.15915494, v136
	v_mul_f32_e32 v143, 0x3d800000, v137
	v_cos_f32_e32 v137, v136
	v_sin_f32_e32 v136, v136
	v_mul_f32_e32 v142, 0x3d800000, v142
	v_cndmask_b32_e64 v137, 1.0, v137, s[4:5]
	v_cndmask_b32_e64 v136, 0, v136, s[4:5]
	v_mul_f32_e32 v161, v21, v136
	v_fma_f32 v161, v85, v137, -v161
	v_mul_f32_e32 v137, v21, v137
	v_fmac_f32_e32 v137, v85, v136
	v_mul_f32_e32 v175, 0x3d800000, v137
	v_lshl_add_u64 v[136:137], v[144:145], 0, v[172:173]
	v_or_b32_e32 v136, v136, v213
	v_lshlrev_b64 v[136:137], 13, v[136:137]
	v_lshl_add_u64 v[136:137], v[130:131], 0, v[136:137]
	v_lshl_add_u64 v[136:137], v[136:137], 0, v[0:1]
	v_mul_f32_e32 v161, 0x3d800000, v161
	v_lshl_add_u64 v[136:137], v[136:137], 0, v[134:135]
	v_lshl_add_u64 v[136:137], v[136:137], 0, v[132:133]
	v_cvt_pk_bf16_f32 v139, v142, v161
	global_store_dwordx2 v[136:137], v[138:139], off
	v_lshl_add_u64 v[136:137], v[166:167], 0, v[172:173]
	v_or_b32_e32 v136, v136, v214
	v_lshlrev_b64 v[136:137], 13, v[136:137]
	v_lshl_add_u64 v[136:137], v[130:131], 0, v[136:137]
	v_lshl_add_u64 v[136:137], v[136:137], 0, v[0:1]
	v_lshl_add_u64 v[136:137], v[136:137], 0, v[134:135]
	v_mul_f32_e32 v0, v149, v174
	v_lshl_add_u64 v[136:137], v[136:137], 0, v[132:133]
	v_cvt_pk_bf16_f32 v138, v140, v141
	v_cvt_pk_bf16_f32 v139, v143, v175
	v_mul_f32_e32 v0, 0.15915494, v0
	global_store_dwordx2 v[136:137], v[138:139], off
	v_cos_f32_e32 v136, v0
	v_sin_f32_e32 v0, v0
	v_cndmask_b32_e64 v136, 1.0, v136, s[4:5]
	v_cndmask_b32_e64 v0, 0, v0, s[4:5]
	v_mul_f32_e32 v137, v2, v0
	v_fma_f32 v137, v66, v136, -v137
	v_mul_f32_e32 v136, v2, v136
	v_fmac_f32_e32 v136, v66, v0
	v_mul_f32_e32 v0, 0x3d800000, v136
	v_mul_f32_e32 v136, v149, v181
	v_mul_f32_e32 v136, 0.15915494, v136
	v_mul_f32_e32 v138, 0x3d800000, v137
	v_cos_f32_e32 v137, v136
	v_sin_f32_e32 v136, v136
	v_cndmask_b32_e64 v137, 1.0, v137, s[4:5]
	v_cndmask_b32_e64 v136, 0, v136, s[4:5]
	v_mul_f32_e32 v139, v3, v136
	v_fma_f32 v139, v67, v137, -v139
	v_mul_f32_e32 v137, v3, v137
	v_fmac_f32_e32 v137, v67, v136
	v_mul_f32_e32 v136, v149, v184
	v_mul_f32_e32 v136, 0.15915494, v136
	v_mul_f32_e32 v140, 0x3d800000, v137
	v_cos_f32_e32 v137, v136
	v_sin_f32_e32 v136, v136
	v_mul_f32_e32 v139, 0x3d800000, v139
	v_cvt_pk_bf16_f32 v138, v138, v139
	v_cndmask_b32_e64 v137, 1.0, v137, s[4:5]
	v_cndmask_b32_e64 v136, 0, v136, s[4:5]
	v_mul_f32_e32 v141, v4, v136
	v_fma_f32 v141, v68, v137, -v141
	v_mul_f32_e32 v137, v4, v137
	v_fmac_f32_e32 v137, v68, v136
	v_mul_f32_e32 v136, v149, v218
	v_mul_f32_e32 v136, 0.15915494, v136
	v_mul_f32_e32 v142, 0x3d800000, v137
	v_cos_f32_e32 v137, v136
	v_sin_f32_e32 v136, v136
	v_mul_f32_e32 v141, 0x3d800000, v141
	v_cndmask_b32_e64 v137, 1.0, v137, s[4:5]
	v_cndmask_b32_e64 v136, 0, v136, s[4:5]
	v_mul_f32_e32 v143, v5, v136
	v_fma_f32 v143, v69, v137, -v143
	v_mul_f32_e32 v137, v5, v137
	v_fmac_f32_e32 v137, v69, v136
	v_mul_f32_e32 v144, 0x3d800000, v137
	v_lshl_add_u64 v[136:137], v[168:169], 0, v[172:173]
	v_or_b32_e32 v136, v136, v215
	v_lshlrev_b64 v[136:137], 13, v[136:137]
	v_lshl_add_u64 v[136:137], v[130:131], 0, v[136:137]
	v_lshl_add_u64 v[136:137], v[136:137], 0, v[164:165]
	v_mul_f32_e32 v143, 0x3d800000, v143
	v_lshl_add_u64 v[136:137], v[136:137], 0, v[134:135]
	v_lshl_add_u64 v[136:137], v[136:137], 0, v[132:133]
	v_cvt_pk_bf16_f32 v139, v141, v143
	global_store_dwordx2 v[136:137], v[138:139], off
	v_lshl_add_u64 v[136:137], v[170:171], 0, v[172:173]
	v_or_b32_e32 v136, v136, v216
	v_lshlrev_b64 v[136:137], 13, v[136:137]
	v_lshl_add_u64 v[130:131], v[130:131], 0, v[136:137]
	v_lshl_add_u64 v[130:131], v[130:131], 0, v[164:165]
	v_lshl_add_u64 v[130:131], v[130:131], 0, v[134:135]
	v_lshl_add_u64 v[130:131], v[130:131], 0, v[132:133]
	v_cvt_pk_bf16_f32 v132, v0, v140
	v_cvt_pk_bf16_f32 v133, v142, v144
	global_store_dwordx2 v[130:131], v[132:133], off

.LBB0_831:
	s_and_b64 vcc, exec, s[2:3]
	s_cbranch_vccz .LBB0_904
	s_cmp_gt_i32 s21, 2
	s_mov_b64 s[2:3], -1
	s_cbranch_scc0 .LBB0_902
	s_add_i32 s2, s65, -4
	s_cmp_gt_u32 s2, 7
	s_mov_b64 s[2:3], -1
	s_cbranch_scc0 .LBB0_899
	s_cmp_gt_i32 s65, 11
	s_cbranch_scc1 .Lretk_fast
	s_branch .Lretq_fast
	v_readlane_b32 s2, v253, 35
	s_cmp_lt_i32 s65, 12
	v_and_b32_e32 v207, 63, v163
	v_mov_b32_e32 v0, s2
	s_cselect_b64 s[2:3], -1, 0
	s_cmp_gt_i32 s65, 11
	s_cselect_b64 s[6:7], -1, 0
	s_and_b32 s4, s31, 32
	v_add_u32_e32 v164, s4, v148
	v_cvt_f32_i32_e32 v132, v164
	v_readlane_b32 s4, v253, 42
	s_and_b32 s68, s65, 3
	s_cmp_lt_i32 s30, 2
	v_mov_b32_e32 v133, s4
	ds_read_b64 v[130:131], v0
	ds_read_b64 v[138:139], v133
	v_or_b32_e32 v133, 1, v164
	v_cvt_f32_i32_e32 v133, v133
	v_mul_f32_e32 v0, 0xbe549a78, v132
	s_mov_b32 s4, 0xc2fc0000
	v_cmp_gt_f32_e32 vcc, s4, v0
	v_mul_f32_e32 v134, 0xbe549a78, v133
	v_bfe_u32 v206, v206, 4, 3
	v_cndmask_b32_e32 v0, 0, v201, vcc
	v_fmac_f32_e32 v0, 0xbe549a78, v132
	v_exp_f32_e32 v0, v0
	v_cndmask_b32_e32 v132, 0, v200, vcc
	v_cmp_gt_f32_e32 vcc, s4, v134
	v_cmp_gt_i32_e64 s[8:9], s86, v160
	v_ldexp_f32 v173, v0, v132
	v_cndmask_b32_e32 v134, 0, v201, vcc
	v_fmac_f32_e32 v134, 0xbe549a78, v133
	v_exp_f32_e32 v133, v134
	v_or_b32_e32 v134, 2, v164
	v_cvt_f32_i32_e32 v134, v134
	v_or_b32_e32 v132, 3, v164
	v_cvt_f32_i32_e32 v132, v132
	v_cndmask_b32_e32 v0, 0, v200, vcc
	v_ldexp_f32 v172, v133, v0
	v_mul_f32_e32 v0, 0xbe549a78, v134
	v_cmp_gt_f32_e32 vcc, s4, v0
	v_mul_f32_e32 v133, 0xbe549a78, v132
	v_cmp_gt_f32_e64 s[4:5], s4, v133
	v_cndmask_b32_e32 v0, 0, v201, vcc
	v_fmac_f32_e32 v0, 0xbe549a78, v134
	v_cndmask_b32_e64 v133, 0, v201, s[4:5]
	v_exp_f32_e32 v0, v0
	v_fmac_f32_e32 v133, 0xbe549a78, v132
	v_exp_f32_e32 v132, v133
	v_cndmask_b32_e32 v133, 0, v200, vcc
	v_ldexp_f32 v171, v0, v133
	v_cndmask_b32_e64 v0, 0, v200, s[4:5]
	v_ldexp_f32 v170, v132, v0
	v_mov_b32_e32 v0, 0x3d800000
	v_cndmask_b32_e64 v169, 1.0, v0, s[6:7]
	v_ashrrev_i32_e32 v0, 6, v160
	s_cselect_b64 s[4:5], -1, 0
	v_cndmask_b32_e64 v0, v207, v0, s[4:5]
	v_cvt_f32_i32_e32 v165, v0
	v_ashrrev_i32_e32 v132, 7, v160
	v_ashrrev_i32_e32 v133, 31, v132
	s_lshl_b32 s67, s68, 3
	v_mul_f32_e32 v0, v173, v165
	v_mul_f32_e32 v0, 0.15915494, v0
	v_sin_f32_e32 v134, v0
	v_lshlrev_b64 v[132:133], 5, v[132:133]
	v_or3_b32 v132, v132, v206, s67
	v_lshlrev_b64 v[132:133], 13, v[132:133]
	v_cos_f32_e32 v0, v0
	s_waitcnt lgkmcnt(0)
	v_lshl_add_u64 v[144:145], v[130:131], 0, v[132:133]
	v_cndmask_b32_e64 v132, 0, v134, s[8:9]
	v_mul_f32_e32 v134, v172, v165
	v_mul_f32_e32 v134, 0.15915494, v134
	v_sin_f32_e32 v135, v134
	v_cndmask_b32_e64 v133, 1.0, v0, s[8:9]
	v_mul_f32_e32 v0, v122, v132
	v_fma_f32 v0, v126, v133, -v0
	v_mul_f32_e32 v133, v122, v133
	v_cos_f32_e32 v134, v134
	v_fmac_f32_e32 v133, v126, v132
	v_cndmask_b32_e64 v132, 0, v135, s[8:9]
	v_mul_f32_e32 v135, v171, v165
	v_mul_f32_e32 v135, 0.15915494, v135
	v_sin_f32_e32 v136, v135
	v_cos_f32_e32 v137, v135
	v_mul_f32_e32 v140, v169, v133
	v_cndmask_b32_e64 v134, 1.0, v134, s[8:9]
	v_mul_f32_e32 v133, v123, v132
	v_fma_f32 v133, v127, v134, -v133
	v_mul_f32_e32 v134, v123, v134
	v_fmac_f32_e32 v134, v127, v132
	v_cndmask_b32_e64 v132, 0, v136, s[8:9]
	v_cndmask_b32_e64 v136, 1.0, v137, s[8:9]
	v_mul_f32_e32 v137, v170, v165
	v_mul_f32_e32 v137, 0.15915494, v137
	v_sin_f32_e32 v142, v137
	v_cos_f32_e32 v137, v137
	v_mul_f32_e32 v135, v169, v134
	v_mul_f32_e32 v134, v124, v132
	v_fma_f32 v134, v128, v136, -v134
	v_mul_f32_e32 v136, v124, v136
	v_fmac_f32_e32 v136, v128, v132
	v_cndmask_b32_e64 v132, 0, v142, s[8:9]
	v_and_b32_e32 v141, 4, v148
	v_mul_f32_e32 v148, v169, v136
	v_cndmask_b32_e64 v136, 1.0, v137, s[8:9]
	v_mul_f32_e32 v137, v125, v132
	v_fma_f32 v137, v129, v136, -v137
	v_mul_f32_e32 v136, v125, v136
	v_fmac_f32_e32 v136, v129, v132
	v_and_b32_e32 v168, 15, v163
	v_mul_f32_e32 v0, v169, v0
	v_mul_f32_e32 v133, v169, v133
	v_mul_f32_e32 v134, v169, v134
	v_mul_f32_e32 v143, v169, v137
	v_mul_f32_e32 v149, v169, v136
	v_ashrrev_i32_e32 v136, 5, v146
	v_lshlrev_b32_e32 v132, 3, v147
	v_add_u32_e32 v147, 0x80, v146
	s_mov_b64 s[30:31], -1
	s_and_b64 vcc, exec, s[2:3]
	v_ashrrev_i32_e32 v137, 31, v136
	v_and_or_b32 v174, v132, 48, v168
	v_lshlrev_b32_e32 v132, 1, v141
	v_cvt_pk_bf16_f32 v142, v0, v133
	v_cvt_pk_bf16_f32 v143, v134, v143
	v_ashrrev_i32_e32 v134, 5, v147
	v_cvt_pk_bf16_f32 v140, v140, v135
	v_cvt_pk_bf16_f32 v141, v148, v149
	s_cbranch_vccz .LBB0_836
	v_lshlrev_b64 v[148:149], 10, v[136:137]
	v_lshl_add_u64 v[148:149], v[144:145], 0, v[148:149]
	v_lshlrev_b32_e32 v0, 4, v174
	v_lshl_add_u64 v[148:149], v[148:149], 0, v[0:1]
	v_mov_b32_e32 v133, v1
	v_lshl_add_u64 v[148:149], v[148:149], 0, v[132:133]
	v_ashrrev_i32_e32 v135, 31, v134
	global_store_dwordx2 v[148:149], v[142:143], off
	v_lshlrev_b64 v[148:149], 10, v[134:135]
	v_lshl_add_u64 v[148:149], v[144:145], 0, v[148:149]
	v_lshl_add_u64 v[148:149], v[148:149], 0, v[0:1]
	v_lshl_add_u64 v[148:149], v[148:149], 0, v[132:133]
	global_store_dwordx2 v[148:149], v[140:141], off
	s_mov_b64 s[30:31], 0

.Lrettk_fast:
	v_mov_b32_e32 v148, v162
	v_cvt_f32_i32_e32 v160, v202
	v_add_u32_e32 v161, 16, v202
	v_cvt_f32_i32_e32 v161, v161
	v_add_u32_e32 v162, 32, v202
	v_cvt_f32_i32_e32 v162, v162
	v_add_u32_e32 v163, 48, v202
	v_cvt_f32_i32_e32 v163, v163
	v_mul_f32_e32 v160, 0xbe549a78, v160
	v_mul_f32_e32 v161, 0xbe549a78, v161
	v_mul_f32_e32 v162, 0xbe549a78, v162
	v_mul_f32_e32 v163, 0xbe549a78, v163
	v_exp_f32_e32 v160, v160
	v_exp_f32_e32 v161, v161
	v_exp_f32_e32 v162, v162
	v_exp_f32_e32 v163, v163
	v_mov_b32_e32 v138, 0x3e22f983
	v_mov_b32_e32 v139, 0x3e22f983
	v_mov_b32_e32 v140, 0x3d800000
	v_mov_b32_e32 v141, 0x3d800000
	s_cmp_eq_u32 s68, 0
	s_cselect_b32 s6, 6, 0
	s_cselect_b32 s7, -1, 63
	s_cmp_lt_i32 s65, 64
	s_cselect_b32 s8, 1.0, 0
	v_readlane_b32 s4, v253, 35
	v_mov_b32_e32 v176, s4
	ds_read_b64 v[174:175], v176
	s_lshl_b32 s4, s65, 3
	s_add_i32 s4, s4, s66
	s_lshl_b32 s4, s4, 3
	s_lshl_b32 s5, s68, 1
	s_add_i32 s4, s4, s5
	s_lshl_b32 s4, s4, 3
	s_lshl_b32 s5, s30, 1
	s_add_i32 s4, s4, s5
	s_lshl_b32 s4, s4, 10
	s_mov_b32 s5, 0
	v_and_b32_e32 v176, 1, v203
	v_lshrrev_b32_e32 v177, 1, v203
	v_lshl_add_u32 v177, v177, 5, v202
	v_lshlrev_b32_e32 v177, 3, v177
	v_lshl_add_u32 v176, v176, 9, v177
	v_lshlrev_b32_e32 v176, 1, v176
	v_mov_b32_e32 v177, 0
	s_waitcnt lgkmcnt(0)
	v_lshl_add_u64 v[172:173], v[174:175], 0, s[4:5]
	v_lshl_add_u64 v[172:173], v[172:173], 0, v[176:177]
	s_mov_b64 s[4:5], 0x8000
	v_lshl_add_u64 v[174:175], v[172:173], 0, s[4:5]
	s_mov_b64 s[2:3], 0x2000
	s_mov_b64 s[28:29], 0x3e000
	v_mov_b32_e32 v130, v148
	v_lshrrev_b32_e32 v130, s6, v130
	v_and_b32_e32 v130, s7, v130
	v_cvt_f32_i32_e32 v130, v130
	v_mul_f32_e32 v130, s8, v130
	v_add_u32_e32 v131, 1, v148
	v_lshrrev_b32_e32 v131, s6, v131
	v_and_b32_e32 v131, s7, v131
	v_cvt_f32_i32_e32 v131, v131
	v_mul_f32_e32 v131, s8, v131
	v_add_u32_e32 v132, 2, v148
	v_lshrrev_b32_e32 v132, s6, v132
	v_and_b32_e32 v132, s7, v132
	v_cvt_f32_i32_e32 v132, v132
	v_mul_f32_e32 v132, s8, v132
	v_add_u32_e32 v133, 3, v148
	v_lshrrev_b32_e32 v133, s6, v133
	v_and_b32_e32 v133, s7, v133
	v_cvt_f32_i32_e32 v133, v133
	v_mul_f32_e32 v133, s8, v133
	v_add_u32_e32 v134, 16, v148
	v_lshrrev_b32_e32 v134, s6, v134
	v_and_b32_e32 v134, s7, v134
	v_cvt_f32_i32_e32 v134, v134
	v_mul_f32_e32 v134, s8, v134
	v_add_u32_e32 v135, 17, v148
	v_lshrrev_b32_e32 v135, s6, v135
	v_and_b32_e32 v135, s7, v135
	v_cvt_f32_i32_e32 v135, v135
	v_mul_f32_e32 v135, s8, v135
	v_add_u32_e32 v136, 18, v148
	v_lshrrev_b32_e32 v136, s6, v136
	v_and_b32_e32 v136, s7, v136
	v_cvt_f32_i32_e32 v136, v136
	v_mul_f32_e32 v136, s8, v136
	v_add_u32_e32 v137, 19, v148
	v_lshrrev_b32_e32 v137, s6, v137
	v_and_b32_e32 v137, s7, v137
	v_cvt_f32_i32_e32 v137, v137
	v_mul_f32_e32 v137, s8, v137
	v_mov_b32_e32 v142, v160
	v_pk_mul_f32 v[206:207], v[130:131], v[142:143] op_sel_hi:[1,0]
	v_pk_mul_f32 v[208:209], v[132:133], v[142:143] op_sel_hi:[1,0]
	v_pk_mul_f32 v[210:211], v[134:135], v[142:143] op_sel_hi:[1,0]
	v_pk_mul_f32 v[212:213], v[136:137], v[142:143] op_sel_hi:[1,0]
	v_pk_mul_f32 v[206:207], v[206:207], v[138:139]
	v_sin_f32_e32 v214, v206
	v_pk_mul_f32 v[208:209], v[208:209], v[138:139]
	v_sin_f32_e32 v215, v207
	v_pk_mul_f32 v[210:211], v[210:211], v[138:139]
	v_sin_f32_e32 v216, v208
	v_pk_mul_f32 v[212:213], v[212:213], v[138:139]
	v_sin_f32_e32 v217, v209
	v_pk_mul_f32 v[214:215], v[214:215], v[140:141]
	v_sin_f32_e32 v218, v210
	v_pk_mul_f32 v[216:217], v[216:217], v[140:141]
	v_sin_f32_e32 v219, v211
	v_pk_mul_f32 v[144:145], v[62:63], v[214:215]
	v_sin_f32_e32 v220, v212
	v_pk_mul_f32 v[218:219], v[218:219], v[140:141]
	v_sin_f32_e32 v221, v213
	v_pk_mul_f32 v[146:147], v[64:65], v[216:217]
	v_cos_f32_e32 v206, v206
	v_pk_mul_f32 v[220:221], v[220:221], v[140:141]
	v_cos_f32_e32 v207, v207
	v_mov_b32_e32 v142, v161
	v_cos_f32_e32 v208, v208
	v_pk_mul_f32 v[206:207], v[206:207], v[140:141]
	v_cos_f32_e32 v209, v209
	v_pk_fma_f32 v[222:223], v[126:127], v[206:207], v[144:145] neg_lo:[0,0,1] neg_hi:[0,0,1]
	v_cos_f32_e32 v210, v210
	v_pk_mul_f32 v[208:209], v[208:209], v[140:141]
	v_cos_f32_e32 v211, v211
	v_pk_mul_f32 v[144:145], v[126:127], v[214:215]
	v_cos_f32_e32 v212, v212
	v_pk_mul_f32 v[210:211], v[210:211], v[140:141]
	v_cos_f32_e32 v213, v213
	v_pk_fma_f32 v[164:165], v[62:63], v[206:207], v[144:145]
	v_pk_mul_f32 v[212:213], v[212:213], v[140:141]
	v_pk_fma_f32 v[224:225], v[128:129], v[208:209], v[146:147] neg_lo:[0,0,1] neg_hi:[0,0,1]
	v_pk_mul_f32 v[146:147], v[128:129], v[216:217]
	v_pk_fma_f32 v[166:167], v[64:65], v[208:209], v[146:147]
	v_pk_mul_f32 v[144:145], v[54:55], v[218:219]
	v_pk_fma_f32 v[226:227], v[118:119], v[210:211], v[144:145] neg_lo:[0,0,1] neg_hi:[0,0,1]
	v_pk_mul_f32 v[144:145], v[118:119], v[218:219]
	v_pk_fma_f32 v[168:169], v[54:55], v[210:211], v[144:145]
	v_pk_mul_f32 v[146:147], v[56:57], v[220:221]
	v_pk_fma_f32 v[228:229], v[120:121], v[212:213], v[146:147] neg_lo:[0,0,1] neg_hi:[0,0,1]
	v_pk_mul_f32 v[146:147], v[120:121], v[220:221]
	v_pk_fma_f32 v[170:171], v[56:57], v[212:213], v[146:147]
	v_cvt_pk_bf16_f32 v222, v222, v223
	v_cvt_pk_bf16_f32 v223, v224, v225
	v_cvt_pk_bf16_f32 v224, v226, v227
	v_cvt_pk_bf16_f32 v225, v228, v229
	v_cvt_pk_bf16_f32 v164, v164, v165
	v_cvt_pk_bf16_f32 v165, v166, v167
	v_cvt_pk_bf16_f32 v166, v168, v169
	v_cvt_pk_bf16_f32 v167, v170, v171
	v_permlane16_swap_b32_e32 v222, v224
	v_permlane16_swap_b32_e32 v223, v225
	v_permlane16_swap_b32_e32 v164, v166
	v_permlane16_swap_b32_e32 v165, v167
	global_store_dwordx4 v[172:173], v[222:225], off
	global_store_dwordx4 v[174:175], v[164:167], off
	v_pk_mul_f32 v[236:237], v[130:131], v[142:143] op_sel_hi:[1,0]
	v_pk_mul_f32 v[238:239], v[132:133], v[142:143] op_sel_hi:[1,0]
	v_pk_mul_f32 v[240:241], v[134:135], v[142:143] op_sel_hi:[1,0]
	v_pk_mul_f32 v[242:243], v[136:137], v[142:143] op_sel_hi:[1,0]
	v_pk_mul_f32 v[236:237], v[236:237], v[138:139]
	v_sin_f32_e32 v244, v236
	v_pk_mul_f32 v[238:239], v[238:239], v[138:139]
	v_sin_f32_e32 v245, v237
	v_pk_mul_f32 v[240:241], v[240:241], v[138:139]
	v_sin_f32_e32 v246, v238
	v_pk_mul_f32 v[242:243], v[242:243], v[138:139]
	v_sin_f32_e32 v247, v239
	v_pk_mul_f32 v[244:245], v[244:245], v[140:141]
	v_sin_f32_e32 v248, v240
	v_pk_mul_f32 v[246:247], v[246:247], v[140:141]
	v_sin_f32_e32 v249, v241
	v_pk_mul_f32 v[144:145], v[46:47], v[244:245]
	v_sin_f32_e32 v250, v242
	v_pk_mul_f32 v[248:249], v[248:249], v[140:141]
	v_sin_f32_e32 v251, v243
	v_pk_mul_f32 v[146:147], v[48:49], v[246:247]
	v_cos_f32_e32 v236, v236
	v_pk_mul_f32 v[250:251], v[250:251], v[140:141]
	v_cos_f32_e32 v237, v237
	v_mov_b32_e32 v142, v162
	v_cos_f32_e32 v238, v238
	v_pk_mul_f32 v[236:237], v[236:237], v[140:141]
	v_cos_f32_e32 v239, v239
	v_pk_fma_f32 v[222:223], v[110:111], v[236:237], v[144:145] neg_lo:[0,0,1] neg_hi:[0,0,1]
	v_cos_f32_e32 v240, v240
	v_pk_mul_f32 v[238:239], v[238:239], v[140:141]
	v_cos_f32_e32 v241, v241
	v_pk_mul_f32 v[144:145], v[110:111], v[244:245]
	v_cos_f32_e32 v242, v242
	v_pk_mul_f32 v[240:241], v[240:241], v[140:141]
	v_cos_f32_e32 v243, v243
	v_pk_fma_f32 v[164:165], v[46:47], v[236:237], v[144:145]
	v_pk_mul_f32 v[242:243], v[242:243], v[140:141]
	v_pk_fma_f32 v[224:225], v[112:113], v[238:239], v[146:147] neg_lo:[0,0,1] neg_hi:[0,0,1]
	v_pk_mul_f32 v[146:147], v[112:113], v[246:247]
	v_pk_fma_f32 v[166:167], v[48:49], v[238:239], v[146:147]
	v_pk_mul_f32 v[144:145], v[38:39], v[248:249]
	v_pk_fma_f32 v[226:227], v[102:103], v[240:241], v[144:145] neg_lo:[0,0,1] neg_hi:[0,0,1]
	v_pk_mul_f32 v[144:145], v[102:103], v[248:249]
	v_pk_fma_f32 v[168:169], v[38:39], v[240:241], v[144:145]
	v_pk_mul_f32 v[146:147], v[40:41], v[250:251]
	v_pk_fma_f32 v[228:229], v[104:105], v[242:243], v[146:147] neg_lo:[0,0,1] neg_hi:[0,0,1]
	v_pk_mul_f32 v[146:147], v[104:105], v[250:251]
	v_pk_fma_f32 v[170:171], v[40:41], v[242:243], v[146:147]
	v_cvt_pk_bf16_f32 v222, v222, v223
	v_cvt_pk_bf16_f32 v223, v224, v225
	v_cvt_pk_bf16_f32 v224, v226, v227
	v_cvt_pk_bf16_f32 v225, v228, v229
	v_cvt_pk_bf16_f32 v164, v164, v165
	v_cvt_pk_bf16_f32 v165, v166, v167
	v_cvt_pk_bf16_f32 v166, v168, v169
	v_cvt_pk_bf16_f32 v167, v170, v171
	v_permlane16_swap_b32_e32 v222, v224
	v_permlane16_swap_b32_e32 v223, v225
	v_permlane16_swap_b32_e32 v164, v166
	v_permlane16_swap_b32_e32 v165, v167
	global_store_dwordx4 v[172:173], v[222:225], off offset:256
	global_store_dwordx4 v[174:175], v[164:167], off offset:256
	v_pk_mul_f32 v[206:207], v[130:131], v[142:143] op_sel_hi:[1,0]
	v_lshl_add_u64 v[172:173], v[172:173], 0, s[2:3]
	v_lshl_add_u64 v[174:175], v[174:175], 0, s[2:3]
	v_pk_mul_f32 v[208:209], v[132:133], v[142:143] op_sel_hi:[1,0]
	v_pk_mul_f32 v[210:211], v[134:135], v[142:143] op_sel_hi:[1,0]
	v_pk_mul_f32 v[212:213], v[136:137], v[142:143] op_sel_hi:[1,0]
	v_pk_mul_f32 v[206:207], v[206:207], v[138:139]
	v_sin_f32_e32 v214, v206
	v_pk_mul_f32 v[208:209], v[208:209], v[138:139]
	v_sin_f32_e32 v215, v207
	v_pk_mul_f32 v[210:211], v[210:211], v[138:139]
	v_sin_f32_e32 v216, v208
	v_pk_mul_f32 v[212:213], v[212:213], v[138:139]
	v_sin_f32_e32 v217, v209
	v_pk_mul_f32 v[214:215], v[214:215], v[140:141]
	v_sin_f32_e32 v218, v210
	v_pk_mul_f32 v[216:217], v[216:217], v[140:141]
	v_sin_f32_e32 v219, v211
	v_pk_mul_f32 v[144:145], v[30:31], v[214:215]
	v_sin_f32_e32 v220, v212
	v_pk_mul_f32 v[218:219], v[218:219], v[140:141]
	v_sin_f32_e32 v221, v213
	v_pk_mul_f32 v[146:147], v[32:33], v[216:217]
	v_cos_f32_e32 v206, v206
	v_pk_mul_f32 v[220:221], v[220:221], v[140:141]
	v_cos_f32_e32 v207, v207
	v_mov_b32_e32 v142, v163
	v_cos_f32_e32 v208, v208
	v_pk_mul_f32 v[206:207], v[206:207], v[140:141]
	v_cos_f32_e32 v209, v209
	v_pk_fma_f32 v[222:223], v[94:95], v[206:207], v[144:145] neg_lo:[0,0,1] neg_hi:[0,0,1]
	v_cos_f32_e32 v210, v210
	v_pk_mul_f32 v[208:209], v[208:209], v[140:141]
	v_cos_f32_e32 v211, v211
	v_pk_mul_f32 v[144:145], v[94:95], v[214:215]
	v_cos_f32_e32 v212, v212
	v_pk_mul_f32 v[210:211], v[210:211], v[140:141]
	v_cos_f32_e32 v213, v213
	v_pk_fma_f32 v[164:165], v[30:31], v[206:207], v[144:145]
	v_pk_mul_f32 v[212:213], v[212:213], v[140:141]
	v_pk_fma_f32 v[224:225], v[96:97], v[208:209], v[146:147] neg_lo:[0,0,1] neg_hi:[0,0,1]
	v_pk_mul_f32 v[146:147], v[96:97], v[216:217]
	v_pk_fma_f32 v[166:167], v[32:33], v[208:209], v[146:147]
	v_pk_mul_f32 v[144:145], v[22:23], v[218:219]
	v_pk_fma_f32 v[226:227], v[86:87], v[210:211], v[144:145] neg_lo:[0,0,1] neg_hi:[0,0,1]
	v_pk_mul_f32 v[144:145], v[86:87], v[218:219]
	v_pk_fma_f32 v[168:169], v[22:23], v[210:211], v[144:145]
	v_pk_mul_f32 v[146:147], v[24:25], v[220:221]
	v_pk_fma_f32 v[228:229], v[88:89], v[212:213], v[146:147] neg_lo:[0,0,1] neg_hi:[0,0,1]
	v_pk_mul_f32 v[146:147], v[88:89], v[220:221]
	v_pk_fma_f32 v[170:171], v[24:25], v[212:213], v[146:147]
	v_cvt_pk_bf16_f32 v222, v222, v223
	v_cvt_pk_bf16_f32 v223, v224, v225
	v_cvt_pk_bf16_f32 v224, v226, v227
	v_cvt_pk_bf16_f32 v225, v228, v229
	v_cvt_pk_bf16_f32 v164, v164, v165
	v_cvt_pk_bf16_f32 v165, v166, v167
	v_cvt_pk_bf16_f32 v166, v168, v169
	v_cvt_pk_bf16_f32 v167, v170, v171
	v_permlane16_swap_b32_e32 v222, v224
	v_permlane16_swap_b32_e32 v223, v225
	v_permlane16_swap_b32_e32 v164, v166
	v_permlane16_swap_b32_e32 v165, v167
	global_store_dwordx4 v[172:173], v[222:225], off
	global_store_dwordx4 v[174:175], v[164:167], off
	v_pk_mul_f32 v[236:237], v[130:131], v[142:143] op_sel_hi:[1,0]
	v_pk_mul_f32 v[238:239], v[132:133], v[142:143] op_sel_hi:[1,0]
	v_pk_mul_f32 v[240:241], v[134:135], v[142:143] op_sel_hi:[1,0]
	v_pk_mul_f32 v[242:243], v[136:137], v[142:143] op_sel_hi:[1,0]
	v_pk_mul_f32 v[236:237], v[236:237], v[138:139]
	v_sin_f32_e32 v244, v236
	v_pk_mul_f32 v[238:239], v[238:239], v[138:139]
	v_sin_f32_e32 v245, v237
	v_pk_mul_f32 v[240:241], v[240:241], v[138:139]
	v_sin_f32_e32 v246, v238
	v_pk_mul_f32 v[242:243], v[242:243], v[138:139]
	v_sin_f32_e32 v247, v239
	v_pk_mul_f32 v[244:245], v[244:245], v[140:141]
	v_sin_f32_e32 v248, v240
	v_pk_mul_f32 v[246:247], v[246:247], v[140:141]
	v_sin_f32_e32 v249, v241
	v_pk_mul_f32 v[144:145], v[14:15], v[244:245]
	v_sin_f32_e32 v250, v242
	v_pk_mul_f32 v[248:249], v[248:249], v[140:141]
	v_sin_f32_e32 v251, v243
	v_pk_mul_f32 v[146:147], v[16:17], v[246:247]
	v_cos_f32_e32 v236, v236
	v_pk_mul_f32 v[250:251], v[250:251], v[140:141]
	v_cos_f32_e32 v237, v237
	v_add_u32_e32 v130, 128, v148
	v_cos_f32_e32 v238, v238
	v_pk_mul_f32 v[236:237], v[236:237], v[140:141]
	v_cos_f32_e32 v239, v239
	v_pk_fma_f32 v[222:223], v[78:79], v[236:237], v[144:145] neg_lo:[0,0,1] neg_hi:[0,0,1]
	v_cos_f32_e32 v240, v240
	v_pk_mul_f32 v[238:239], v[238:239], v[140:141]
	v_cos_f32_e32 v241, v241
	v_pk_mul_f32 v[144:145], v[78:79], v[244:245]
	v_cos_f32_e32 v242, v242
	v_pk_mul_f32 v[240:241], v[240:241], v[140:141]
	v_cos_f32_e32 v243, v243
	v_pk_fma_f32 v[164:165], v[14:15], v[236:237], v[144:145]
	v_pk_mul_f32 v[242:243], v[242:243], v[140:141]
	v_pk_fma_f32 v[224:225], v[80:81], v[238:239], v[146:147] neg_lo:[0,0,1] neg_hi:[0,0,1]
	v_pk_mul_f32 v[146:147], v[80:81], v[246:247]
	v_pk_fma_f32 v[166:167], v[16:17], v[238:239], v[146:147]
	v_pk_mul_f32 v[144:145], v[6:7], v[248:249]
	v_pk_fma_f32 v[226:227], v[70:71], v[240:241], v[144:145] neg_lo:[0,0,1] neg_hi:[0,0,1]
	v_pk_mul_f32 v[144:145], v[70:71], v[248:249]
	v_pk_fma_f32 v[168:169], v[6:7], v[240:241], v[144:145]
	v_pk_mul_f32 v[146:147], v[8:9], v[250:251]
	v_pk_fma_f32 v[228:229], v[72:73], v[242:243], v[146:147] neg_lo:[0,0,1] neg_hi:[0,0,1]
	v_pk_mul_f32 v[146:147], v[72:73], v[250:251]
	v_pk_fma_f32 v[170:171], v[8:9], v[242:243], v[146:147]
	v_cvt_pk_bf16_f32 v222, v222, v223
	v_cvt_pk_bf16_f32 v223, v224, v225
	v_cvt_pk_bf16_f32 v224, v226, v227
	v_cvt_pk_bf16_f32 v225, v228, v229
	v_cvt_pk_bf16_f32 v164, v164, v165
	v_cvt_pk_bf16_f32 v165, v166, v167
	v_cvt_pk_bf16_f32 v166, v168, v169
	v_cvt_pk_bf16_f32 v167, v170, v171
	v_permlane16_swap_b32_e32 v222, v224
	v_permlane16_swap_b32_e32 v223, v225
	v_permlane16_swap_b32_e32 v164, v166
	v_permlane16_swap_b32_e32 v165, v167
	global_store_dwordx4 v[172:173], v[222:225], off offset:256
	global_store_dwordx4 v[174:175], v[164:167], off offset:256
	v_lshrrev_b32_e32 v130, s6, v130
	v_lshl_add_u64 v[172:173], v[172:173], 0, s[28:29]
	v_lshl_add_u64 v[174:175], v[174:175], 0, s[28:29]
	v_and_b32_e32 v130, s7, v130
	v_cvt_f32_i32_e32 v130, v130
	v_mul_f32_e32 v130, s8, v130
	v_add_u32_e32 v131, 129, v148
	v_lshrrev_b32_e32 v131, s6, v131
	v_and_b32_e32 v131, s7, v131
	v_cvt_f32_i32_e32 v131, v131
	v_mul_f32_e32 v131, s8, v131
	v_add_u32_e32 v132, 130, v148
	v_lshrrev_b32_e32 v132, s6, v132
	v_and_b32_e32 v132, s7, v132
	v_cvt_f32_i32_e32 v132, v132
	v_mul_f32_e32 v132, s8, v132
	v_add_u32_e32 v133, 131, v148
	v_lshrrev_b32_e32 v133, s6, v133
	v_and_b32_e32 v133, s7, v133
	v_cvt_f32_i32_e32 v133, v133
	v_mul_f32_e32 v133, s8, v133
	v_add_u32_e32 v134, 144, v148
	v_lshrrev_b32_e32 v134, s6, v134
	v_and_b32_e32 v134, s7, v134
	v_cvt_f32_i32_e32 v134, v134
	v_mul_f32_e32 v134, s8, v134
	v_add_u32_e32 v135, 145, v148
	v_lshrrev_b32_e32 v135, s6, v135
	v_and_b32_e32 v135, s7, v135
	v_cvt_f32_i32_e32 v135, v135
	v_mul_f32_e32 v135, s8, v135
	v_add_u32_e32 v136, 146, v148
	v_lshrrev_b32_e32 v136, s6, v136
	v_and_b32_e32 v136, s7, v136
	v_cvt_f32_i32_e32 v136, v136
	v_mul_f32_e32 v136, s8, v136
	v_add_u32_e32 v137, 147, v148
	v_lshrrev_b32_e32 v137, s6, v137
	v_and_b32_e32 v137, s7, v137
	v_cvt_f32_i32_e32 v137, v137
	v_mul_f32_e32 v137, s8, v137
	v_mov_b32_e32 v142, v160
	v_pk_mul_f32 v[206:207], v[130:131], v[142:143] op_sel_hi:[1,0]
	v_pk_mul_f32 v[208:209], v[132:133], v[142:143] op_sel_hi:[1,0]
	v_pk_mul_f32 v[210:211], v[134:135], v[142:143] op_sel_hi:[1,0]
	v_pk_mul_f32 v[212:213], v[136:137], v[142:143] op_sel_hi:[1,0]
	v_pk_mul_f32 v[206:207], v[206:207], v[138:139]
	v_sin_f32_e32 v214, v206
	v_pk_mul_f32 v[208:209], v[208:209], v[138:139]
	v_sin_f32_e32 v215, v207
	v_pk_mul_f32 v[210:211], v[210:211], v[138:139]
	v_sin_f32_e32 v216, v208
	v_pk_mul_f32 v[212:213], v[212:213], v[138:139]
	v_sin_f32_e32 v217, v209
	v_pk_mul_f32 v[214:215], v[214:215], v[140:141]
	v_sin_f32_e32 v218, v210
	v_pk_mul_f32 v[216:217], v[216:217], v[140:141]
	v_sin_f32_e32 v219, v211
	v_pk_mul_f32 v[144:145], v[58:59], v[214:215]
	v_sin_f32_e32 v220, v212
	v_pk_mul_f32 v[218:219], v[218:219], v[140:141]
	v_sin_f32_e32 v221, v213
	v_pk_mul_f32 v[146:147], v[60:61], v[216:217]
	v_cos_f32_e32 v206, v206
	v_pk_mul_f32 v[220:221], v[220:221], v[140:141]
	v_cos_f32_e32 v207, v207
	v_mov_b32_e32 v142, v161
	v_cos_f32_e32 v208, v208
	v_pk_mul_f32 v[206:207], v[206:207], v[140:141]
	v_cos_f32_e32 v209, v209
	v_pk_fma_f32 v[222:223], v[122:123], v[206:207], v[144:145] neg_lo:[0,0,1] neg_hi:[0,0,1]
	v_cos_f32_e32 v210, v210
	v_pk_mul_f32 v[208:209], v[208:209], v[140:141]
	v_cos_f32_e32 v211, v211
	v_pk_mul_f32 v[144:145], v[122:123], v[214:215]
	v_cos_f32_e32 v212, v212
	v_pk_mul_f32 v[210:211], v[210:211], v[140:141]
	v_cos_f32_e32 v213, v213
	v_pk_fma_f32 v[164:165], v[58:59], v[206:207], v[144:145]
	v_pk_mul_f32 v[212:213], v[212:213], v[140:141]
	v_pk_fma_f32 v[224:225], v[124:125], v[208:209], v[146:147] neg_lo:[0,0,1] neg_hi:[0,0,1]
	v_pk_mul_f32 v[146:147], v[124:125], v[216:217]
	v_pk_fma_f32 v[166:167], v[60:61], v[208:209], v[146:147]
	v_pk_mul_f32 v[144:145], v[50:51], v[218:219]
	v_pk_fma_f32 v[226:227], v[114:115], v[210:211], v[144:145] neg_lo:[0,0,1] neg_hi:[0,0,1]
	v_pk_mul_f32 v[144:145], v[114:115], v[218:219]
	v_pk_fma_f32 v[168:169], v[50:51], v[210:211], v[144:145]
	v_pk_mul_f32 v[146:147], v[52:53], v[220:221]
	v_pk_fma_f32 v[228:229], v[116:117], v[212:213], v[146:147] neg_lo:[0,0,1] neg_hi:[0,0,1]
	v_pk_mul_f32 v[146:147], v[116:117], v[220:221]
	v_pk_fma_f32 v[170:171], v[52:53], v[212:213], v[146:147]
	v_cvt_pk_bf16_f32 v222, v222, v223
	v_cvt_pk_bf16_f32 v223, v224, v225
	v_cvt_pk_bf16_f32 v224, v226, v227
	v_cvt_pk_bf16_f32 v225, v228, v229
	v_cvt_pk_bf16_f32 v164, v164, v165
	v_cvt_pk_bf16_f32 v165, v166, v167
	v_cvt_pk_bf16_f32 v166, v168, v169
	v_cvt_pk_bf16_f32 v167, v170, v171
	v_permlane16_swap_b32_e32 v222, v224
	v_permlane16_swap_b32_e32 v223, v225
	v_permlane16_swap_b32_e32 v164, v166
	v_permlane16_swap_b32_e32 v165, v167
	global_store_dwordx4 v[172:173], v[222:225], off
	global_store_dwordx4 v[174:175], v[164:167], off
	v_pk_mul_f32 v[236:237], v[130:131], v[142:143] op_sel_hi:[1,0]
	v_pk_mul_f32 v[238:239], v[132:133], v[142:143] op_sel_hi:[1,0]
	v_pk_mul_f32 v[240:241], v[134:135], v[142:143] op_sel_hi:[1,0]
	v_pk_mul_f32 v[242:243], v[136:137], v[142:143] op_sel_hi:[1,0]
	v_pk_mul_f32 v[236:237], v[236:237], v[138:139]
	v_sin_f32_e32 v244, v236
	v_pk_mul_f32 v[238:239], v[238:239], v[138:139]
	v_sin_f32_e32 v245, v237
	v_pk_mul_f32 v[240:241], v[240:241], v[138:139]
	v_sin_f32_e32 v246, v238
	v_pk_mul_f32 v[242:243], v[242:243], v[138:139]
	v_sin_f32_e32 v247, v239
	v_pk_mul_f32 v[244:245], v[244:245], v[140:141]
	v_sin_f32_e32 v248, v240
	v_pk_mul_f32 v[246:247], v[246:247], v[140:141]
	v_sin_f32_e32 v249, v241
	v_pk_mul_f32 v[144:145], v[42:43], v[244:245]
	v_sin_f32_e32 v250, v242
	v_pk_mul_f32 v[248:249], v[248:249], v[140:141]
	v_sin_f32_e32 v251, v243
	v_pk_mul_f32 v[146:147], v[44:45], v[246:247]
	v_cos_f32_e32 v236, v236
	v_pk_mul_f32 v[250:251], v[250:251], v[140:141]
	v_cos_f32_e32 v237, v237
	v_mov_b32_e32 v142, v162
	v_cos_f32_e32 v238, v238
	v_pk_mul_f32 v[236:237], v[236:237], v[140:141]
	v_cos_f32_e32 v239, v239
	v_pk_fma_f32 v[222:223], v[106:107], v[236:237], v[144:145] neg_lo:[0,0,1] neg_hi:[0,0,1]
	v_cos_f32_e32 v240, v240
	v_pk_mul_f32 v[238:239], v[238:239], v[140:141]
	v_cos_f32_e32 v241, v241
	v_pk_mul_f32 v[144:145], v[106:107], v[244:245]
	v_cos_f32_e32 v242, v242
	v_pk_mul_f32 v[240:241], v[240:241], v[140:141]
	v_cos_f32_e32 v243, v243
	v_pk_fma_f32 v[164:165], v[42:43], v[236:237], v[144:145]
	v_pk_mul_f32 v[242:243], v[242:243], v[140:141]
	v_pk_fma_f32 v[224:225], v[108:109], v[238:239], v[146:147] neg_lo:[0,0,1] neg_hi:[0,0,1]
	v_pk_mul_f32 v[146:147], v[108:109], v[246:247]
	v_pk_fma_f32 v[166:167], v[44:45], v[238:239], v[146:147]
	v_pk_mul_f32 v[144:145], v[34:35], v[248:249]
	v_pk_fma_f32 v[226:227], v[98:99], v[240:241], v[144:145] neg_lo:[0,0,1] neg_hi:[0,0,1]
	v_pk_mul_f32 v[144:145], v[98:99], v[248:249]
	v_pk_fma_f32 v[168:169], v[34:35], v[240:241], v[144:145]
	v_pk_mul_f32 v[146:147], v[36:37], v[250:251]
	v_pk_fma_f32 v[228:229], v[100:101], v[242:243], v[146:147] neg_lo:[0,0,1] neg_hi:[0,0,1]
	v_pk_mul_f32 v[146:147], v[100:101], v[250:251]
	v_pk_fma_f32 v[170:171], v[36:37], v[242:243], v[146:147]
	v_cvt_pk_bf16_f32 v222, v222, v223
	v_cvt_pk_bf16_f32 v223, v224, v225
	v_cvt_pk_bf16_f32 v224, v226, v227
	v_cvt_pk_bf16_f32 v225, v228, v229
	v_cvt_pk_bf16_f32 v164, v164, v165
	v_cvt_pk_bf16_f32 v165, v166, v167
	v_cvt_pk_bf16_f32 v166, v168, v169
	v_cvt_pk_bf16_f32 v167, v170, v171
	v_permlane16_swap_b32_e32 v222, v224
	v_permlane16_swap_b32_e32 v223, v225
	v_permlane16_swap_b32_e32 v164, v166
	v_permlane16_swap_b32_e32 v165, v167
	global_store_dwordx4 v[172:173], v[222:225], off offset:256
	global_store_dwordx4 v[174:175], v[164:167], off offset:256
	v_pk_mul_f32 v[206:207], v[130:131], v[142:143] op_sel_hi:[1,0]
	v_lshl_add_u64 v[172:173], v[172:173], 0, s[2:3]
	v_lshl_add_u64 v[174:175], v[174:175], 0, s[2:3]
	v_pk_mul_f32 v[208:209], v[132:133], v[142:143] op_sel_hi:[1,0]
	v_pk_mul_f32 v[210:211], v[134:135], v[142:143] op_sel_hi:[1,0]
	v_pk_mul_f32 v[212:213], v[136:137], v[142:143] op_sel_hi:[1,0]
	v_pk_mul_f32 v[206:207], v[206:207], v[138:139]
	v_sin_f32_e32 v214, v206
	v_pk_mul_f32 v[208:209], v[208:209], v[138:139]
	v_sin_f32_e32 v215, v207
	v_pk_mul_f32 v[210:211], v[210:211], v[138:139]
	v_sin_f32_e32 v216, v208
	v_pk_mul_f32 v[212:213], v[212:213], v[138:139]
	v_sin_f32_e32 v217, v209
	v_pk_mul_f32 v[214:215], v[214:215], v[140:141]
	v_sin_f32_e32 v218, v210
	v_pk_mul_f32 v[216:217], v[216:217], v[140:141]
	v_sin_f32_e32 v219, v211
	v_pk_mul_f32 v[144:145], v[26:27], v[214:215]
	v_sin_f32_e32 v220, v212
	v_pk_mul_f32 v[218:219], v[218:219], v[140:141]
	v_sin_f32_e32 v221, v213
	v_pk_mul_f32 v[146:147], v[28:29], v[216:217]
	v_cos_f32_e32 v206, v206
	v_pk_mul_f32 v[220:221], v[220:221], v[140:141]
	v_cos_f32_e32 v207, v207
	v_mov_b32_e32 v142, v163
	v_cos_f32_e32 v208, v208
	v_pk_mul_f32 v[206:207], v[206:207], v[140:141]
	v_cos_f32_e32 v209, v209
	v_pk_fma_f32 v[222:223], v[90:91], v[206:207], v[144:145] neg_lo:[0,0,1] neg_hi:[0,0,1]
	v_cos_f32_e32 v210, v210
	v_pk_mul_f32 v[208:209], v[208:209], v[140:141]
	v_cos_f32_e32 v211, v211
	v_pk_mul_f32 v[144:145], v[90:91], v[214:215]
	v_cos_f32_e32 v212, v212
	v_pk_mul_f32 v[210:211], v[210:211], v[140:141]
	v_cos_f32_e32 v213, v213
	v_pk_fma_f32 v[164:165], v[26:27], v[206:207], v[144:145]
	v_pk_mul_f32 v[212:213], v[212:213], v[140:141]
	v_pk_fma_f32 v[224:225], v[92:93], v[208:209], v[146:147] neg_lo:[0,0,1] neg_hi:[0,0,1]
	v_pk_mul_f32 v[146:147], v[92:93], v[216:217]
	v_pk_fma_f32 v[166:167], v[28:29], v[208:209], v[146:147]
	v_pk_mul_f32 v[144:145], v[18:19], v[218:219]
	v_pk_fma_f32 v[226:227], v[82:83], v[210:211], v[144:145] neg_lo:[0,0,1] neg_hi:[0,0,1]
	v_pk_mul_f32 v[144:145], v[82:83], v[218:219]
	v_pk_fma_f32 v[168:169], v[18:19], v[210:211], v[144:145]
	v_pk_mul_f32 v[146:147], v[20:21], v[220:221]
	v_pk_fma_f32 v[228:229], v[84:85], v[212:213], v[146:147] neg_lo:[0,0,1] neg_hi:[0,0,1]
	v_pk_mul_f32 v[146:147], v[84:85], v[220:221]
	v_pk_fma_f32 v[170:171], v[20:21], v[212:213], v[146:147]
	v_cvt_pk_bf16_f32 v222, v222, v223
	v_cvt_pk_bf16_f32 v223, v224, v225
	v_cvt_pk_bf16_f32 v224, v226, v227
	v_cvt_pk_bf16_f32 v225, v228, v229
	v_cvt_pk_bf16_f32 v164, v164, v165
	v_cvt_pk_bf16_f32 v165, v166, v167
	v_cvt_pk_bf16_f32 v166, v168, v169
	v_cvt_pk_bf16_f32 v167, v170, v171
	v_permlane16_swap_b32_e32 v222, v224
	v_permlane16_swap_b32_e32 v223, v225
	v_permlane16_swap_b32_e32 v164, v166
	v_permlane16_swap_b32_e32 v165, v167
	global_store_dwordx4 v[172:173], v[222:225], off
	global_store_dwordx4 v[174:175], v[164:167], off
	v_pk_mul_f32 v[236:237], v[130:131], v[142:143] op_sel_hi:[1,0]
	v_pk_mul_f32 v[238:239], v[132:133], v[142:143] op_sel_hi:[1,0]
	v_pk_mul_f32 v[240:241], v[134:135], v[142:143] op_sel_hi:[1,0]
	v_pk_mul_f32 v[242:243], v[136:137], v[142:143] op_sel_hi:[1,0]
	v_pk_mul_f32 v[236:237], v[236:237], v[138:139]
	v_sin_f32_e32 v244, v236
	v_pk_mul_f32 v[238:239], v[238:239], v[138:139]
	v_sin_f32_e32 v245, v237
	v_pk_mul_f32 v[240:241], v[240:241], v[138:139]
	v_sin_f32_e32 v246, v238
	v_pk_mul_f32 v[242:243], v[242:243], v[138:139]
	v_sin_f32_e32 v247, v239
	v_pk_mul_f32 v[244:245], v[244:245], v[140:141]
	v_sin_f32_e32 v248, v240
	v_pk_mul_f32 v[246:247], v[246:247], v[140:141]
	v_sin_f32_e32 v249, v241
	v_pk_mul_f32 v[144:145], v[10:11], v[244:245]
	v_sin_f32_e32 v250, v242
	v_pk_mul_f32 v[248:249], v[248:249], v[140:141]
	v_sin_f32_e32 v251, v243
	v_pk_mul_f32 v[146:147], v[12:13], v[246:247]
	v_cos_f32_e32 v236, v236
	v_pk_mul_f32 v[250:251], v[250:251], v[140:141]
	v_cos_f32_e32 v237, v237
	v_cos_f32_e32 v238, v238
	v_pk_mul_f32 v[236:237], v[236:237], v[140:141]
	v_cos_f32_e32 v239, v239
	v_pk_fma_f32 v[222:223], v[74:75], v[236:237], v[144:145] neg_lo:[0,0,1] neg_hi:[0,0,1]
	v_cos_f32_e32 v240, v240
	v_pk_mul_f32 v[238:239], v[238:239], v[140:141]
	v_cos_f32_e32 v241, v241
	v_pk_mul_f32 v[144:145], v[74:75], v[244:245]
	v_cos_f32_e32 v242, v242
	v_pk_mul_f32 v[240:241], v[240:241], v[140:141]
	v_cos_f32_e32 v243, v243
	v_pk_fma_f32 v[164:165], v[10:11], v[236:237], v[144:145]
	v_pk_mul_f32 v[242:243], v[242:243], v[140:141]
	v_pk_fma_f32 v[224:225], v[76:77], v[238:239], v[146:147] neg_lo:[0,0,1] neg_hi:[0,0,1]
	v_pk_mul_f32 v[146:147], v[76:77], v[246:247]
	v_pk_fma_f32 v[166:167], v[12:13], v[238:239], v[146:147]
	v_pk_mul_f32 v[144:145], v[2:3], v[248:249]
	v_pk_fma_f32 v[226:227], v[66:67], v[240:241], v[144:145] neg_lo:[0,0,1] neg_hi:[0,0,1]
	v_pk_mul_f32 v[144:145], v[66:67], v[248:249]
	v_pk_fma_f32 v[168:169], v[2:3], v[240:241], v[144:145]
	v_pk_mul_f32 v[146:147], v[4:5], v[250:251]
	v_pk_fma_f32 v[228:229], v[68:69], v[242:243], v[146:147] neg_lo:[0,0,1] neg_hi:[0,0,1]
	v_pk_mul_f32 v[146:147], v[68:69], v[250:251]
	v_pk_fma_f32 v[170:171], v[4:5], v[242:243], v[146:147]
	v_cvt_pk_bf16_f32 v222, v222, v223
	v_cvt_pk_bf16_f32 v223, v224, v225
	v_cvt_pk_bf16_f32 v224, v226, v227
	v_cvt_pk_bf16_f32 v225, v228, v229
	v_cvt_pk_bf16_f32 v164, v164, v165
	v_cvt_pk_bf16_f32 v165, v166, v167
	v_cvt_pk_bf16_f32 v166, v168, v169
	v_cvt_pk_bf16_f32 v167, v170, v171
	v_permlane16_swap_b32_e32 v222, v224
	v_permlane16_swap_b32_e32 v223, v225
	v_permlane16_swap_b32_e32 v164, v166
	v_permlane16_swap_b32_e32 v165, v167
	global_store_dwordx4 v[172:173], v[222:225], off offset:256
	global_store_dwordx4 v[174:175], v[164:167], off offset:256
	s_branch .LBB0_816
.Lretk_fast:
	s_and_b32 s4, s31, 32
	v_lshl_add_u32 v148, v203, 2, s4
	v_cvt_f32_i32_e32 v130, v148
	v_add_u32_e32 v131, 1, v148
	v_cvt_f32_i32_e32 v131, v131
	v_add_u32_e32 v132, 2, v148
	v_cvt_f32_i32_e32 v132, v132
	v_add_u32_e32 v133, 3, v148
	v_cvt_f32_i32_e32 v133, v133
	v_add_u32_e32 v134, 16, v148
	v_cvt_f32_i32_e32 v134, v134
	v_add_u32_e32 v135, 17, v148
	v_cvt_f32_i32_e32 v135, v135
	v_add_u32_e32 v136, 18, v148
	v_cvt_f32_i32_e32 v136, v136
	v_add_u32_e32 v137, 19, v148
	v_cvt_f32_i32_e32 v137, v137
	v_mul_f32_e32 v130, 0xbe549a78, v130
	v_mul_f32_e32 v131, 0xbe549a78, v131
	v_mul_f32_e32 v132, 0xbe549a78, v132
	v_mul_f32_e32 v133, 0xbe549a78, v133
	v_mul_f32_e32 v134, 0xbe549a78, v134
	v_mul_f32_e32 v135, 0xbe549a78, v135
	v_mul_f32_e32 v136, 0xbe549a78, v136
	v_mul_f32_e32 v137, 0xbe549a78, v137
	v_exp_f32_e32 v130, v130
	v_exp_f32_e32 v131, v131
	v_exp_f32_e32 v132, v132
	v_exp_f32_e32 v133, v133
	v_exp_f32_e32 v134, v134
	v_exp_f32_e32 v135, v135
	v_exp_f32_e32 v136, v136
	v_exp_f32_e32 v137, v137
	v_mov_b32_e32 v138, 0x3e22f983
	v_mov_b32_e32 v139, 0x3e22f983
	s_cmp_lt_i32 s30, 2
	s_cselect_b32 s6, 6, 0
	s_cselect_b32 s7, -1, 63
	s_cmp_lt_i32 s66, 64
	s_cselect_b32 s8, 1.0, 0
	s_and_b32 s9, s65, 3
	v_mov_b32_e32 v140, 0x3d800000
	v_mov_b32_e32 v141, 0x3d800000
	v_readlane_b32 s4, v253, 42
	v_mov_b32_e32 v176, s4
	ds_read_b64 v[174:175], v176
	s_lshl_b32 s4, s9, 8
	s_add_i32 s4, s4, s31
	v_and_b32_e32 v176, 1, v203
	v_lshrrev_b32_e32 v177, 1, v203
	v_lshlrev_b32_e32 v176, 4, v176
	v_lshl_add_u32 v176, v177, 3, v176
	v_add_u32_e32 v176, s4, v176
	v_lshlrev_b32_e32 v176, 1, v176
	v_mov_b32_e32 v177, 0
	v_ashrrev_i32_e32 v161, 31, v160
	v_lshlrev_b64 v[172:173], 11, v[160:161]
	s_waitcnt lgkmcnt(0)
	v_lshl_add_u64 v[172:173], v[172:173], 0, v[174:175]
	v_lshl_add_u64 v[172:173], v[172:173], 0, v[176:177]
	s_mov_b64 s[2:3], 0x8000
	s_mov_b64 s[28:29], 0x28000
	v_mov_b32_e32 v142, v160
	v_lshrrev_b32_e32 v142, s6, v142
	v_and_b32_e32 v142, s7, v142
	v_cvt_f32_i32_e32 v142, v142
	v_mul_f32_e32 v142, s8, v142
	v_pk_mul_f32 v[206:207], v[130:131], v[142:143] op_sel_hi:[1,0]
	v_pk_mul_f32 v[208:209], v[132:133], v[142:143] op_sel_hi:[1,0]
	v_pk_mul_f32 v[210:211], v[134:135], v[142:143] op_sel_hi:[1,0]
	v_pk_mul_f32 v[212:213], v[136:137], v[142:143] op_sel_hi:[1,0]
	v_pk_mul_f32 v[206:207], v[206:207], v[138:139]
	v_sin_f32_e32 v214, v206
	v_pk_mul_f32 v[208:209], v[208:209], v[138:139]
	v_sin_f32_e32 v215, v207
	v_pk_mul_f32 v[210:211], v[210:211], v[138:139]
	v_sin_f32_e32 v216, v208
	v_pk_mul_f32 v[212:213], v[212:213], v[138:139]
	v_sin_f32_e32 v217, v209
	v_pk_mul_f32 v[214:215], v[214:215], v[140:141]
	v_sin_f32_e32 v218, v210
	v_pk_mul_f32 v[216:217], v[216:217], v[140:141]
	v_sin_f32_e32 v219, v211
	v_pk_mul_f32 v[144:145], v[122:123], v[214:215]
	v_sin_f32_e32 v220, v212
	v_pk_mul_f32 v[218:219], v[218:219], v[140:141]
	v_sin_f32_e32 v221, v213
	v_pk_mul_f32 v[146:147], v[124:125], v[216:217]
	v_cos_f32_e32 v206, v206
	v_pk_mul_f32 v[220:221], v[220:221], v[140:141]
	v_cos_f32_e32 v207, v207
	v_add_u32_e32 v142, 16, v160
	v_cos_f32_e32 v208, v208
	v_pk_mul_f32 v[206:207], v[206:207], v[140:141]
	v_cos_f32_e32 v209, v209
	v_pk_fma_f32 v[222:223], v[126:127], v[206:207], v[144:145] neg_lo:[0,0,1] neg_hi:[0,0,1]
	v_cos_f32_e32 v210, v210
	v_pk_mul_f32 v[208:209], v[208:209], v[140:141]
	v_cos_f32_e32 v211, v211
	v_pk_mul_f32 v[144:145], v[126:127], v[214:215]
	v_cos_f32_e32 v212, v212
	v_pk_mul_f32 v[210:211], v[210:211], v[140:141]
	v_cos_f32_e32 v213, v213
	v_pk_fma_f32 v[164:165], v[122:123], v[206:207], v[144:145]
	v_pk_mul_f32 v[212:213], v[212:213], v[140:141]
	v_pk_fma_f32 v[224:225], v[128:129], v[208:209], v[146:147] neg_lo:[0,0,1] neg_hi:[0,0,1]
	v_pk_mul_f32 v[146:147], v[128:129], v[216:217]
	v_pk_fma_f32 v[166:167], v[124:125], v[208:209], v[146:147]
	v_pk_mul_f32 v[144:145], v[114:115], v[218:219]
	v_pk_fma_f32 v[226:227], v[118:119], v[210:211], v[144:145] neg_lo:[0,0,1] neg_hi:[0,0,1]
	v_pk_mul_f32 v[144:145], v[118:119], v[218:219]
	v_pk_fma_f32 v[168:169], v[114:115], v[210:211], v[144:145]
	v_pk_mul_f32 v[146:147], v[116:117], v[220:221]
	v_pk_fma_f32 v[228:229], v[120:121], v[212:213], v[146:147] neg_lo:[0,0,1] neg_hi:[0,0,1]
	v_pk_mul_f32 v[146:147], v[120:121], v[220:221]
	v_pk_fma_f32 v[170:171], v[116:117], v[212:213], v[146:147]
	v_cvt_pk_bf16_f32 v222, v222, v223
	v_cvt_pk_bf16_f32 v223, v224, v225
	v_cvt_pk_bf16_f32 v224, v226, v227
	v_cvt_pk_bf16_f32 v225, v228, v229
	v_cvt_pk_bf16_f32 v164, v164, v165
	v_cvt_pk_bf16_f32 v165, v166, v167
	v_cvt_pk_bf16_f32 v166, v168, v169
	v_cvt_pk_bf16_f32 v167, v170, v171
	v_permlane16_swap_b32_e32 v222, v224
	v_permlane16_swap_b32_e32 v223, v225
	v_permlane16_swap_b32_e32 v164, v166
	v_permlane16_swap_b32_e32 v165, v167
	global_store_dwordx4 v[172:173], v[222:225], off
	global_store_dwordx4 v[172:173], v[164:167], off offset:256
	v_lshrrev_b32_e32 v142, s6, v142
	v_and_b32_e32 v142, s7, v142
	v_lshl_add_u64 v[172:173], v[172:173], 0, s[2:3]
	v_cvt_f32_i32_e32 v142, v142
	v_mul_f32_e32 v142, s8, v142
	v_pk_mul_f32 v[236:237], v[130:131], v[142:143] op_sel_hi:[1,0]
	v_pk_mul_f32 v[238:239], v[132:133], v[142:143] op_sel_hi:[1,0]
	v_pk_mul_f32 v[240:241], v[134:135], v[142:143] op_sel_hi:[1,0]
	v_pk_mul_f32 v[242:243], v[136:137], v[142:143] op_sel_hi:[1,0]
	v_pk_mul_f32 v[236:237], v[236:237], v[138:139]
	v_sin_f32_e32 v244, v236
	v_pk_mul_f32 v[238:239], v[238:239], v[138:139]
	v_sin_f32_e32 v245, v237
	v_pk_mul_f32 v[240:241], v[240:241], v[138:139]
	v_sin_f32_e32 v246, v238
	v_pk_mul_f32 v[242:243], v[242:243], v[138:139]
	v_sin_f32_e32 v247, v239
	v_pk_mul_f32 v[244:245], v[244:245], v[140:141]
	v_sin_f32_e32 v248, v240
	v_pk_mul_f32 v[246:247], v[246:247], v[140:141]
	v_sin_f32_e32 v249, v241
	v_pk_mul_f32 v[144:145], v[106:107], v[244:245]
	v_sin_f32_e32 v250, v242
	v_pk_mul_f32 v[248:249], v[248:249], v[140:141]
	v_sin_f32_e32 v251, v243
	v_pk_mul_f32 v[146:147], v[108:109], v[246:247]
	v_cos_f32_e32 v236, v236
	v_pk_mul_f32 v[250:251], v[250:251], v[140:141]
	v_cos_f32_e32 v237, v237
	v_add_u32_e32 v142, 32, v160
	v_cos_f32_e32 v238, v238
	v_pk_mul_f32 v[236:237], v[236:237], v[140:141]
	v_cos_f32_e32 v239, v239
	v_pk_fma_f32 v[222:223], v[110:111], v[236:237], v[144:145] neg_lo:[0,0,1] neg_hi:[0,0,1]
	v_cos_f32_e32 v240, v240
	v_pk_mul_f32 v[238:239], v[238:239], v[140:141]
	v_cos_f32_e32 v241, v241
	v_pk_mul_f32 v[144:145], v[110:111], v[244:245]
	v_cos_f32_e32 v242, v242
	v_pk_mul_f32 v[240:241], v[240:241], v[140:141]
	v_cos_f32_e32 v243, v243
	v_pk_fma_f32 v[164:165], v[106:107], v[236:237], v[144:145]
	v_pk_mul_f32 v[242:243], v[242:243], v[140:141]
	v_pk_fma_f32 v[224:225], v[112:113], v[238:239], v[146:147] neg_lo:[0,0,1] neg_hi:[0,0,1]
	v_pk_mul_f32 v[146:147], v[112:113], v[246:247]
	v_pk_fma_f32 v[166:167], v[108:109], v[238:239], v[146:147]
	v_pk_mul_f32 v[144:145], v[98:99], v[248:249]
	v_pk_fma_f32 v[226:227], v[102:103], v[240:241], v[144:145] neg_lo:[0,0,1] neg_hi:[0,0,1]
	v_pk_mul_f32 v[144:145], v[102:103], v[248:249]
	v_pk_fma_f32 v[168:169], v[98:99], v[240:241], v[144:145]
	v_pk_mul_f32 v[146:147], v[100:101], v[250:251]
	v_pk_fma_f32 v[228:229], v[104:105], v[242:243], v[146:147] neg_lo:[0,0,1] neg_hi:[0,0,1]
	v_pk_mul_f32 v[146:147], v[104:105], v[250:251]
	v_pk_fma_f32 v[170:171], v[100:101], v[242:243], v[146:147]
	v_cvt_pk_bf16_f32 v222, v222, v223
	v_cvt_pk_bf16_f32 v223, v224, v225
	v_cvt_pk_bf16_f32 v224, v226, v227
	v_cvt_pk_bf16_f32 v225, v228, v229
	v_cvt_pk_bf16_f32 v164, v164, v165
	v_cvt_pk_bf16_f32 v165, v166, v167
	v_cvt_pk_bf16_f32 v166, v168, v169
	v_cvt_pk_bf16_f32 v167, v170, v171
	v_permlane16_swap_b32_e32 v222, v224
	v_permlane16_swap_b32_e32 v223, v225
	v_permlane16_swap_b32_e32 v164, v166
	v_permlane16_swap_b32_e32 v165, v167
	global_store_dwordx4 v[172:173], v[222:225], off
	global_store_dwordx4 v[172:173], v[164:167], off offset:256
	v_lshrrev_b32_e32 v142, s6, v142
	v_and_b32_e32 v142, s7, v142
	v_lshl_add_u64 v[172:173], v[172:173], 0, s[2:3]
	v_cvt_f32_i32_e32 v142, v142
	v_mul_f32_e32 v142, s8, v142
	v_pk_mul_f32 v[206:207], v[130:131], v[142:143] op_sel_hi:[1,0]
	v_pk_mul_f32 v[208:209], v[132:133], v[142:143] op_sel_hi:[1,0]
	v_pk_mul_f32 v[210:211], v[134:135], v[142:143] op_sel_hi:[1,0]
	v_pk_mul_f32 v[212:213], v[136:137], v[142:143] op_sel_hi:[1,0]
	v_pk_mul_f32 v[206:207], v[206:207], v[138:139]
	v_sin_f32_e32 v214, v206
	v_pk_mul_f32 v[208:209], v[208:209], v[138:139]
	v_sin_f32_e32 v215, v207
	v_pk_mul_f32 v[210:211], v[210:211], v[138:139]
	v_sin_f32_e32 v216, v208
	v_pk_mul_f32 v[212:213], v[212:213], v[138:139]
	v_sin_f32_e32 v217, v209
	v_pk_mul_f32 v[214:215], v[214:215], v[140:141]
	v_sin_f32_e32 v218, v210
	v_pk_mul_f32 v[216:217], v[216:217], v[140:141]
	v_sin_f32_e32 v219, v211
	v_pk_mul_f32 v[144:145], v[90:91], v[214:215]
	v_sin_f32_e32 v220, v212
	v_pk_mul_f32 v[218:219], v[218:219], v[140:141]
	v_sin_f32_e32 v221, v213
	v_pk_mul_f32 v[146:147], v[92:93], v[216:217]
	v_cos_f32_e32 v206, v206
	v_pk_mul_f32 v[220:221], v[220:221], v[140:141]
	v_cos_f32_e32 v207, v207
	v_add_u32_e32 v142, 48, v160
	v_cos_f32_e32 v208, v208
	v_pk_mul_f32 v[206:207], v[206:207], v[140:141]
	v_cos_f32_e32 v209, v209
	v_pk_fma_f32 v[222:223], v[94:95], v[206:207], v[144:145] neg_lo:[0,0,1] neg_hi:[0,0,1]
	v_cos_f32_e32 v210, v210
	v_pk_mul_f32 v[208:209], v[208:209], v[140:141]
	v_cos_f32_e32 v211, v211
	v_pk_mul_f32 v[144:145], v[94:95], v[214:215]
	v_cos_f32_e32 v212, v212
	v_pk_mul_f32 v[210:211], v[210:211], v[140:141]
	v_cos_f32_e32 v213, v213
	v_pk_fma_f32 v[164:165], v[90:91], v[206:207], v[144:145]
	v_pk_mul_f32 v[212:213], v[212:213], v[140:141]
	v_pk_fma_f32 v[224:225], v[96:97], v[208:209], v[146:147] neg_lo:[0,0,1] neg_hi:[0,0,1]
	v_pk_mul_f32 v[146:147], v[96:97], v[216:217]
	v_pk_fma_f32 v[166:167], v[92:93], v[208:209], v[146:147]
	v_pk_mul_f32 v[144:145], v[82:83], v[218:219]
	v_pk_fma_f32 v[226:227], v[86:87], v[210:211], v[144:145] neg_lo:[0,0,1] neg_hi:[0,0,1]
	v_pk_mul_f32 v[144:145], v[86:87], v[218:219]
	v_pk_fma_f32 v[168:169], v[82:83], v[210:211], v[144:145]
	v_pk_mul_f32 v[146:147], v[84:85], v[220:221]
	v_pk_fma_f32 v[228:229], v[88:89], v[212:213], v[146:147] neg_lo:[0,0,1] neg_hi:[0,0,1]
	v_pk_mul_f32 v[146:147], v[88:89], v[220:221]
	v_pk_fma_f32 v[170:171], v[84:85], v[212:213], v[146:147]
	v_cvt_pk_bf16_f32 v222, v222, v223
	v_cvt_pk_bf16_f32 v223, v224, v225
	v_cvt_pk_bf16_f32 v224, v226, v227
	v_cvt_pk_bf16_f32 v225, v228, v229
	v_cvt_pk_bf16_f32 v164, v164, v165
	v_cvt_pk_bf16_f32 v165, v166, v167
	v_cvt_pk_bf16_f32 v166, v168, v169
	v_cvt_pk_bf16_f32 v167, v170, v171
	v_permlane16_swap_b32_e32 v222, v224
	v_permlane16_swap_b32_e32 v223, v225
	v_permlane16_swap_b32_e32 v164, v166
	v_permlane16_swap_b32_e32 v165, v167
	global_store_dwordx4 v[172:173], v[222:225], off
	global_store_dwordx4 v[172:173], v[164:167], off offset:256
	v_lshrrev_b32_e32 v142, s6, v142
	v_and_b32_e32 v142, s7, v142
	v_lshl_add_u64 v[172:173], v[172:173], 0, s[2:3]
	v_cvt_f32_i32_e32 v142, v142
	v_mul_f32_e32 v142, s8, v142
	v_pk_mul_f32 v[236:237], v[130:131], v[142:143] op_sel_hi:[1,0]
	v_pk_mul_f32 v[238:239], v[132:133], v[142:143] op_sel_hi:[1,0]
	v_pk_mul_f32 v[240:241], v[134:135], v[142:143] op_sel_hi:[1,0]
	v_pk_mul_f32 v[242:243], v[136:137], v[142:143] op_sel_hi:[1,0]
	v_pk_mul_f32 v[236:237], v[236:237], v[138:139]
	v_sin_f32_e32 v244, v236
	v_pk_mul_f32 v[238:239], v[238:239], v[138:139]
	v_sin_f32_e32 v245, v237
	v_pk_mul_f32 v[240:241], v[240:241], v[138:139]
	v_sin_f32_e32 v246, v238
	v_pk_mul_f32 v[242:243], v[242:243], v[138:139]
	v_sin_f32_e32 v247, v239
	v_pk_mul_f32 v[244:245], v[244:245], v[140:141]
	v_sin_f32_e32 v248, v240
	v_pk_mul_f32 v[246:247], v[246:247], v[140:141]
	v_sin_f32_e32 v249, v241
	v_pk_mul_f32 v[144:145], v[74:75], v[244:245]
	v_sin_f32_e32 v250, v242
	v_pk_mul_f32 v[248:249], v[248:249], v[140:141]
	v_sin_f32_e32 v251, v243
	v_pk_mul_f32 v[146:147], v[76:77], v[246:247]
	v_cos_f32_e32 v236, v236
	v_pk_mul_f32 v[250:251], v[250:251], v[140:141]
	v_cos_f32_e32 v237, v237
	v_add_u32_e32 v142, 128, v160
	v_cos_f32_e32 v238, v238
	v_pk_mul_f32 v[236:237], v[236:237], v[140:141]
	v_cos_f32_e32 v239, v239
	v_pk_fma_f32 v[222:223], v[78:79], v[236:237], v[144:145] neg_lo:[0,0,1] neg_hi:[0,0,1]
	v_cos_f32_e32 v240, v240
	v_pk_mul_f32 v[238:239], v[238:239], v[140:141]
	v_cos_f32_e32 v241, v241
	v_pk_mul_f32 v[144:145], v[78:79], v[244:245]
	v_cos_f32_e32 v242, v242
	v_pk_mul_f32 v[240:241], v[240:241], v[140:141]
	v_cos_f32_e32 v243, v243
	v_pk_fma_f32 v[164:165], v[74:75], v[236:237], v[144:145]
	v_pk_mul_f32 v[242:243], v[242:243], v[140:141]
	v_pk_fma_f32 v[224:225], v[80:81], v[238:239], v[146:147] neg_lo:[0,0,1] neg_hi:[0,0,1]
	v_pk_mul_f32 v[146:147], v[80:81], v[246:247]
	v_pk_fma_f32 v[166:167], v[76:77], v[238:239], v[146:147]
	v_pk_mul_f32 v[144:145], v[66:67], v[248:249]
	v_pk_fma_f32 v[226:227], v[70:71], v[240:241], v[144:145] neg_lo:[0,0,1] neg_hi:[0,0,1]
	v_pk_mul_f32 v[144:145], v[70:71], v[248:249]
	v_pk_fma_f32 v[168:169], v[66:67], v[240:241], v[144:145]
	v_pk_mul_f32 v[146:147], v[68:69], v[250:251]
	v_pk_fma_f32 v[228:229], v[72:73], v[242:243], v[146:147] neg_lo:[0,0,1] neg_hi:[0,0,1]
	v_pk_mul_f32 v[146:147], v[72:73], v[250:251]
	v_pk_fma_f32 v[170:171], v[68:69], v[242:243], v[146:147]
	v_cvt_pk_bf16_f32 v222, v222, v223
	v_cvt_pk_bf16_f32 v223, v224, v225
	v_cvt_pk_bf16_f32 v224, v226, v227
	v_cvt_pk_bf16_f32 v225, v228, v229
	v_cvt_pk_bf16_f32 v164, v164, v165
	v_cvt_pk_bf16_f32 v165, v166, v167
	v_cvt_pk_bf16_f32 v166, v168, v169
	v_cvt_pk_bf16_f32 v167, v170, v171
	v_permlane16_swap_b32_e32 v222, v224
	v_permlane16_swap_b32_e32 v223, v225
	v_permlane16_swap_b32_e32 v164, v166
	v_permlane16_swap_b32_e32 v165, v167
	global_store_dwordx4 v[172:173], v[222:225], off
	global_store_dwordx4 v[172:173], v[164:167], off offset:256
	v_lshrrev_b32_e32 v142, s6, v142
	v_and_b32_e32 v142, s7, v142
	v_lshl_add_u64 v[172:173], v[172:173], 0, s[28:29]
	v_cvt_f32_i32_e32 v142, v142
	v_mul_f32_e32 v142, s8, v142
	v_pk_mul_f32 v[206:207], v[130:131], v[142:143] op_sel_hi:[1,0]
	v_pk_mul_f32 v[208:209], v[132:133], v[142:143] op_sel_hi:[1,0]
	v_pk_mul_f32 v[210:211], v[134:135], v[142:143] op_sel_hi:[1,0]
	v_pk_mul_f32 v[212:213], v[136:137], v[142:143] op_sel_hi:[1,0]
	v_pk_mul_f32 v[206:207], v[206:207], v[138:139]
	v_sin_f32_e32 v214, v206
	v_pk_mul_f32 v[208:209], v[208:209], v[138:139]
	v_sin_f32_e32 v215, v207
	v_pk_mul_f32 v[210:211], v[210:211], v[138:139]
	v_sin_f32_e32 v216, v208
	v_pk_mul_f32 v[212:213], v[212:213], v[138:139]
	v_sin_f32_e32 v217, v209
	v_pk_mul_f32 v[214:215], v[214:215], v[140:141]
	v_sin_f32_e32 v218, v210
	v_pk_mul_f32 v[216:217], v[216:217], v[140:141]
	v_sin_f32_e32 v219, v211
	v_pk_mul_f32 v[144:145], v[58:59], v[214:215]
	v_sin_f32_e32 v220, v212
	v_pk_mul_f32 v[218:219], v[218:219], v[140:141]
	v_sin_f32_e32 v221, v213
	v_pk_mul_f32 v[146:147], v[60:61], v[216:217]
	v_cos_f32_e32 v206, v206
	v_pk_mul_f32 v[220:221], v[220:221], v[140:141]
	v_cos_f32_e32 v207, v207
	v_add_u32_e32 v142, 144, v160
	v_cos_f32_e32 v208, v208
	v_pk_mul_f32 v[206:207], v[206:207], v[140:141]
	v_cos_f32_e32 v209, v209
	v_pk_fma_f32 v[222:223], v[62:63], v[206:207], v[144:145] neg_lo:[0,0,1] neg_hi:[0,0,1]
	v_cos_f32_e32 v210, v210
	v_pk_mul_f32 v[208:209], v[208:209], v[140:141]
	v_cos_f32_e32 v211, v211
	v_pk_mul_f32 v[144:145], v[62:63], v[214:215]
	v_cos_f32_e32 v212, v212
	v_pk_mul_f32 v[210:211], v[210:211], v[140:141]
	v_cos_f32_e32 v213, v213
	v_pk_fma_f32 v[164:165], v[58:59], v[206:207], v[144:145]
	v_pk_mul_f32 v[212:213], v[212:213], v[140:141]
	v_pk_fma_f32 v[224:225], v[64:65], v[208:209], v[146:147] neg_lo:[0,0,1] neg_hi:[0,0,1]
	v_pk_mul_f32 v[146:147], v[64:65], v[216:217]
	v_pk_fma_f32 v[166:167], v[60:61], v[208:209], v[146:147]
	v_pk_mul_f32 v[144:145], v[50:51], v[218:219]
	v_pk_fma_f32 v[226:227], v[54:55], v[210:211], v[144:145] neg_lo:[0,0,1] neg_hi:[0,0,1]
	v_pk_mul_f32 v[144:145], v[54:55], v[218:219]
	v_pk_fma_f32 v[168:169], v[50:51], v[210:211], v[144:145]
	v_pk_mul_f32 v[146:147], v[52:53], v[220:221]
	v_pk_fma_f32 v[228:229], v[56:57], v[212:213], v[146:147] neg_lo:[0,0,1] neg_hi:[0,0,1]
	v_pk_mul_f32 v[146:147], v[56:57], v[220:221]
	v_pk_fma_f32 v[170:171], v[52:53], v[212:213], v[146:147]
	v_cvt_pk_bf16_f32 v222, v222, v223
	v_cvt_pk_bf16_f32 v223, v224, v225
	v_cvt_pk_bf16_f32 v224, v226, v227
	v_cvt_pk_bf16_f32 v225, v228, v229
	v_cvt_pk_bf16_f32 v164, v164, v165
	v_cvt_pk_bf16_f32 v165, v166, v167
	v_cvt_pk_bf16_f32 v166, v168, v169
	v_cvt_pk_bf16_f32 v167, v170, v171
	v_permlane16_swap_b32_e32 v222, v224
	v_permlane16_swap_b32_e32 v223, v225
	v_permlane16_swap_b32_e32 v164, v166
	v_permlane16_swap_b32_e32 v165, v167
	global_store_dwordx4 v[172:173], v[222:225], off
	global_store_dwordx4 v[172:173], v[164:167], off offset:256
	v_lshrrev_b32_e32 v142, s6, v142
	v_and_b32_e32 v142, s7, v142
	v_lshl_add_u64 v[172:173], v[172:173], 0, s[2:3]
	v_cvt_f32_i32_e32 v142, v142
	v_mul_f32_e32 v142, s8, v142
	v_pk_mul_f32 v[236:237], v[130:131], v[142:143] op_sel_hi:[1,0]
	v_pk_mul_f32 v[238:239], v[132:133], v[142:143] op_sel_hi:[1,0]
	v_pk_mul_f32 v[240:241], v[134:135], v[142:143] op_sel_hi:[1,0]
	v_pk_mul_f32 v[242:243], v[136:137], v[142:143] op_sel_hi:[1,0]
	v_pk_mul_f32 v[236:237], v[236:237], v[138:139]
	v_sin_f32_e32 v244, v236
	v_pk_mul_f32 v[238:239], v[238:239], v[138:139]
	v_sin_f32_e32 v245, v237
	v_pk_mul_f32 v[240:241], v[240:241], v[138:139]
	v_sin_f32_e32 v246, v238
	v_pk_mul_f32 v[242:243], v[242:243], v[138:139]
	v_sin_f32_e32 v247, v239
	v_pk_mul_f32 v[244:245], v[244:245], v[140:141]
	v_sin_f32_e32 v248, v240
	v_pk_mul_f32 v[246:247], v[246:247], v[140:141]
	v_sin_f32_e32 v249, v241
	v_pk_mul_f32 v[144:145], v[42:43], v[244:245]
	v_sin_f32_e32 v250, v242
	v_pk_mul_f32 v[248:249], v[248:249], v[140:141]
	v_sin_f32_e32 v251, v243
	v_pk_mul_f32 v[146:147], v[44:45], v[246:247]
	v_cos_f32_e32 v236, v236
	v_pk_mul_f32 v[250:251], v[250:251], v[140:141]
	v_cos_f32_e32 v237, v237
	v_add_u32_e32 v142, 160, v160
	v_cos_f32_e32 v238, v238
	v_pk_mul_f32 v[236:237], v[236:237], v[140:141]
	v_cos_f32_e32 v239, v239
	v_pk_fma_f32 v[222:223], v[46:47], v[236:237], v[144:145] neg_lo:[0,0,1] neg_hi:[0,0,1]
	v_cos_f32_e32 v240, v240
	v_pk_mul_f32 v[238:239], v[238:239], v[140:141]
	v_cos_f32_e32 v241, v241
	v_pk_mul_f32 v[144:145], v[46:47], v[244:245]
	v_cos_f32_e32 v242, v242
	v_pk_mul_f32 v[240:241], v[240:241], v[140:141]
	v_cos_f32_e32 v243, v243
	v_pk_fma_f32 v[164:165], v[42:43], v[236:237], v[144:145]
	v_pk_mul_f32 v[242:243], v[242:243], v[140:141]
	v_pk_fma_f32 v[224:225], v[48:49], v[238:239], v[146:147] neg_lo:[0,0,1] neg_hi:[0,0,1]
	v_pk_mul_f32 v[146:147], v[48:49], v[246:247]
	v_pk_fma_f32 v[166:167], v[44:45], v[238:239], v[146:147]
	v_pk_mul_f32 v[144:145], v[34:35], v[248:249]
	v_pk_fma_f32 v[226:227], v[38:39], v[240:241], v[144:145] neg_lo:[0,0,1] neg_hi:[0,0,1]
	v_pk_mul_f32 v[144:145], v[38:39], v[248:249]
	v_pk_fma_f32 v[168:169], v[34:35], v[240:241], v[144:145]
	v_pk_mul_f32 v[146:147], v[36:37], v[250:251]
	v_pk_fma_f32 v[228:229], v[40:41], v[242:243], v[146:147] neg_lo:[0,0,1] neg_hi:[0,0,1]
	v_pk_mul_f32 v[146:147], v[40:41], v[250:251]
	v_pk_fma_f32 v[170:171], v[36:37], v[242:243], v[146:147]
	v_cvt_pk_bf16_f32 v222, v222, v223
	v_cvt_pk_bf16_f32 v223, v224, v225
	v_cvt_pk_bf16_f32 v224, v226, v227
	v_cvt_pk_bf16_f32 v225, v228, v229
	v_cvt_pk_bf16_f32 v164, v164, v165
	v_cvt_pk_bf16_f32 v165, v166, v167
	v_cvt_pk_bf16_f32 v166, v168, v169
	v_cvt_pk_bf16_f32 v167, v170, v171
	v_permlane16_swap_b32_e32 v222, v224
	v_permlane16_swap_b32_e32 v223, v225
	v_permlane16_swap_b32_e32 v164, v166
	v_permlane16_swap_b32_e32 v165, v167
	global_store_dwordx4 v[172:173], v[222:225], off
	global_store_dwordx4 v[172:173], v[164:167], off offset:256
	v_lshrrev_b32_e32 v142, s6, v142
	v_and_b32_e32 v142, s7, v142
	v_lshl_add_u64 v[172:173], v[172:173], 0, s[2:3]
	v_cvt_f32_i32_e32 v142, v142
	v_mul_f32_e32 v142, s8, v142
	v_pk_mul_f32 v[206:207], v[130:131], v[142:143] op_sel_hi:[1,0]
	v_pk_mul_f32 v[208:209], v[132:133], v[142:143] op_sel_hi:[1,0]
	v_pk_mul_f32 v[210:211], v[134:135], v[142:143] op_sel_hi:[1,0]
	v_pk_mul_f32 v[212:213], v[136:137], v[142:143] op_sel_hi:[1,0]
	v_pk_mul_f32 v[206:207], v[206:207], v[138:139]
	v_sin_f32_e32 v214, v206
	v_pk_mul_f32 v[208:209], v[208:209], v[138:139]
	v_sin_f32_e32 v215, v207
	v_pk_mul_f32 v[210:211], v[210:211], v[138:139]
	v_sin_f32_e32 v216, v208
	v_pk_mul_f32 v[212:213], v[212:213], v[138:139]
	v_sin_f32_e32 v217, v209
	v_pk_mul_f32 v[214:215], v[214:215], v[140:141]
	v_sin_f32_e32 v218, v210
	v_pk_mul_f32 v[216:217], v[216:217], v[140:141]
	v_sin_f32_e32 v219, v211
	v_pk_mul_f32 v[144:145], v[26:27], v[214:215]
	v_sin_f32_e32 v220, v212
	v_pk_mul_f32 v[218:219], v[218:219], v[140:141]
	v_sin_f32_e32 v221, v213
	v_pk_mul_f32 v[146:147], v[28:29], v[216:217]
	v_cos_f32_e32 v206, v206
	v_pk_mul_f32 v[220:221], v[220:221], v[140:141]
	v_cos_f32_e32 v207, v207
	v_add_u32_e32 v142, 176, v160
	v_cos_f32_e32 v208, v208
	v_pk_mul_f32 v[206:207], v[206:207], v[140:141]
	v_cos_f32_e32 v209, v209
	v_pk_fma_f32 v[222:223], v[30:31], v[206:207], v[144:145] neg_lo:[0,0,1] neg_hi:[0,0,1]
	v_cos_f32_e32 v210, v210
	v_pk_mul_f32 v[208:209], v[208:209], v[140:141]
	v_cos_f32_e32 v211, v211
	v_pk_mul_f32 v[144:145], v[30:31], v[214:215]
	v_cos_f32_e32 v212, v212
	v_pk_mul_f32 v[210:211], v[210:211], v[140:141]
	v_cos_f32_e32 v213, v213
	v_pk_fma_f32 v[164:165], v[26:27], v[206:207], v[144:145]
	v_pk_mul_f32 v[212:213], v[212:213], v[140:141]
	v_pk_fma_f32 v[224:225], v[32:33], v[208:209], v[146:147] neg_lo:[0,0,1] neg_hi:[0,0,1]
	v_pk_mul_f32 v[146:147], v[32:33], v[216:217]
	v_pk_fma_f32 v[166:167], v[28:29], v[208:209], v[146:147]
	v_pk_mul_f32 v[144:145], v[18:19], v[218:219]
	v_pk_fma_f32 v[226:227], v[22:23], v[210:211], v[144:145] neg_lo:[0,0,1] neg_hi:[0,0,1]
	v_pk_mul_f32 v[144:145], v[22:23], v[218:219]
	v_pk_fma_f32 v[168:169], v[18:19], v[210:211], v[144:145]
	v_pk_mul_f32 v[146:147], v[20:21], v[220:221]
	v_pk_fma_f32 v[228:229], v[24:25], v[212:213], v[146:147] neg_lo:[0,0,1] neg_hi:[0,0,1]
	v_pk_mul_f32 v[146:147], v[24:25], v[220:221]
	v_pk_fma_f32 v[170:171], v[20:21], v[212:213], v[146:147]
	v_cvt_pk_bf16_f32 v222, v222, v223
	v_cvt_pk_bf16_f32 v223, v224, v225
	v_cvt_pk_bf16_f32 v224, v226, v227
	v_cvt_pk_bf16_f32 v225, v228, v229
	v_cvt_pk_bf16_f32 v164, v164, v165
	v_cvt_pk_bf16_f32 v165, v166, v167
	v_cvt_pk_bf16_f32 v166, v168, v169
	v_cvt_pk_bf16_f32 v167, v170, v171
	v_permlane16_swap_b32_e32 v222, v224
	v_permlane16_swap_b32_e32 v223, v225
	v_permlane16_swap_b32_e32 v164, v166
	v_permlane16_swap_b32_e32 v165, v167
	global_store_dwordx4 v[172:173], v[222:225], off
	global_store_dwordx4 v[172:173], v[164:167], off offset:256
	v_lshrrev_b32_e32 v142, s6, v142
	v_and_b32_e32 v142, s7, v142
	v_lshl_add_u64 v[172:173], v[172:173], 0, s[2:3]
	v_cvt_f32_i32_e32 v142, v142
	v_mul_f32_e32 v142, s8, v142
	v_pk_mul_f32 v[236:237], v[130:131], v[142:143] op_sel_hi:[1,0]
	v_pk_mul_f32 v[238:239], v[132:133], v[142:143] op_sel_hi:[1,0]
	v_pk_mul_f32 v[240:241], v[134:135], v[142:143] op_sel_hi:[1,0]
	v_pk_mul_f32 v[242:243], v[136:137], v[142:143] op_sel_hi:[1,0]
	v_pk_mul_f32 v[236:237], v[236:237], v[138:139]
	v_sin_f32_e32 v244, v236
	v_pk_mul_f32 v[238:239], v[238:239], v[138:139]
	v_sin_f32_e32 v245, v237
	v_pk_mul_f32 v[240:241], v[240:241], v[138:139]
	v_sin_f32_e32 v246, v238
	v_pk_mul_f32 v[242:243], v[242:243], v[138:139]
	v_sin_f32_e32 v247, v239
	v_pk_mul_f32 v[244:245], v[244:245], v[140:141]
	v_sin_f32_e32 v248, v240
	v_pk_mul_f32 v[246:247], v[246:247], v[140:141]
	v_sin_f32_e32 v249, v241
	v_pk_mul_f32 v[144:145], v[10:11], v[244:245]
	v_sin_f32_e32 v250, v242
	v_pk_mul_f32 v[248:249], v[248:249], v[140:141]
	v_sin_f32_e32 v251, v243
	v_pk_mul_f32 v[146:147], v[12:13], v[246:247]
	v_cos_f32_e32 v236, v236
	v_pk_mul_f32 v[250:251], v[250:251], v[140:141]
	v_cos_f32_e32 v237, v237
	v_cos_f32_e32 v238, v238
	v_pk_mul_f32 v[236:237], v[236:237], v[140:141]
	v_cos_f32_e32 v239, v239
	v_pk_fma_f32 v[222:223], v[14:15], v[236:237], v[144:145] neg_lo:[0,0,1] neg_hi:[0,0,1]
	v_cos_f32_e32 v240, v240
	v_pk_mul_f32 v[238:239], v[238:239], v[140:141]
	v_cos_f32_e32 v241, v241
	v_pk_mul_f32 v[144:145], v[14:15], v[244:245]
	v_cos_f32_e32 v242, v242
	v_pk_mul_f32 v[240:241], v[240:241], v[140:141]
	v_cos_f32_e32 v243, v243
	v_pk_fma_f32 v[164:165], v[10:11], v[236:237], v[144:145]
	v_pk_mul_f32 v[242:243], v[242:243], v[140:141]
	v_pk_fma_f32 v[224:225], v[16:17], v[238:239], v[146:147] neg_lo:[0,0,1] neg_hi:[0,0,1]
	v_pk_mul_f32 v[146:147], v[16:17], v[246:247]
	v_pk_fma_f32 v[166:167], v[12:13], v[238:239], v[146:147]
	v_pk_mul_f32 v[144:145], v[2:3], v[248:249]
	v_pk_fma_f32 v[226:227], v[6:7], v[240:241], v[144:145] neg_lo:[0,0,1] neg_hi:[0,0,1]
	v_pk_mul_f32 v[144:145], v[6:7], v[248:249]
	v_pk_fma_f32 v[168:169], v[2:3], v[240:241], v[144:145]
	v_pk_mul_f32 v[146:147], v[4:5], v[250:251]
	v_pk_fma_f32 v[228:229], v[8:9], v[242:243], v[146:147] neg_lo:[0,0,1] neg_hi:[0,0,1]
	v_pk_mul_f32 v[146:147], v[8:9], v[250:251]
	v_pk_fma_f32 v[170:171], v[4:5], v[242:243], v[146:147]
	v_cvt_pk_bf16_f32 v222, v222, v223
	v_cvt_pk_bf16_f32 v223, v224, v225
	v_cvt_pk_bf16_f32 v224, v226, v227
	v_cvt_pk_bf16_f32 v225, v228, v229
	v_cvt_pk_bf16_f32 v164, v164, v165
	v_cvt_pk_bf16_f32 v165, v166, v167
	v_cvt_pk_bf16_f32 v166, v168, v169
	v_cvt_pk_bf16_f32 v167, v170, v171
	v_permlane16_swap_b32_e32 v222, v224
	v_permlane16_swap_b32_e32 v223, v225
	v_permlane16_swap_b32_e32 v164, v166
	v_permlane16_swap_b32_e32 v165, v167
	global_store_dwordx4 v[172:173], v[222:225], off
	global_store_dwordx4 v[172:173], v[164:167], off offset:256
	s_branch .LBB0_816
.Lretq_fast:
	s_and_b32 s4, s31, 32
	v_lshl_add_u32 v148, v203, 2, s4
	v_cvt_f32_i32_e32 v130, v148
	v_add_u32_e32 v131, 1, v148
	v_cvt_f32_i32_e32 v131, v131
	v_add_u32_e32 v132, 2, v148
	v_cvt_f32_i32_e32 v132, v132
	v_add_u32_e32 v133, 3, v148
	v_cvt_f32_i32_e32 v133, v133
	v_add_u32_e32 v134, 16, v148
	v_cvt_f32_i32_e32 v134, v134
	v_add_u32_e32 v135, 17, v148
	v_cvt_f32_i32_e32 v135, v135
	v_add_u32_e32 v136, 18, v148
	v_cvt_f32_i32_e32 v136, v136
	v_add_u32_e32 v137, 19, v148
	v_cvt_f32_i32_e32 v137, v137
	v_mul_f32_e32 v130, 0xbe549a78, v130
	v_mul_f32_e32 v131, 0xbe549a78, v131
	v_mul_f32_e32 v132, 0xbe549a78, v132
	v_mul_f32_e32 v133, 0xbe549a78, v133
	v_mul_f32_e32 v134, 0xbe549a78, v134
	v_mul_f32_e32 v135, 0xbe549a78, v135
	v_mul_f32_e32 v136, 0xbe549a78, v136
	v_mul_f32_e32 v137, 0xbe549a78, v137
	v_exp_f32_e32 v130, v130
	v_exp_f32_e32 v131, v131
	v_exp_f32_e32 v132, v132
	v_exp_f32_e32 v133, v133
	v_exp_f32_e32 v134, v134
	v_exp_f32_e32 v135, v135
	v_exp_f32_e32 v136, v136
	v_exp_f32_e32 v137, v137
	v_mov_b32_e32 v138, 0x3e22f983
	v_mov_b32_e32 v139, 0x3e22f983
	s_cmp_lt_i32 s30, 2
	s_cselect_b32 s6, 6, 0
	s_cselect_b32 s7, -1, 63
	s_cmp_lt_i32 s66, 64
	s_cselect_b32 s8, 1.0, 0
	s_and_b32 s9, s65, 3
	v_readlane_b32 s4, v253, 35
	v_mov_b32_e32 v176, s4
	ds_read_b64 v[174:175], v176
	s_lshl_b32 s4, s66, 3
	s_add_i32 s4, s4, s9
	s_lshl_b32 s4, s4, 3
	s_lshl_b32 s5, s68, 2
	s_add_i32 s4, s4, s5
	s_lshl_b32 s4, s4, 3
	s_add_i32 s4, s4, s30
	s_lshl_b32 s4, s4, 10
	s_mov_b32 s5, 0
	v_and_b32_e32 v176, 1, v203
	v_lshrrev_b32_e32 v177, 1, v203
	v_lshl_add_u32 v176, v176, 1, v177
	v_lshl_add_u32 v176, v176, 4, v202
	v_lshlrev_b32_e32 v176, 4, v176
	v_mov_b32_e32 v177, 0
	s_waitcnt lgkmcnt(0)
	v_lshl_add_u64 v[172:173], v[174:175], 0, s[4:5]
	v_lshl_add_u64 v[172:173], v[172:173], 0, v[176:177]
	s_mov_b64 s[4:5], 0x1000
	v_lshl_add_u64 v[174:175], v[172:173], 0, s[4:5]
	s_mov_b64 s[2:3], 0x2000
	s_mov_b64 s[28:29], 0x3a000
	v_mov_b32_e32 v142, v160
	v_lshrrev_b32_e32 v142, s6, v142
	v_and_b32_e32 v142, s7, v142
	v_cvt_f32_i32_e32 v142, v142
	v_mul_f32_e32 v142, s8, v142
	v_pk_mul_f32 v[206:207], v[130:131], v[142:143] op_sel_hi:[1,0]
	v_pk_mul_f32 v[208:209], v[132:133], v[142:143] op_sel_hi:[1,0]
	v_pk_mul_f32 v[210:211], v[134:135], v[142:143] op_sel_hi:[1,0]
	v_pk_mul_f32 v[212:213], v[136:137], v[142:143] op_sel_hi:[1,0]
	v_pk_mul_f32 v[206:207], v[206:207], v[138:139]
	v_sin_f32_e32 v214, v206
	v_pk_mul_f32 v[208:209], v[208:209], v[138:139]
	v_sin_f32_e32 v215, v207
	v_pk_mul_f32 v[210:211], v[210:211], v[138:139]
	v_sin_f32_e32 v216, v208
	v_pk_mul_f32 v[212:213], v[212:213], v[138:139]
	v_sin_f32_e32 v217, v209
	v_pk_mul_f32 v[144:145], v[122:123], v[214:215]
	v_sin_f32_e32 v218, v210
	v_pk_mul_f32 v[146:147], v[124:125], v[216:217]
	v_sin_f32_e32 v219, v211
	v_add_u32_e32 v142, 16, v160
	v_sin_f32_e32 v220, v212
	v_lshrrev_b32_e32 v142, s6, v142
	v_sin_f32_e32 v221, v213
	v_and_b32_e32 v142, s7, v142
	v_cos_f32_e32 v206, v206
	v_cvt_f32_i32_e32 v142, v142
	v_cos_f32_e32 v207, v207
	v_mul_f32_e32 v142, s8, v142
	v_cos_f32_e32 v208, v208
	v_pk_fma_f32 v[222:223], v[126:127], v[206:207], v[144:145] neg_lo:[0,0,1] neg_hi:[0,0,1]
	v_cos_f32_e32 v209, v209
	v_pk_mul_f32 v[144:145], v[126:127], v[214:215]
	v_cos_f32_e32 v210, v210
	v_pk_fma_f32 v[164:165], v[122:123], v[206:207], v[144:145]
	v_cos_f32_e32 v211, v211
	v_pk_fma_f32 v[224:225], v[128:129], v[208:209], v[146:147] neg_lo:[0,0,1] neg_hi:[0,0,1]
	v_cos_f32_e32 v212, v212
	v_pk_mul_f32 v[146:147], v[128:129], v[216:217]
	v_cos_f32_e32 v213, v213
	v_pk_fma_f32 v[166:167], v[124:125], v[208:209], v[146:147]
	v_pk_mul_f32 v[144:145], v[114:115], v[218:219]
	v_pk_fma_f32 v[226:227], v[118:119], v[210:211], v[144:145] neg_lo:[0,0,1] neg_hi:[0,0,1]
	v_pk_mul_f32 v[144:145], v[118:119], v[218:219]
	v_pk_fma_f32 v[168:169], v[114:115], v[210:211], v[144:145]
	v_pk_mul_f32 v[146:147], v[116:117], v[220:221]
	v_pk_fma_f32 v[228:229], v[120:121], v[212:213], v[146:147] neg_lo:[0,0,1] neg_hi:[0,0,1]
	v_pk_mul_f32 v[146:147], v[120:121], v[220:221]
	v_pk_fma_f32 v[170:171], v[116:117], v[212:213], v[146:147]
	v_cvt_pk_bf16_f32 v222, v222, v223
	v_cvt_pk_bf16_f32 v223, v224, v225
	v_cvt_pk_bf16_f32 v224, v226, v227
	v_cvt_pk_bf16_f32 v225, v228, v229
	v_cvt_pk_bf16_f32 v164, v164, v165
	v_cvt_pk_bf16_f32 v165, v166, v167
	v_cvt_pk_bf16_f32 v166, v168, v169
	v_cvt_pk_bf16_f32 v167, v170, v171
	v_permlane16_swap_b32_e32 v222, v224
	v_permlane16_swap_b32_e32 v223, v225
	v_permlane16_swap_b32_e32 v164, v166
	v_permlane16_swap_b32_e32 v165, v167
	global_store_dwordx4 v[172:173], v[222:225], off
	global_store_dwordx4 v[174:175], v[164:167], off
	v_pk_mul_f32 v[236:237], v[130:131], v[142:143] op_sel_hi:[1,0]
	v_lshl_add_u64 v[172:173], v[172:173], 0, s[2:3]
	v_lshl_add_u64 v[174:175], v[174:175], 0, s[2:3]
	v_pk_mul_f32 v[238:239], v[132:133], v[142:143] op_sel_hi:[1,0]
	v_pk_mul_f32 v[240:241], v[134:135], v[142:143] op_sel_hi:[1,0]
	v_pk_mul_f32 v[242:243], v[136:137], v[142:143] op_sel_hi:[1,0]
	v_pk_mul_f32 v[236:237], v[236:237], v[138:139]
	v_sin_f32_e32 v244, v236
	v_pk_mul_f32 v[238:239], v[238:239], v[138:139]
	v_sin_f32_e32 v245, v237
	v_pk_mul_f32 v[240:241], v[240:241], v[138:139]
	v_sin_f32_e32 v246, v238
	v_pk_mul_f32 v[242:243], v[242:243], v[138:139]
	v_sin_f32_e32 v247, v239
	v_pk_mul_f32 v[144:145], v[106:107], v[244:245]
	v_sin_f32_e32 v248, v240
	v_pk_mul_f32 v[146:147], v[108:109], v[246:247]
	v_sin_f32_e32 v249, v241
	v_add_u32_e32 v142, 32, v160
	v_sin_f32_e32 v250, v242
	v_lshrrev_b32_e32 v142, s6, v142
	v_sin_f32_e32 v251, v243
	v_and_b32_e32 v142, s7, v142
	v_cos_f32_e32 v236, v236
	v_cvt_f32_i32_e32 v142, v142
	v_cos_f32_e32 v237, v237
	v_mul_f32_e32 v142, s8, v142
	v_cos_f32_e32 v238, v238
	v_pk_fma_f32 v[222:223], v[110:111], v[236:237], v[144:145] neg_lo:[0,0,1] neg_hi:[0,0,1]
	v_cos_f32_e32 v239, v239
	v_pk_mul_f32 v[144:145], v[110:111], v[244:245]
	v_cos_f32_e32 v240, v240
	v_pk_fma_f32 v[164:165], v[106:107], v[236:237], v[144:145]
	v_cos_f32_e32 v241, v241
	v_pk_fma_f32 v[224:225], v[112:113], v[238:239], v[146:147] neg_lo:[0,0,1] neg_hi:[0,0,1]
	v_cos_f32_e32 v242, v242
	v_pk_mul_f32 v[146:147], v[112:113], v[246:247]
	v_cos_f32_e32 v243, v243
	v_pk_fma_f32 v[166:167], v[108:109], v[238:239], v[146:147]
	v_pk_mul_f32 v[144:145], v[98:99], v[248:249]
	v_pk_fma_f32 v[226:227], v[102:103], v[240:241], v[144:145] neg_lo:[0,0,1] neg_hi:[0,0,1]
	v_pk_mul_f32 v[144:145], v[102:103], v[248:249]
	v_pk_fma_f32 v[168:169], v[98:99], v[240:241], v[144:145]
	v_pk_mul_f32 v[146:147], v[100:101], v[250:251]
	v_pk_fma_f32 v[228:229], v[104:105], v[242:243], v[146:147] neg_lo:[0,0,1] neg_hi:[0,0,1]
	v_pk_mul_f32 v[146:147], v[104:105], v[250:251]
	v_pk_fma_f32 v[170:171], v[100:101], v[242:243], v[146:147]
	v_cvt_pk_bf16_f32 v222, v222, v223
	v_cvt_pk_bf16_f32 v223, v224, v225
	v_cvt_pk_bf16_f32 v224, v226, v227
	v_cvt_pk_bf16_f32 v225, v228, v229
	v_cvt_pk_bf16_f32 v164, v164, v165
	v_cvt_pk_bf16_f32 v165, v166, v167
	v_cvt_pk_bf16_f32 v166, v168, v169
	v_cvt_pk_bf16_f32 v167, v170, v171
	v_permlane16_swap_b32_e32 v222, v224
	v_permlane16_swap_b32_e32 v223, v225
	v_permlane16_swap_b32_e32 v164, v166
	v_permlane16_swap_b32_e32 v165, v167
	global_store_dwordx4 v[172:173], v[222:225], off
	global_store_dwordx4 v[174:175], v[164:167], off
	v_pk_mul_f32 v[206:207], v[130:131], v[142:143] op_sel_hi:[1,0]
	v_lshl_add_u64 v[172:173], v[172:173], 0, s[2:3]
	v_lshl_add_u64 v[174:175], v[174:175], 0, s[2:3]
	v_pk_mul_f32 v[208:209], v[132:133], v[142:143] op_sel_hi:[1,0]
	v_pk_mul_f32 v[210:211], v[134:135], v[142:143] op_sel_hi:[1,0]
	v_pk_mul_f32 v[212:213], v[136:137], v[142:143] op_sel_hi:[1,0]
	v_pk_mul_f32 v[206:207], v[206:207], v[138:139]
	v_sin_f32_e32 v214, v206
	v_pk_mul_f32 v[208:209], v[208:209], v[138:139]
	v_sin_f32_e32 v215, v207
	v_pk_mul_f32 v[210:211], v[210:211], v[138:139]
	v_sin_f32_e32 v216, v208
	v_pk_mul_f32 v[212:213], v[212:213], v[138:139]
	v_sin_f32_e32 v217, v209
	v_pk_mul_f32 v[144:145], v[90:91], v[214:215]
	v_sin_f32_e32 v218, v210
	v_pk_mul_f32 v[146:147], v[92:93], v[216:217]
	v_sin_f32_e32 v219, v211
	v_add_u32_e32 v142, 48, v160
	v_sin_f32_e32 v220, v212
	v_lshrrev_b32_e32 v142, s6, v142
	v_sin_f32_e32 v221, v213
	v_and_b32_e32 v142, s7, v142
	v_cos_f32_e32 v206, v206
	v_cvt_f32_i32_e32 v142, v142
	v_cos_f32_e32 v207, v207
	v_mul_f32_e32 v142, s8, v142
	v_cos_f32_e32 v208, v208
	v_pk_fma_f32 v[222:223], v[94:95], v[206:207], v[144:145] neg_lo:[0,0,1] neg_hi:[0,0,1]
	v_cos_f32_e32 v209, v209
	v_pk_mul_f32 v[144:145], v[94:95], v[214:215]
	v_cos_f32_e32 v210, v210
	v_pk_fma_f32 v[164:165], v[90:91], v[206:207], v[144:145]
	v_cos_f32_e32 v211, v211
	v_pk_fma_f32 v[224:225], v[96:97], v[208:209], v[146:147] neg_lo:[0,0,1] neg_hi:[0,0,1]
	v_cos_f32_e32 v212, v212
	v_pk_mul_f32 v[146:147], v[96:97], v[216:217]
	v_cos_f32_e32 v213, v213
	v_pk_fma_f32 v[166:167], v[92:93], v[208:209], v[146:147]
	v_pk_mul_f32 v[144:145], v[82:83], v[218:219]
	v_pk_fma_f32 v[226:227], v[86:87], v[210:211], v[144:145] neg_lo:[0,0,1] neg_hi:[0,0,1]
	v_pk_mul_f32 v[144:145], v[86:87], v[218:219]
	v_pk_fma_f32 v[168:169], v[82:83], v[210:211], v[144:145]
	v_pk_mul_f32 v[146:147], v[84:85], v[220:221]
	v_pk_fma_f32 v[228:229], v[88:89], v[212:213], v[146:147] neg_lo:[0,0,1] neg_hi:[0,0,1]
	v_pk_mul_f32 v[146:147], v[88:89], v[220:221]
	v_pk_fma_f32 v[170:171], v[84:85], v[212:213], v[146:147]
	v_cvt_pk_bf16_f32 v222, v222, v223
	v_cvt_pk_bf16_f32 v223, v224, v225
	v_cvt_pk_bf16_f32 v224, v226, v227
	v_cvt_pk_bf16_f32 v225, v228, v229
	v_cvt_pk_bf16_f32 v164, v164, v165
	v_cvt_pk_bf16_f32 v165, v166, v167
	v_cvt_pk_bf16_f32 v166, v168, v169
	v_cvt_pk_bf16_f32 v167, v170, v171
	v_permlane16_swap_b32_e32 v222, v224
	v_permlane16_swap_b32_e32 v223, v225
	v_permlane16_swap_b32_e32 v164, v166
	v_permlane16_swap_b32_e32 v165, v167
	global_store_dwordx4 v[172:173], v[222:225], off
	global_store_dwordx4 v[174:175], v[164:167], off
	v_pk_mul_f32 v[236:237], v[130:131], v[142:143] op_sel_hi:[1,0]
	v_lshl_add_u64 v[172:173], v[172:173], 0, s[2:3]
	v_lshl_add_u64 v[174:175], v[174:175], 0, s[2:3]
	v_pk_mul_f32 v[238:239], v[132:133], v[142:143] op_sel_hi:[1,0]
	v_pk_mul_f32 v[240:241], v[134:135], v[142:143] op_sel_hi:[1,0]
	v_pk_mul_f32 v[242:243], v[136:137], v[142:143] op_sel_hi:[1,0]
	v_pk_mul_f32 v[236:237], v[236:237], v[138:139]
	v_sin_f32_e32 v244, v236
	v_pk_mul_f32 v[238:239], v[238:239], v[138:139]
	v_sin_f32_e32 v245, v237
	v_pk_mul_f32 v[240:241], v[240:241], v[138:139]
	v_sin_f32_e32 v246, v238
	v_pk_mul_f32 v[242:243], v[242:243], v[138:139]
	v_sin_f32_e32 v247, v239
	v_pk_mul_f32 v[144:145], v[74:75], v[244:245]
	v_sin_f32_e32 v248, v240
	v_pk_mul_f32 v[146:147], v[76:77], v[246:247]
	v_sin_f32_e32 v249, v241
	v_add_u32_e32 v142, 128, v160
	v_sin_f32_e32 v250, v242
	v_lshrrev_b32_e32 v142, s6, v142
	v_sin_f32_e32 v251, v243
	v_and_b32_e32 v142, s7, v142
	v_cos_f32_e32 v236, v236
	v_cvt_f32_i32_e32 v142, v142
	v_cos_f32_e32 v237, v237
	v_mul_f32_e32 v142, s8, v142
	v_cos_f32_e32 v238, v238
	v_pk_fma_f32 v[222:223], v[78:79], v[236:237], v[144:145] neg_lo:[0,0,1] neg_hi:[0,0,1]
	v_cos_f32_e32 v239, v239
	v_pk_mul_f32 v[144:145], v[78:79], v[244:245]
	v_cos_f32_e32 v240, v240
	v_pk_fma_f32 v[164:165], v[74:75], v[236:237], v[144:145]
	v_cos_f32_e32 v241, v241
	v_pk_fma_f32 v[224:225], v[80:81], v[238:239], v[146:147] neg_lo:[0,0,1] neg_hi:[0,0,1]
	v_cos_f32_e32 v242, v242
	v_pk_mul_f32 v[146:147], v[80:81], v[246:247]
	v_cos_f32_e32 v243, v243
	v_pk_fma_f32 v[166:167], v[76:77], v[238:239], v[146:147]
	v_pk_mul_f32 v[144:145], v[66:67], v[248:249]
	v_pk_fma_f32 v[226:227], v[70:71], v[240:241], v[144:145] neg_lo:[0,0,1] neg_hi:[0,0,1]
	v_pk_mul_f32 v[144:145], v[70:71], v[248:249]
	v_pk_fma_f32 v[168:169], v[66:67], v[240:241], v[144:145]
	v_pk_mul_f32 v[146:147], v[68:69], v[250:251]
	v_pk_fma_f32 v[228:229], v[72:73], v[242:243], v[146:147] neg_lo:[0,0,1] neg_hi:[0,0,1]
	v_pk_mul_f32 v[146:147], v[72:73], v[250:251]
	v_pk_fma_f32 v[170:171], v[68:69], v[242:243], v[146:147]
	v_cvt_pk_bf16_f32 v222, v222, v223
	v_cvt_pk_bf16_f32 v223, v224, v225
	v_cvt_pk_bf16_f32 v224, v226, v227
	v_cvt_pk_bf16_f32 v225, v228, v229
	v_cvt_pk_bf16_f32 v164, v164, v165
	v_cvt_pk_bf16_f32 v165, v166, v167
	v_cvt_pk_bf16_f32 v166, v168, v169
	v_cvt_pk_bf16_f32 v167, v170, v171
	v_permlane16_swap_b32_e32 v222, v224
	v_permlane16_swap_b32_e32 v223, v225
	v_permlane16_swap_b32_e32 v164, v166
	v_permlane16_swap_b32_e32 v165, v167
	global_store_dwordx4 v[172:173], v[222:225], off
	global_store_dwordx4 v[174:175], v[164:167], off
	v_pk_mul_f32 v[206:207], v[130:131], v[142:143] op_sel_hi:[1,0]
	v_lshl_add_u64 v[172:173], v[172:173], 0, s[28:29]
	v_lshl_add_u64 v[174:175], v[174:175], 0, s[28:29]
	v_pk_mul_f32 v[208:209], v[132:133], v[142:143] op_sel_hi:[1,0]
	v_pk_mul_f32 v[210:211], v[134:135], v[142:143] op_sel_hi:[1,0]
	v_pk_mul_f32 v[212:213], v[136:137], v[142:143] op_sel_hi:[1,0]
	v_pk_mul_f32 v[206:207], v[206:207], v[138:139]
	v_sin_f32_e32 v214, v206
	v_pk_mul_f32 v[208:209], v[208:209], v[138:139]
	v_sin_f32_e32 v215, v207
	v_pk_mul_f32 v[210:211], v[210:211], v[138:139]
	v_sin_f32_e32 v216, v208
	v_pk_mul_f32 v[212:213], v[212:213], v[138:139]
	v_sin_f32_e32 v217, v209
	v_pk_mul_f32 v[144:145], v[58:59], v[214:215]
	v_sin_f32_e32 v218, v210
	v_pk_mul_f32 v[146:147], v[60:61], v[216:217]
	v_sin_f32_e32 v219, v211
	v_add_u32_e32 v142, 144, v160
	v_sin_f32_e32 v220, v212
	v_lshrrev_b32_e32 v142, s6, v142
	v_sin_f32_e32 v221, v213
	v_and_b32_e32 v142, s7, v142
	v_cos_f32_e32 v206, v206
	v_cvt_f32_i32_e32 v142, v142
	v_cos_f32_e32 v207, v207
	v_mul_f32_e32 v142, s8, v142
	v_cos_f32_e32 v208, v208
	v_pk_fma_f32 v[222:223], v[62:63], v[206:207], v[144:145] neg_lo:[0,0,1] neg_hi:[0,0,1]
	v_cos_f32_e32 v209, v209
	v_pk_mul_f32 v[144:145], v[62:63], v[214:215]
	v_cos_f32_e32 v210, v210
	v_pk_fma_f32 v[164:165], v[58:59], v[206:207], v[144:145]
	v_cos_f32_e32 v211, v211
	v_pk_fma_f32 v[224:225], v[64:65], v[208:209], v[146:147] neg_lo:[0,0,1] neg_hi:[0,0,1]
	v_cos_f32_e32 v212, v212
	v_pk_mul_f32 v[146:147], v[64:65], v[216:217]
	v_cos_f32_e32 v213, v213
	v_pk_fma_f32 v[166:167], v[60:61], v[208:209], v[146:147]
	v_pk_mul_f32 v[144:145], v[50:51], v[218:219]
	v_pk_fma_f32 v[226:227], v[54:55], v[210:211], v[144:145] neg_lo:[0,0,1] neg_hi:[0,0,1]
	v_pk_mul_f32 v[144:145], v[54:55], v[218:219]
	v_pk_fma_f32 v[168:169], v[50:51], v[210:211], v[144:145]
	v_pk_mul_f32 v[146:147], v[52:53], v[220:221]
	v_pk_fma_f32 v[228:229], v[56:57], v[212:213], v[146:147] neg_lo:[0,0,1] neg_hi:[0,0,1]
	v_pk_mul_f32 v[146:147], v[56:57], v[220:221]
	v_pk_fma_f32 v[170:171], v[52:53], v[212:213], v[146:147]
	v_cvt_pk_bf16_f32 v222, v222, v223
	v_cvt_pk_bf16_f32 v223, v224, v225
	v_cvt_pk_bf16_f32 v224, v226, v227
	v_cvt_pk_bf16_f32 v225, v228, v229
	v_cvt_pk_bf16_f32 v164, v164, v165
	v_cvt_pk_bf16_f32 v165, v166, v167
	v_cvt_pk_bf16_f32 v166, v168, v169
	v_cvt_pk_bf16_f32 v167, v170, v171
	v_permlane16_swap_b32_e32 v222, v224
	v_permlane16_swap_b32_e32 v223, v225
	v_permlane16_swap_b32_e32 v164, v166
	v_permlane16_swap_b32_e32 v165, v167
	global_store_dwordx4 v[172:173], v[222:225], off
	global_store_dwordx4 v[174:175], v[164:167], off
	v_pk_mul_f32 v[236:237], v[130:131], v[142:143] op_sel_hi:[1,0]
	v_lshl_add_u64 v[172:173], v[172:173], 0, s[2:3]
	v_lshl_add_u64 v[174:175], v[174:175], 0, s[2:3]
	v_pk_mul_f32 v[238:239], v[132:133], v[142:143] op_sel_hi:[1,0]
	v_pk_mul_f32 v[240:241], v[134:135], v[142:143] op_sel_hi:[1,0]
	v_pk_mul_f32 v[242:243], v[136:137], v[142:143] op_sel_hi:[1,0]
	v_pk_mul_f32 v[236:237], v[236:237], v[138:139]
	v_sin_f32_e32 v244, v236
	v_pk_mul_f32 v[238:239], v[238:239], v[138:139]
	v_sin_f32_e32 v245, v237
	v_pk_mul_f32 v[240:241], v[240:241], v[138:139]
	v_sin_f32_e32 v246, v238
	v_pk_mul_f32 v[242:243], v[242:243], v[138:139]
	v_sin_f32_e32 v247, v239
	v_pk_mul_f32 v[144:145], v[42:43], v[244:245]
	v_sin_f32_e32 v248, v240
	v_pk_mul_f32 v[146:147], v[44:45], v[246:247]
	v_sin_f32_e32 v249, v241
	v_add_u32_e32 v142, 160, v160
	v_sin_f32_e32 v250, v242
	v_lshrrev_b32_e32 v142, s6, v142
	v_sin_f32_e32 v251, v243
	v_and_b32_e32 v142, s7, v142
	v_cos_f32_e32 v236, v236
	v_cvt_f32_i32_e32 v142, v142
	v_cos_f32_e32 v237, v237
	v_mul_f32_e32 v142, s8, v142
	v_cos_f32_e32 v238, v238
	v_pk_fma_f32 v[222:223], v[46:47], v[236:237], v[144:145] neg_lo:[0,0,1] neg_hi:[0,0,1]
	v_cos_f32_e32 v239, v239
	v_pk_mul_f32 v[144:145], v[46:47], v[244:245]
	v_cos_f32_e32 v240, v240
	v_pk_fma_f32 v[164:165], v[42:43], v[236:237], v[144:145]
	v_cos_f32_e32 v241, v241
	v_pk_fma_f32 v[224:225], v[48:49], v[238:239], v[146:147] neg_lo:[0,0,1] neg_hi:[0,0,1]
	v_cos_f32_e32 v242, v242
	v_pk_mul_f32 v[146:147], v[48:49], v[246:247]
	v_cos_f32_e32 v243, v243
	v_pk_fma_f32 v[166:167], v[44:45], v[238:239], v[146:147]
	v_pk_mul_f32 v[144:145], v[34:35], v[248:249]
	v_pk_fma_f32 v[226:227], v[38:39], v[240:241], v[144:145] neg_lo:[0,0,1] neg_hi:[0,0,1]
	v_pk_mul_f32 v[144:145], v[38:39], v[248:249]
	v_pk_fma_f32 v[168:169], v[34:35], v[240:241], v[144:145]
	v_pk_mul_f32 v[146:147], v[36:37], v[250:251]
	v_pk_fma_f32 v[228:229], v[40:41], v[242:243], v[146:147] neg_lo:[0,0,1] neg_hi:[0,0,1]
	v_pk_mul_f32 v[146:147], v[40:41], v[250:251]
	v_pk_fma_f32 v[170:171], v[36:37], v[242:243], v[146:147]
	v_cvt_pk_bf16_f32 v222, v222, v223
	v_cvt_pk_bf16_f32 v223, v224, v225
	v_cvt_pk_bf16_f32 v224, v226, v227
	v_cvt_pk_bf16_f32 v225, v228, v229
	v_cvt_pk_bf16_f32 v164, v164, v165
	v_cvt_pk_bf16_f32 v165, v166, v167
	v_cvt_pk_bf16_f32 v166, v168, v169
	v_cvt_pk_bf16_f32 v167, v170, v171
	v_permlane16_swap_b32_e32 v222, v224
	v_permlane16_swap_b32_e32 v223, v225
	v_permlane16_swap_b32_e32 v164, v166
	v_permlane16_swap_b32_e32 v165, v167
	global_store_dwordx4 v[172:173], v[222:225], off
	global_store_dwordx4 v[174:175], v[164:167], off
	v_pk_mul_f32 v[206:207], v[130:131], v[142:143] op_sel_hi:[1,0]
	v_lshl_add_u64 v[172:173], v[172:173], 0, s[2:3]
	v_lshl_add_u64 v[174:175], v[174:175], 0, s[2:3]
	v_pk_mul_f32 v[208:209], v[132:133], v[142:143] op_sel_hi:[1,0]
	v_pk_mul_f32 v[210:211], v[134:135], v[142:143] op_sel_hi:[1,0]
	v_pk_mul_f32 v[212:213], v[136:137], v[142:143] op_sel_hi:[1,0]
	v_pk_mul_f32 v[206:207], v[206:207], v[138:139]
	v_sin_f32_e32 v214, v206
	v_pk_mul_f32 v[208:209], v[208:209], v[138:139]
	v_sin_f32_e32 v215, v207
	v_pk_mul_f32 v[210:211], v[210:211], v[138:139]
	v_sin_f32_e32 v216, v208
	v_pk_mul_f32 v[212:213], v[212:213], v[138:139]
	v_sin_f32_e32 v217, v209
	v_pk_mul_f32 v[144:145], v[26:27], v[214:215]
	v_sin_f32_e32 v218, v210
	v_pk_mul_f32 v[146:147], v[28:29], v[216:217]
	v_sin_f32_e32 v219, v211
	v_add_u32_e32 v142, 176, v160
	v_sin_f32_e32 v220, v212
	v_lshrrev_b32_e32 v142, s6, v142
	v_sin_f32_e32 v221, v213
	v_and_b32_e32 v142, s7, v142
	v_cos_f32_e32 v206, v206
	v_cvt_f32_i32_e32 v142, v142
	v_cos_f32_e32 v207, v207
	v_mul_f32_e32 v142, s8, v142
	v_cos_f32_e32 v208, v208
	v_pk_fma_f32 v[222:223], v[30:31], v[206:207], v[144:145] neg_lo:[0,0,1] neg_hi:[0,0,1]
	v_cos_f32_e32 v209, v209
	v_pk_mul_f32 v[144:145], v[30:31], v[214:215]
	v_cos_f32_e32 v210, v210
	v_pk_fma_f32 v[164:165], v[26:27], v[206:207], v[144:145]
	v_cos_f32_e32 v211, v211
	v_pk_fma_f32 v[224:225], v[32:33], v[208:209], v[146:147] neg_lo:[0,0,1] neg_hi:[0,0,1]
	v_cos_f32_e32 v212, v212
	v_pk_mul_f32 v[146:147], v[32:33], v[216:217]
	v_cos_f32_e32 v213, v213
	v_pk_fma_f32 v[166:167], v[28:29], v[208:209], v[146:147]
	v_pk_mul_f32 v[144:145], v[18:19], v[218:219]
	v_pk_fma_f32 v[226:227], v[22:23], v[210:211], v[144:145] neg_lo:[0,0,1] neg_hi:[0,0,1]
	v_pk_mul_f32 v[144:145], v[22:23], v[218:219]
	v_pk_fma_f32 v[168:169], v[18:19], v[210:211], v[144:145]
	v_pk_mul_f32 v[146:147], v[20:21], v[220:221]
	v_pk_fma_f32 v[228:229], v[24:25], v[212:213], v[146:147] neg_lo:[0,0,1] neg_hi:[0,0,1]
	v_pk_mul_f32 v[146:147], v[24:25], v[220:221]
	v_pk_fma_f32 v[170:171], v[20:21], v[212:213], v[146:147]
	v_cvt_pk_bf16_f32 v222, v222, v223
	v_cvt_pk_bf16_f32 v223, v224, v225
	v_cvt_pk_bf16_f32 v224, v226, v227
	v_cvt_pk_bf16_f32 v225, v228, v229
	v_cvt_pk_bf16_f32 v164, v164, v165
	v_cvt_pk_bf16_f32 v165, v166, v167
	v_cvt_pk_bf16_f32 v166, v168, v169
	v_cvt_pk_bf16_f32 v167, v170, v171
	v_permlane16_swap_b32_e32 v222, v224
	v_permlane16_swap_b32_e32 v223, v225
	v_permlane16_swap_b32_e32 v164, v166
	v_permlane16_swap_b32_e32 v165, v167
	global_store_dwordx4 v[172:173], v[222:225], off
	global_store_dwordx4 v[174:175], v[164:167], off
	v_pk_mul_f32 v[236:237], v[130:131], v[142:143] op_sel_hi:[1,0]
	v_lshl_add_u64 v[172:173], v[172:173], 0, s[2:3]
	v_lshl_add_u64 v[174:175], v[174:175], 0, s[2:3]
	v_pk_mul_f32 v[238:239], v[132:133], v[142:143] op_sel_hi:[1,0]
	v_pk_mul_f32 v[240:241], v[134:135], v[142:143] op_sel_hi:[1,0]
	v_pk_mul_f32 v[242:243], v[136:137], v[142:143] op_sel_hi:[1,0]
	v_pk_mul_f32 v[236:237], v[236:237], v[138:139]
	v_sin_f32_e32 v244, v236
	v_pk_mul_f32 v[238:239], v[238:239], v[138:139]
	v_sin_f32_e32 v245, v237
	v_pk_mul_f32 v[240:241], v[240:241], v[138:139]
	v_sin_f32_e32 v246, v238
	v_pk_mul_f32 v[242:243], v[242:243], v[138:139]
	v_sin_f32_e32 v247, v239
	v_pk_mul_f32 v[144:145], v[10:11], v[244:245]
	v_sin_f32_e32 v248, v240
	v_pk_mul_f32 v[146:147], v[12:13], v[246:247]
	v_sin_f32_e32 v249, v241
	v_sin_f32_e32 v250, v242
	v_sin_f32_e32 v251, v243
	v_cos_f32_e32 v236, v236
	v_cos_f32_e32 v237, v237
	v_cos_f32_e32 v238, v238
	v_pk_fma_f32 v[222:223], v[14:15], v[236:237], v[144:145] neg_lo:[0,0,1] neg_hi:[0,0,1]
	v_cos_f32_e32 v239, v239
	v_pk_mul_f32 v[144:145], v[14:15], v[244:245]
	v_cos_f32_e32 v240, v240
	v_pk_fma_f32 v[164:165], v[10:11], v[236:237], v[144:145]
	v_cos_f32_e32 v241, v241
	v_pk_fma_f32 v[224:225], v[16:17], v[238:239], v[146:147] neg_lo:[0,0,1] neg_hi:[0,0,1]
	v_cos_f32_e32 v242, v242
	v_pk_mul_f32 v[146:147], v[16:17], v[246:247]
	v_cos_f32_e32 v243, v243
	v_pk_fma_f32 v[166:167], v[12:13], v[238:239], v[146:147]
	v_pk_mul_f32 v[144:145], v[2:3], v[248:249]
	v_pk_fma_f32 v[226:227], v[6:7], v[240:241], v[144:145] neg_lo:[0,0,1] neg_hi:[0,0,1]
	v_pk_mul_f32 v[144:145], v[6:7], v[248:249]
	v_pk_fma_f32 v[168:169], v[2:3], v[240:241], v[144:145]
	v_pk_mul_f32 v[146:147], v[4:5], v[250:251]
	v_pk_fma_f32 v[228:229], v[8:9], v[242:243], v[146:147] neg_lo:[0,0,1] neg_hi:[0,0,1]
	v_pk_mul_f32 v[146:147], v[8:9], v[250:251]
	v_pk_fma_f32 v[170:171], v[4:5], v[242:243], v[146:147]
	v_cvt_pk_bf16_f32 v222, v222, v223
	v_cvt_pk_bf16_f32 v223, v224, v225
	v_cvt_pk_bf16_f32 v224, v226, v227
	v_cvt_pk_bf16_f32 v225, v228, v229
	v_cvt_pk_bf16_f32 v164, v164, v165
	v_cvt_pk_bf16_f32 v165, v166, v167
	v_cvt_pk_bf16_f32 v166, v168, v169
	v_cvt_pk_bf16_f32 v167, v170, v171
	v_permlane16_swap_b32_e32 v222, v224
	v_permlane16_swap_b32_e32 v223, v225
	v_permlane16_swap_b32_e32 v164, v166
	v_permlane16_swap_b32_e32 v165, v167
	global_store_dwordx4 v[172:173], v[222:225], off
	global_store_dwordx4 v[174:175], v[164:167], off
	s_branch .LBB0_816
